# stacked: MoBA partial-tile fast path + C-phase H reads inside K loop + rope table prefetch ring + rolling 16-row window in PEER v-pass
# speedup vs baseline: 1.0247x; 1.0175x over previous
; template <int MI, bool SWAP, bool F8 = false>
; __device__ __forceinline__ void gemm_core(const bf16_t* __restrict__ A, int lda, const bf16_t* __restrict__ B, int ldb,
;                                           int K, char* smem, f32x4 (&acc)[MI][4]) {
;     ...
;   for (int kt = 0; kt < nk; ++kt) {
;     __syncthreads();
; #pragma unroll
;     for (int i = 0; i < MI; ++i) *(u32x4*)(smem + woff + i * 4096) = ra[i];
; #pragma unroll
;     for (int i = 0; i < 4; ++i) *(u32x4*)(smem + 32768 + woff + i * 4096) = rb[i];
;     __syncthreads();
;     if (kt + 1 < nk) {
; #pragma unroll
;       for (int i = 0; i < MI; ++i) ra[i] = *(const u32x4*)(ap + (size_t)(32 * i) * lda + (kt + 1) * 64);
; #pragma unroll
;       for (int i = 0; i < 4; ++i) rb[i] = *(const u32x4*)(bp + (size_t)(32 * i) * ldb + (kt + 1) * 64);
;     }
;     if (F8) {
;       const int c0 = (g ^ (li & 7)) << 4, c1 = ((4 + g) ^ (li & 7)) << 4;
;       i32x8 wf8[4];
; #pragma unroll
;       for (int j = 0; j < 4; ++j) {
;         const char* rp = smem + wrow + ((j & 1) * 16 + (j >> 1) * 64) * 128;
;         const u32x4 lo = *(const u32x4*)(rp + c0), hi = *(const u32x4*)(rp + c1);
;         wf8[j] = (i32x8){(int)lo.x, (int)lo.y, (int)lo.z, (int)lo.w, (int)hi.x, (int)hi.y, (int)hi.z, (int)hi.w};
;       }
; #pragma unroll
;       for (int i = 0; i < MI; ++i) {
;         const char* rp = smem + xrow + i * 2048;
;         const u32x4 lo = *(const u32x4*)(rp + c0), hi = *(const u32x4*)(rp + c1);
;         const i32x8 xf8 = {(int)lo.x, (int)lo.y, (int)lo.z, (int)lo.w, (int)hi.x, (int)hi.y, (int)hi.z, (int)hi.w};
; #pragma unroll
;         for (int j = 0; j < 4; ++j)
;           acc[i][j] = __builtin_amdgcn_mfma_scale_f32_16x16x128_f8f6f4(wf8[j], xf8, acc[i][j], 0, 0, 0, 0x77777777, 0, 0x7f7f7f7f);
;       }
;     } else {
; #pragma unroll
;     for (int kk = 0; kk < 2; ++kk) {
;       const int ch = ((kk * 4 + g) ^ (li & 7)) << 4;
;       bf16x8 xf[MI], wf[4];
; #pragma unroll
;       for (int j = 0; j < 4; ++j) wf[j] = *(const bf16x8*)(smem + wrow + ((j & 1) * 16 + (j >> 1) * 64) * 128 + ch);
; #pragma unroll
;       for (int i = 0; i < MI; ++i) xf[i] = *(const bf16x8*)(smem + xrow + i * 2048 + ch);
; #pragma unroll
;       for (int i = 0; i < MI; ++i)
; #pragma unroll
;         for (int j = 0; j < 4; ++j) {
.LBB0_301:
	v_add_u32_e32 v213, v204, v205
	s_barrier
	s_mov_b32 m0, s62
	s_nop 0
	global_load_lds_dwordx4 v252, s[56:57]
	s_add_u32 m0, s62, 0x1000
	s_nop 0
	global_load_lds_dwordx4 v253, s[56:57]
	s_add_u32 s56, s56, 0x20000
	s_addc_u32 s57, s57, 0
	s_add_u32 m0, s62, 0x2000
	s_nop 0
	global_load_lds_dwordx4 v252, s[56:57]
	s_add_u32 m0, s62, 0x3000
	s_nop 0
	global_load_lds_dwordx4 v253, s[56:57]
	s_add_u32 s56, s56, 0x20000
	s_addc_u32 s57, s57, 0
	s_add_u32 m0, s62, 0x4000
	s_nop 0
	global_load_lds_dwordx4 v252, s[56:57]
	s_add_u32 m0, s62, 0x5000
	s_nop 0
	global_load_lds_dwordx4 v253, s[56:57]
	s_add_u32 s56, s56, 0x20000
	s_addc_u32 s57, s57, 0
	s_add_u32 m0, s62, 0x6000
	s_nop 0
	global_load_lds_dwordx4 v252, s[56:57]
	s_add_u32 m0, s62, 0x7000
	s_nop 0
	global_load_lds_dwordx4 v253, s[56:57]
	s_sub_u32 s56, s56, 0x60000
	s_subb_u32 s57, s57, 0
	s_add_u32 m0, s62, 0x8000
	s_nop 0
	global_load_lds_dwordx4 v252, s[58:59]
	s_add_u32 m0, s62, 0x9000
	s_nop 0
	global_load_lds_dwordx4 v253, s[58:59]
	s_add_u32 s58, s58, 0x20000
	s_addc_u32 s59, s59, 0
	s_add_u32 m0, s62, 0xa000
	s_nop 0
	global_load_lds_dwordx4 v252, s[58:59]
	s_add_u32 m0, s62, 0xb000
	s_nop 0
	global_load_lds_dwordx4 v253, s[58:59]
	s_sub_u32 s58, s58, 0x20000
	s_subb_u32 s59, s59, 0
	v_add_u32_e32 v252, 0x80, v252
	v_add_u32_e32 v253, 0x80, v253
	s_waitcnt vmcnt(0)
	s_barrier
	v_add_u32_e32 v0, v203, v205
	ds_read_b128 v[136:139], v213 offset:32768
	ds_read_b128 v[144:147], v213 offset:34816
	ds_read_b128 v[152:155], v0
	ds_read_b128 v[156:159], v0 offset:2048
	ds_read_b128 v[164:167], v213 offset:40960
	ds_read_b128 v[168:171], v213 offset:43008
	s_waitcnt lgkmcnt(3)
	v_mfma_f32_16x16x32_bf16 v[148:151], v[136:139], v[152:155], v[148:151]
	v_add_u32_e32 v215, v204, v206
	v_add_u32_e32 v207, v203, v206
	v_mfma_f32_16x16x32_bf16 v[140:143], v[144:147], v[152:155], v[140:143]
	s_waitcnt lgkmcnt(1)
	v_mfma_f32_16x16x32_bf16 v[132:135], v[164:167], v[152:155], v[132:135]
	s_waitcnt lgkmcnt(0)
	v_mfma_f32_16x16x32_bf16 v[128:131], v[168:171], v[152:155], v[128:131]
	v_mfma_f32_16x16x32_bf16 v[124:127], v[136:139], v[156:159], v[124:127]
	v_mfma_f32_16x16x32_bf16 v[120:123], v[144:147], v[156:159], v[120:123]
	v_mfma_f32_16x16x32_bf16 v[116:119], v[164:167], v[156:159], v[116:119]
	v_mfma_f32_16x16x32_bf16 v[112:115], v[168:171], v[156:159], v[112:115]
	ds_read_b128 v[152:155], v0 offset:4096
	ds_read_b128 v[156:159], v0 offset:6144
	s_waitcnt lgkmcnt(1)
	v_mfma_f32_16x16x32_bf16 v[108:111], v[136:139], v[152:155], v[108:111]
	v_mfma_f32_16x16x32_bf16 v[104:107], v[144:147], v[152:155], v[104:107]
	v_mfma_f32_16x16x32_bf16 v[100:103], v[164:167], v[152:155], v[100:103]
	v_mfma_f32_16x16x32_bf16 v[96:99], v[168:171], v[152:155], v[96:99]
	s_waitcnt lgkmcnt(0)
	v_mfma_f32_16x16x32_bf16 v[92:95], v[136:139], v[156:159], v[92:95]
	v_mfma_f32_16x16x32_bf16 v[88:91], v[144:147], v[156:159], v[88:91]
	v_mfma_f32_16x16x32_bf16 v[84:87], v[164:167], v[156:159], v[84:87]
	v_mfma_f32_16x16x32_bf16 v[80:83], v[168:171], v[156:159], v[80:83]
	ds_read_b128 v[152:155], v0 offset:8192
	ds_read_b128 v[156:159], v0 offset:10240
	s_waitcnt lgkmcnt(1)
	v_mfma_f32_16x16x32_bf16 v[68:71], v[136:139], v[152:155], v[68:71]
	v_mfma_f32_16x16x32_bf16 v[64:67], v[144:147], v[152:155], v[64:67]
	v_mfma_f32_16x16x32_bf16 v[60:63], v[164:167], v[152:155], v[60:63]
	v_mfma_f32_16x16x32_bf16 v[56:59], v[168:171], v[152:155], v[56:59]
	s_waitcnt lgkmcnt(0)
	v_mfma_f32_16x16x32_bf16 v[48:51], v[136:139], v[156:159], v[48:51]
	v_mfma_f32_16x16x32_bf16 v[44:47], v[144:147], v[156:159], v[44:47]
	v_mfma_f32_16x16x32_bf16 v[40:43], v[164:167], v[156:159], v[40:43]
	v_mfma_f32_16x16x32_bf16 v[36:39], v[168:171], v[156:159], v[36:39]
	ds_read_b128 v[152:155], v0 offset:12288
	ds_read_b128 v[156:159], v0 offset:14336
	ds_read_b128 v[172:175], v215 offset:32768
	ds_read_b128 v[180:183], v215 offset:34816
	s_waitcnt lgkmcnt(3)
	v_mfma_f32_16x16x32_bf16 v[28:31], v[136:139], v[152:155], v[28:31]
	v_mfma_f32_16x16x32_bf16 v[24:27], v[144:147], v[152:155], v[24:27]
	v_mfma_f32_16x16x32_bf16 v[76:79], v[164:167], v[152:155], v[76:79]
	v_mfma_f32_16x16x32_bf16 v[72:75], v[168:171], v[152:155], v[72:75]
	s_waitcnt lgkmcnt(2)
	v_mfma_f32_16x16x32_bf16 v[52:55], v[136:139], v[156:159], v[52:55]
	v_mfma_f32_16x16x32_bf16 v[32:35], v[144:147], v[156:159], v[32:35]
	ds_read_b128 v[136:139], v207
	ds_read_b128 v[144:147], v207 offset:2048
	ds_read_b128 v[192:195], v215 offset:40960
	ds_read_b128 v[196:199], v215 offset:43008
	v_mfma_f32_16x16x32_bf16 v[20:23], v[164:167], v[156:159], v[20:23]
	v_mfma_f32_16x16x32_bf16 v[160:163], v[168:171], v[156:159], v[160:163]
	s_waitcnt lgkmcnt(3)
	v_mfma_f32_16x16x32_bf16 v[148:151], v[172:175], v[136:139], v[148:151]
	v_mfma_f32_16x16x32_bf16 v[140:143], v[180:183], v[136:139], v[140:143]
	s_waitcnt lgkmcnt(1)
	v_mfma_f32_16x16x32_bf16 v[132:135], v[192:195], v[136:139], v[132:135]
	s_waitcnt lgkmcnt(0)
	v_mfma_f32_16x16x32_bf16 v[128:131], v[196:199], v[136:139], v[128:131]
	v_mfma_f32_16x16x32_bf16 v[124:127], v[172:175], v[144:147], v[124:127]
	v_mfma_f32_16x16x32_bf16 v[120:123], v[180:183], v[144:147], v[120:123]
	v_mfma_f32_16x16x32_bf16 v[116:119], v[192:195], v[144:147], v[116:119]
	v_mfma_f32_16x16x32_bf16 v[112:115], v[196:199], v[144:147], v[112:115]
	ds_read_b128 v[136:139], v207 offset:4096
	ds_read_b128 v[144:147], v207 offset:6144
	s_waitcnt lgkmcnt(1)
; template <int MI, bool SWAP, bool F8 = false>
; __device__ __forceinline__ void gemm_core(const bf16_t* __restrict__ A, int lda, const bf16_t* __restrict__ B, int ldb,
;                                           int K, char* smem, f32x4 (&acc)[MI][4]) {
;     ...
;   for (int kt = 0; kt < nk; ++kt) {
;     __syncthreads();
; #pragma unroll
;     for (int i = 0; i < MI; ++i) *(u32x4*)(smem + woff + i * 4096) = ra[i];
; #pragma unroll
;     for (int i = 0; i < 4; ++i) *(u32x4*)(smem + 32768 + woff + i * 4096) = rb[i];
;     __syncthreads();
;     if (kt + 1 < nk) {
; #pragma unroll
;       for (int i = 0; i < MI; ++i) ra[i] = *(const u32x4*)(ap + (size_t)(32 * i) * lda + (kt + 1) * 64);
; #pragma unroll
;       for (int i = 0; i < 4; ++i) rb[i] = *(const u32x4*)(bp + (size_t)(32 * i) * ldb + (kt + 1) * 64);
;     }
;     if (F8) {
;       const int c0 = (g ^ (li & 7)) << 4, c1 = ((4 + g) ^ (li & 7)) << 4;
;       i32x8 wf8[4];
; #pragma unroll
;       for (int j = 0; j < 4; ++j) {
;         const char* rp = smem + wrow + ((j & 1) * 16 + (j >> 1) * 64) * 128;
;         const u32x4 lo = *(const u32x4*)(rp + c0), hi = *(const u32x4*)(rp + c1);
;         wf8[j] = (i32x8){(int)lo.x, (int)lo.y, (int)lo.z, (int)lo.w, (int)hi.x, (int)hi.y, (int)hi.z, (int)hi.w};
;       }
; #pragma unroll
;       for (int i = 0; i < MI; ++i) {
;         const char* rp = smem + xrow + i * 2048;
;         const u32x4 lo = *(const u32x4*)(rp + c0), hi = *(const u32x4*)(rp + c1);
;         const i32x8 xf8 = {(int)lo.x, (int)lo.y, (int)lo.z, (int)lo.w, (int)hi.x, (int)hi.y, (int)hi.z, (int)hi.w};
; #pragma unroll
;         for (int j = 0; j < 4; ++j)
;           acc[i][j] = __builtin_amdgcn_mfma_scale_f32_16x16x128_f8f6f4(wf8[j], xf8, acc[i][j], 0, 0, 0, 0x77777777, 0, 0x7f7f7f7f);
;       }
;     } else {
; #pragma unroll
;     for (int kk = 0; kk < 2; ++kk) {
;       const int ch = ((kk * 4 + g) ^ (li & 7)) << 4;
;       bf16x8 xf[MI], wf[4];
; #pragma unroll
;       for (int j = 0; j < 4; ++j) wf[j] = *(const bf16x8*)(smem + wrow + ((j & 1) * 16 + (j >> 1) * 64) * 128 + ch);
; #pragma unroll
;       for (int i = 0; i < MI; ++i) xf[i] = *(const bf16x8*)(smem + xrow + i * 2048 + ch);
; #pragma unroll
;       for (int i = 0; i < MI; ++i)
; #pragma unroll
;         for (int j = 0; j < 4; ++j) {
	v_mfma_f32_16x16x32_bf16 v[108:111], v[172:175], v[136:139], v[108:111]
	ds_read_b128 v[152:155], v207 offset:12288
	ds_read_b128 v[216:219], v207 offset:14336
	v_mfma_f32_16x16x32_bf16 v[104:107], v[180:183], v[136:139], v[104:107]
	v_mfma_f32_16x16x32_bf16 v[100:103], v[192:195], v[136:139], v[100:103]
	v_mfma_f32_16x16x32_bf16 v[96:99], v[196:199], v[136:139], v[96:99]
	ds_read_b128 v[136:139], v207 offset:8192
	s_waitcnt lgkmcnt(3)
	v_mfma_f32_16x16x32_bf16 v[92:95], v[172:175], v[144:147], v[92:95]
	v_mfma_f32_16x16x32_bf16 v[88:91], v[180:183], v[144:147], v[88:91]
	v_mfma_f32_16x16x32_bf16 v[84:87], v[192:195], v[144:147], v[84:87]
	v_mfma_f32_16x16x32_bf16 v[80:83], v[196:199], v[144:147], v[80:83]
	ds_read_b128 v[144:147], v207 offset:10240
	s_waitcnt lgkmcnt(1)
	v_mfma_f32_16x16x32_bf16 v[68:71], v[172:175], v[136:139], v[68:71]
	v_mfma_f32_16x16x32_bf16 v[64:67], v[180:183], v[136:139], v[64:67]
	v_mfma_f32_16x16x32_bf16 v[60:63], v[192:195], v[136:139], v[60:63]
	v_mfma_f32_16x16x32_bf16 v[56:59], v[196:199], v[136:139], v[56:59]
	s_waitcnt lgkmcnt(0)
	v_mfma_f32_16x16x32_bf16 v[48:51], v[172:175], v[144:147], v[48:51]
	v_mfma_f32_16x16x32_bf16 v[44:47], v[180:183], v[144:147], v[44:47]
	v_mfma_f32_16x16x32_bf16 v[40:43], v[192:195], v[144:147], v[40:43]
	v_mfma_f32_16x16x32_bf16 v[36:39], v[196:199], v[144:147], v[36:39]
	v_mfma_f32_16x16x32_bf16 v[28:31], v[172:175], v[152:155], v[28:31]
	v_mfma_f32_16x16x32_bf16 v[24:27], v[180:183], v[152:155], v[24:27]
	v_mfma_f32_16x16x32_bf16 v[76:79], v[192:195], v[152:155], v[76:79]
	v_mfma_f32_16x16x32_bf16 v[72:75], v[196:199], v[152:155], v[72:75]
	v_mfma_f32_16x16x32_bf16 v[52:55], v[172:175], v[216:219], v[52:55]
	v_mfma_f32_16x16x32_bf16 v[32:35], v[180:183], v[216:219], v[32:35]
	v_mfma_f32_16x16x32_bf16 v[20:23], v[192:195], v[216:219], v[20:23]
	v_mfma_f32_16x16x32_bf16 v[160:163], v[196:199], v[216:219], v[160:163]
	s_add_u32 s26, s26, 0x80
	s_addc_u32 s27, s27, 0
	s_cmpk_lg_i32 s26, 0x780
	s_cbranch_scc1 .LBB0_301
	s_barrier
	s_mov_b32 m0, s62
	s_nop 0
	global_load_lds_dwordx4 v252, s[56:57]
	s_add_u32 m0, s62, 0x1000
	s_nop 0
	global_load_lds_dwordx4 v253, s[56:57]
	s_add_u32 s56, s56, 0x20000
	s_addc_u32 s57, s57, 0
	s_add_u32 m0, s62, 0x2000
	s_nop 0
	global_load_lds_dwordx4 v252, s[56:57]
	s_add_u32 m0, s62, 0x3000
	s_nop 0
	global_load_lds_dwordx4 v253, s[56:57]
	s_add_u32 s56, s56, 0x20000
	s_addc_u32 s57, s57, 0
	s_add_u32 m0, s62, 0x4000
	s_nop 0
	global_load_lds_dwordx4 v252, s[56:57]
	s_add_u32 m0, s62, 0x5000
	s_nop 0
	global_load_lds_dwordx4 v253, s[56:57]
	s_add_u32 s56, s56, 0x20000
	s_addc_u32 s57, s57, 0
	s_add_u32 m0, s62, 0x6000
	s_nop 0
	global_load_lds_dwordx4 v252, s[56:57]
	s_add_u32 m0, s62, 0x7000
	s_nop 0
	global_load_lds_dwordx4 v253, s[56:57]
	s_sub_u32 s56, s56, 0x60000
	s_subb_u32 s57, s57, 0
	s_add_u32 m0, s62, 0x8000
	s_nop 0
	global_load_lds_dwordx4 v252, s[58:59]
	s_add_u32 m0, s62, 0x9000
	s_nop 0
	global_load_lds_dwordx4 v253, s[58:59]
	s_add_u32 s58, s58, 0x20000
	s_addc_u32 s59, s59, 0
	s_add_u32 m0, s62, 0xa000
	s_nop 0
	global_load_lds_dwordx4 v252, s[58:59]
	s_add_u32 m0, s62, 0xb000
	s_nop 0
	global_load_lds_dwordx4 v253, s[58:59]
	s_sub_u32 s58, s58, 0x20000
	s_subb_u32 s59, s59, 0
	s_waitcnt vmcnt(0)
	s_barrier
	v_bfe_u32 v12, v208, 4, 1
	v_mul_u32_u24_e32 v12, 24, v12
	v_mov_b32_e32 v13, 0
	ds_read_b128 v[136:139], v213 offset:32768
	ds_read_b128 v[144:147], v213 offset:34816
	ds_read_b128 v[152:155], v0
	ds_read_b128 v[156:159], v0 offset:2048
	ds_read_b128 v[164:167], v213 offset:40960
	ds_read_b128 v[168:171], v213 offset:43008
	s_waitcnt lgkmcnt(3)
	v_mfma_f32_16x16x32_bf16 v[148:151], v[136:139], v[152:155], v[148:151]
	s_cmp_eq_u32 s42, 6
	s_cselect_b64 s[26:27], -1, 0
	s_cmp_lg_u32 s42, 6
	v_mfma_f32_16x16x32_bf16 v[140:143], v[144:147], v[152:155], v[140:143]
	s_cselect_b64 s[30:31], -1, 0
	s_and_b64 vcc, exec, s[26:27]
	s_waitcnt lgkmcnt(1)
	v_mfma_f32_16x16x32_bf16 v[132:135], v[164:167], v[152:155], v[132:135]
	s_waitcnt lgkmcnt(0)
	v_mfma_f32_16x16x32_bf16 v[128:131], v[168:171], v[152:155], v[128:131]
	v_mfma_f32_16x16x32_bf16 v[172:175], v[136:139], v[156:159], v[124:127]
	s_nop 2
	ds_read_b128 v[124:127], v0 offset:4096
	ds_read_b128 v[152:155], v0 offset:6144
	s_waitcnt lgkmcnt(0)
	v_mfma_f32_16x16x32_bf16 v[176:179], v[164:167], v[152:155], v[84:87]
	v_mfma_f32_16x16x32_bf16 v[180:183], v[168:171], v[152:155], v[80:83]
	s_nop 2
	ds_read_b128 v[80:83], v0 offset:8192
	ds_read_b128 v[84:87], v0 offset:10240
	s_waitcnt lgkmcnt(1)
	v_mfma_f32_16x16x32_bf16 v[196:199], v[168:171], v[80:83], v[56:59]
	s_waitcnt lgkmcnt(0)
	v_mfma_f32_16x16x32_bf16 v[200:203], v[136:139], v[84:87], v[48:51]
	s_nop 2
	ds_read_b128 v[48:51], v0 offset:12288
	ds_read_b128 v[56:59], v0 offset:14336
	v_mfma_f32_16x16x32_bf16 v[116:119], v[164:167], v[156:159], v[116:119]
	v_mfma_f32_16x16x32_bf16 v[112:115], v[168:171], v[156:159], v[112:115]
	v_mfma_f32_16x16x32_bf16 v[100:103], v[164:167], v[124:127], v[100:103]
	v_mfma_f32_16x16x32_bf16 v[96:99], v[168:171], v[124:127], v[96:99]
	v_mfma_f32_16x16x32_bf16 v[192:195], v[164:167], v[80:83], v[60:63]
	v_mfma_f32_16x16x32_bf16 v[40:43], v[164:167], v[84:87], v[40:43]
	v_mfma_f32_16x16x32_bf16 v[36:39], v[168:171], v[84:87], v[36:39]
	s_waitcnt lgkmcnt(1)
	v_mfma_f32_16x16x32_bf16 v[28:31], v[136:139], v[48:51], v[28:31]
	v_mfma_f32_16x16x32_bf16 v[24:27], v[144:147], v[48:51], v[24:27]
	v_mfma_f32_16x16x32_bf16 v[76:79], v[164:167], v[48:51], v[76:79]
	v_mfma_f32_16x16x32_bf16 v[216:219], v[168:171], v[48:51], v[72:75]
	s_waitcnt lgkmcnt(0)
; template <int MI, bool SWAP, bool F8 = false>
; __device__ __forceinline__ void gemm_core(const bf16_t* __restrict__ A, int lda, const bf16_t* __restrict__ B, int ldb,
;                                           int K, char* smem, f32x4 (&acc)[MI][4]) {
;     ...
;     for (int kk = 0; kk < 2; ++kk) {
;       const int ch = ((kk * 4 + g) ^ (li & 7)) << 4;
;       bf16x8 xf[MI], wf[4];
; #pragma unroll
;       for (int j = 0; j < 4; ++j) wf[j] = *(const bf16x8*)(smem + wrow + ((j & 1) * 16 + (j >> 1) * 64) * 128 + ch);
; #pragma unroll
;       for (int i = 0; i < MI; ++i) xf[i] = *(const bf16x8*)(smem + xrow + i * 2048 + ch);
; #pragma unroll
;       for (int i = 0; i < MI; ++i)
; #pragma unroll
;         for (int j = 0; j < 4; ++j) {
;           if (SWAP) acc[i][j] = __builtin_amdgcn_mfma_f32_16x16x32_bf16(xf[i], wf[j], acc[i][j], 0, 0, 0);
;           else acc[i][j] = __builtin_amdgcn_mfma_f32_16x16x32_bf16(wf[j], xf[i], acc[i][j], 0, 0, 0);
;         }
;     }
; __device__ void even_in_tile(const P& p, int li_even, int tm, int tn, char* smem) {
;     ...
; #pragma unroll
;     for (int i = 0; i < MI; ++i) {
;       const int s = s0 + MROW(i);
; #pragma unroll
;       for (int jj = 0; jj < 2; ++jj) {
;         const int d = wn * 32 + jj * 16 + g * 4;
;         const f32x4 c = *(const f32x4*)(ctab + s * 64 + d);
;         const f32x4 sn = *(const f32x4*)(stab + s * 64 + d);
	v_mfma_f32_16x16x32_bf16 v[224:227], v[144:147], v[56:59], v[32:35]
	v_mfma_f32_16x16x32_bf16 v[20:23], v[164:167], v[56:59], v[20:23]
	ds_read_b128 v[164:167], v215 offset:32768
	v_mfma_f32_16x16x32_bf16 v[160:163], v[168:171], v[56:59], v[160:163]
	ds_read_b128 v[168:171], v215 offset:34816
	ds_read_b128 v[32:35], v207
	ds_read_b128 v[48:51], v207 offset:2048
	ds_read_b128 v[228:231], v215 offset:40960
	ds_read_b128 v[232:235], v215 offset:43008
	v_mfma_f32_16x16x32_bf16 v[120:123], v[144:147], v[156:159], v[120:123]
	v_mov_b32_e32 v215, v208
	v_mfma_f32_16x16x32_bf16 v[108:111], v[136:139], v[124:127], v[108:111]
	v_mfma_f32_16x16x32_bf16 v[104:107], v[144:147], v[124:127], v[104:107]
	v_mfma_f32_16x16x32_bf16 v[92:95], v[136:139], v[152:155], v[92:95]
	v_mfma_f32_16x16x32_bf16 v[156:159], v[144:147], v[152:155], v[88:91]
	v_mfma_f32_16x16x32_bf16 v[184:187], v[136:139], v[80:83], v[68:71]
	v_mfma_f32_16x16x32_bf16 v[188:191], v[144:147], v[80:83], v[64:67]
	v_mfma_f32_16x16x32_bf16 v[44:47], v[144:147], v[84:87], v[44:47]
	v_mfma_f32_16x16x32_bf16 v[220:223], v[136:139], v[56:59], v[52:55]
	s_waitcnt lgkmcnt(3)
	v_mfma_f32_16x16x32_bf16 v[124:127], v[164:167], v[32:35], v[148:151]
	v_mfma_f32_16x16x32_bf16 v[150:153], v[168:171], v[32:35], v[140:143]
	s_waitcnt lgkmcnt(1)
	v_mfma_f32_16x16x32_bf16 v[88:91], v[228:231], v[32:35], v[132:135]
	s_waitcnt lgkmcnt(0)
	v_mfma_f32_16x16x32_bf16 v[84:87], v[232:235], v[32:35], v[128:131]
	v_mfma_f32_16x16x32_bf16 v[134:137], v[164:167], v[48:51], v[172:175]
	v_mfma_f32_16x16x32_bf16 v[138:141], v[168:171], v[48:51], v[120:123]
	v_mfma_f32_16x16x32_bf16 v[80:83], v[228:231], v[48:51], v[116:119]
	v_mfma_f32_16x16x32_bf16 v[72:75], v[232:235], v[48:51], v[112:115]
	ds_read_b128 v[32:35], v207 offset:4096
	ds_read_b128 v[48:51], v207 offset:6144
	s_waitcnt lgkmcnt(1)
	v_mfma_f32_16x16x32_bf16 v[142:145], v[164:167], v[32:35], v[108:111]
	v_mfma_f32_16x16x32_bf16 v[146:149], v[168:171], v[32:35], v[104:107]
	v_mfma_f32_16x16x32_bf16 v[68:71], v[228:231], v[32:35], v[100:103]
	v_mfma_f32_16x16x32_bf16 v[64:67], v[232:235], v[32:35], v[96:99]
	s_waitcnt lgkmcnt(0)
	v_mfma_f32_16x16x32_bf16 v[128:131], v[164:167], v[48:51], v[92:95]
	ds_read_b128 v[32:35], v207 offset:8192
	s_nop 1
	ds_read_b128 v[92:95], v207 offset:10240
	v_mfma_f32_16x16x32_bf16 v[120:123], v[168:171], v[48:51], v[156:159]
	v_mfma_f32_16x16x32_bf16 v[60:63], v[228:231], v[48:51], v[176:179]
	v_mfma_f32_16x16x32_bf16 v[56:59], v[232:235], v[48:51], v[180:183]
	s_waitcnt lgkmcnt(1)
	v_mfma_f32_16x16x32_bf16 v[112:115], v[164:167], v[32:35], v[184:187]
	v_mfma_f32_16x16x32_bf16 v[108:111], v[168:171], v[32:35], v[188:191]
	v_mfma_f32_16x16x32_bf16 v[52:55], v[228:231], v[32:35], v[192:195]
	v_mfma_f32_16x16x32_bf16 v[48:51], v[232:235], v[32:35], v[196:199]
	ds_read_b128 v[32:35], v207 offset:12288
	ds_read_b128 v[116:119], v207 offset:14336
	s_waitcnt lgkmcnt(2)
	v_mfma_f32_16x16x32_bf16 v[104:107], v[164:167], v[92:95], v[200:203]
	v_and_b32_e32 v213, 15, v215
	v_mfma_f32_16x16x32_bf16 v[100:103], v[168:171], v[92:95], v[44:47]
	v_mfma_f32_16x16x32_bf16 v[44:47], v[228:231], v[92:95], v[40:43]
	v_mfma_f32_16x16x32_bf16 v[40:43], v[232:235], v[92:95], v[36:39]
	s_waitcnt lgkmcnt(1)
	v_mfma_f32_16x16x32_bf16 v[96:99], v[164:167], v[32:35], v[28:31]
	v_mfma_f32_16x16x32_bf16 v[92:95], v[168:171], v[32:35], v[24:27]
	v_mfma_f32_16x16x32_bf16 v[36:39], v[228:231], v[32:35], v[76:79]
	v_mfma_f32_16x16x32_bf16 v[32:35], v[232:235], v[32:35], v[216:219]
	s_waitcnt lgkmcnt(0)
	v_mfma_f32_16x16x32_bf16 v[76:79], v[164:167], v[116:119], v[220:223]
	s_nop 0
	v_bfe_u32 v218, v215, 6, 1
	v_bfe_u32 v219, v215, 4, 2
	v_mfma_f32_16x16x32_bf16 v[28:31], v[168:171], v[116:119], v[224:227]
	v_mfma_f32_16x16x32_bf16 v[24:27], v[228:231], v[116:119], v[20:23]
	v_mfma_f32_16x16x32_bf16 v[20:23], v[232:235], v[116:119], v[160:163]
	s_cbranch_vccnz .LBB0_315
	v_and_b32_e32 v0, 0x3ffff80, v215
	v_add_u32_e32 v0, s41, v0
	s_add_u32 s34, s45, 0x4000
	v_or_b32_e32 v0, v0, v213
	s_addc_u32 s35, s48, 0
	v_lshlrev_b32_e32 v2, 6, v0
	s_add_u32 s36, s45, 0x104000
	v_ashrrev_i32_e32 v3, 31, v2
	s_addc_u32 s37, s48, 0
	v_lshlrev_b64 v[116:117], 2, v[2:3]
	v_lshlrev_b32_e32 v0, 4, v219
	v_lshl_add_u64 v[118:119], s[34:35], 0, v[116:117]
	v_lshl_add_u64 v[116:117], s[36:37], 0, v[116:117]
	v_lshl_or_b32 v0, v218, 7, v0
	v_lshl_add_u64 v[132:133], v[118:119], 0, v[0:1]
	v_lshl_add_u64 v[162:163], v[116:117], 0, v[0:1]
	v_lshl_add_u32 v236, v2, 2, v0
	global_load_dwordx4 v[164:167], v236, s[34:35]
	global_load_dwordx4 v[168:171], v236, s[36:37]
	global_load_dwordx4 v[172:175], v236, s[34:35] offset:64
	global_load_dwordx4 v[176:179], v236, s[36:37] offset:64
	v_add_u32_e32 v236, 0x1000, v236
	global_load_dwordx4 v[180:183], v236, s[34:35]
	global_load_dwordx4 v[184:187], v236, s[36:37]
	global_load_dwordx4 v[188:191], v236, s[34:35] offset:64
	global_load_dwordx4 v[192:195], v236, s[36:37] offset:64
	v_add_u32_e32 v236, 0x1000, v236
	global_load_dwordx4 v[196:199], v236, s[34:35]
	global_load_dwordx4 v[200:203], v236, s[36:37]
	global_load_dwordx4 v[204:207], v236, s[34:35] offset:64
	global_load_dwordx4 v[220:223], v236, s[36:37] offset:64
	v_add_u32_e32 v236, 0x1000, v236
	global_load_dwordx4 v[224:227], v236, s[34:35]
	global_load_dwordx4 v[228:231], v236, s[36:37]
	global_load_dwordx4 v[232:235], v236, s[34:35] offset:64
	global_load_dwordx4 v[4:7], v236, s[36:37] offset:64
	v_add_u32_e32 v236, 0x1000, v236
	s_waitcnt vmcnt(14)
; __device__ void even_in_tile(const P& p, int li_even, int tm, int tn, char* smem) {
;     ...
; #pragma unroll
;     for (int i = 0; i < MI; ++i) {
;       const int s = s0 + MROW(i);
; #pragma unroll
;       for (int jj = 0; jj < 2; ++jj) {
;         const int d = wn * 32 + jj * 16 + g * 4;
;         const f32x4 c = *(const f32x4*)(ctab + s * 64 + d);
;         const f32x4 sn = *(const f32x4*)(stab + s * 64 + d);
; #pragma unroll
;         for (int r = 0; r < 4; ++r) {
;           const float a = acc[i][jj][r], bb = acc[i][jj + 2][r];
;           acc[i][jj][r] = a * c[r] - bb * sn[r];
;           acc[i][jj + 2][r] = bb * c[r] + a * sn[r];
;         }
;       }
;     }
	v_mov_b32_e32 v154, v164
	v_mov_b32_e32 v155, v165
	v_mov_b32_e32 v156, v166
	v_mov_b32_e32 v157, v167
	v_mov_b32_e32 v158, v168
	v_mov_b32_e32 v159, v169
	v_mov_b32_e32 v160, v170
	v_mov_b32_e32 v161, v171
	global_load_dwordx4 v[164:167], v236, s[34:35]
	global_load_dwordx4 v[168:171], v236, s[36:37]
	v_pk_mul_f32 v[116:117], v[88:89], v[158:159]
	v_pk_mul_f32 v[118:119], v[124:125], v[158:159]
	v_pk_fma_f32 v[116:117], v[124:125], v[154:155], v[116:117] neg_lo:[0,0,1] neg_hi:[0,0,1]
	v_pk_fma_f32 v[88:89], v[88:89], v[154:155], v[118:119]
	v_mul_f32_e32 v118, v126, v156
	v_mul_f32_e32 v124, v90, v160
	v_mul_f32_e32 v154, v90, v156
	v_mul_f32_e32 v156, v126, v160
	v_mov_b32_e32 v90, v127
	v_mov_b32_e32 v160, v157
	v_mov_b32_e32 v126, v91
	v_pk_mul_f32 v[158:159], v[90:91], v[160:161]
	v_pk_mul_f32 v[90:91], v[126:127], v[160:161]
	v_mov_b32_e32 v119, v158
	v_mov_b32_e32 v155, v90
	v_mov_b32_e32 v157, v91
	v_mov_b32_e32 v125, v159
	v_pk_add_f32 v[90:91], v[154:155], v[156:157]
	v_pk_add_f32 v[118:119], v[118:119], v[124:125] neg_lo:[0,1] neg_hi:[0,1]
	s_waitcnt vmcnt(14)
	v_mov_b32_e32 v154, v172
	v_mov_b32_e32 v155, v173
	v_mov_b32_e32 v156, v174
	v_mov_b32_e32 v157, v175
	v_mov_b32_e32 v158, v176
	v_mov_b32_e32 v159, v177
	v_mov_b32_e32 v160, v178
	v_mov_b32_e32 v161, v179
	global_load_dwordx4 v[172:175], v236, s[34:35] offset:64
	global_load_dwordx4 v[176:179], v236, s[36:37] offset:64
	v_add_u32_e32 v236, 0x1000, v236
	v_pk_mul_f32 v[124:125], v[84:85], v[158:159]
	v_pk_mul_f32 v[126:127], v[150:151], v[158:159]
	v_pk_fma_f32 v[124:125], v[150:151], v[154:155], v[124:125] neg_lo:[0,0,1] neg_hi:[0,0,1]
	v_pk_fma_f32 v[84:85], v[84:85], v[154:155], v[126:127]
	v_mul_f32_e32 v132, v86, v160
	v_mul_f32_e32 v150, v86, v156
	v_mul_f32_e32 v154, v152, v160
	v_mov_b32_e32 v86, v153
	v_mov_b32_e32 v160, v157
	v_mul_f32_e32 v126, v152, v156
	v_pk_mul_f32 v[156:157], v[86:87], v[160:161]
	v_mov_b32_e32 v152, v87
	v_mov_b32_e32 v127, v156
	v_mov_b32_e32 v133, v157
	v_pk_add_f32 v[126:127], v[126:127], v[132:133] neg_lo:[0,1] neg_hi:[0,1]
	v_or_b32_e32 v132, 0x400, v2
	v_pk_mul_f32 v[86:87], v[152:153], v[160:161]
	v_ashrrev_i32_e32 v133, 31, v132
	v_mov_b32_e32 v151, v86
	v_mov_b32_e32 v155, v87
	v_lshlrev_b64 v[132:133], 2, v[132:133]
	v_pk_add_f32 v[86:87], v[150:151], v[154:155]
	v_lshl_add_u64 v[150:151], s[34:35], 0, v[132:133]
	v_lshl_add_u64 v[132:133], s[36:37], 0, v[132:133]
	v_lshl_add_u64 v[158:159], v[150:151], 0, v[0:1]
	v_lshl_add_u64 v[160:161], v[132:133], 0, v[0:1]
	s_waitcnt vmcnt(14)
	v_mov_b32_e32 v150, v180
	v_mov_b32_e32 v151, v181
	v_mov_b32_e32 v152, v182
	v_mov_b32_e32 v153, v183
	v_mov_b32_e32 v154, v184
	v_mov_b32_e32 v155, v185
	v_mov_b32_e32 v156, v186
	v_mov_b32_e32 v157, v187
	global_load_dwordx4 v[180:183], v236, s[34:35]
	global_load_dwordx4 v[184:187], v236, s[36:37]
	v_pk_mul_f32 v[132:133], v[80:81], v[154:155]
	s_nop 0
	v_pk_fma_f32 v[132:133], v[134:135], v[150:151], v[132:133] neg_lo:[0,0,1] neg_hi:[0,0,1]
	v_pk_mul_f32 v[134:135], v[134:135], v[154:155]
	v_mul_f32_e32 v154, v136, v156
	v_pk_fma_f32 v[80:81], v[80:81], v[150:151], v[134:135]
	v_mul_f32_e32 v134, v136, v152
	v_mul_f32_e32 v150, v82, v156
	v_mul_f32_e32 v152, v82, v152
	v_mov_b32_e32 v82, v137
	v_mov_b32_e32 v156, v153
	v_mov_b32_e32 v136, v83
	v_pk_mul_f32 v[162:163], v[82:83], v[156:157]
	v_pk_mul_f32 v[82:83], v[136:137], v[156:157]
	v_mov_b32_e32 v135, v162
	v_mov_b32_e32 v151, v163
	v_mov_b32_e32 v153, v82
	v_mov_b32_e32 v155, v83
	v_pk_add_f32 v[134:135], v[134:135], v[150:151] neg_lo:[0,1] neg_hi:[0,1]
	v_pk_add_f32 v[82:83], v[152:153], v[154:155]
	s_waitcnt vmcnt(14)
	v_mov_b32_e32 v150, v188
	v_mov_b32_e32 v151, v189
	v_mov_b32_e32 v152, v190
	v_mov_b32_e32 v153, v191
	v_mov_b32_e32 v154, v192
	v_mov_b32_e32 v155, v193
	v_mov_b32_e32 v156, v194
	v_mov_b32_e32 v157, v195
	global_load_dwordx4 v[188:191], v236, s[34:35] offset:64
	global_load_dwordx4 v[192:195], v236, s[36:37] offset:64
	v_add_u32_e32 v236, 0x1000, v236
	v_pk_mul_f32 v[136:137], v[72:73], v[154:155]
	s_nop 0
	v_pk_fma_f32 v[136:137], v[138:139], v[150:151], v[136:137] neg_lo:[0,0,1] neg_hi:[0,0,1]
	v_pk_mul_f32 v[138:139], v[138:139], v[154:155]
	v_mul_f32_e32 v154, v140, v156
	v_pk_fma_f32 v[72:73], v[72:73], v[150:151], v[138:139]
	v_mul_f32_e32 v138, v140, v152
	v_mul_f32_e32 v150, v74, v156
	v_mul_f32_e32 v152, v74, v152
	v_mov_b32_e32 v74, v141
	v_mov_b32_e32 v156, v153
	v_mov_b32_e32 v140, v75
	v_pk_mul_f32 v[158:159], v[74:75], v[156:157]
	v_pk_mul_f32 v[74:75], v[140:141], v[156:157]
	v_or_b32_e32 v140, 0x800, v2
	v_ashrrev_i32_e32 v141, 31, v140
	v_mov_b32_e32 v139, v158
	v_mov_b32_e32 v151, v159
	v_lshlrev_b64 v[140:141], 2, v[140:141]
	v_pk_add_f32 v[138:139], v[138:139], v[150:151] neg_lo:[0,1] neg_hi:[0,1]
	v_lshl_add_u64 v[150:151], s[34:35], 0, v[140:141]
	v_lshl_add_u64 v[140:141], s[36:37], 0, v[140:141]
	v_mov_b32_e32 v153, v74
	v_mov_b32_e32 v155, v75
	v_lshl_add_u64 v[158:159], v[150:151], 0, v[0:1]
	v_lshl_add_u64 v[160:161], v[140:141], 0, v[0:1]
	v_pk_add_f32 v[74:75], v[152:153], v[154:155]
	s_waitcnt vmcnt(14)
; __device__ void even_in_tile(const P& p, int li_even, int tm, int tn, char* smem) {
;     ...
; #pragma unroll
;     for (int i = 0; i < MI; ++i) {
;       const int s = s0 + MROW(i);
; #pragma unroll
;       for (int jj = 0; jj < 2; ++jj) {
;         const int d = wn * 32 + jj * 16 + g * 4;
;         const f32x4 c = *(const f32x4*)(ctab + s * 64 + d);
;         const f32x4 sn = *(const f32x4*)(stab + s * 64 + d);
; #pragma unroll
;         for (int r = 0; r < 4; ++r) {
;           const float a = acc[i][jj][r], bb = acc[i][jj + 2][r];
;           acc[i][jj][r] = a * c[r] - bb * sn[r];
;           acc[i][jj + 2][r] = bb * c[r] + a * sn[r];
;         }
;       }
;     }
	v_mov_b32_e32 v150, v196
	v_mov_b32_e32 v151, v197
	v_mov_b32_e32 v152, v198
	v_mov_b32_e32 v153, v199
	v_mov_b32_e32 v154, v200
	v_mov_b32_e32 v155, v201
	v_mov_b32_e32 v156, v202
	v_mov_b32_e32 v157, v203
	global_load_dwordx4 v[196:199], v236, s[34:35]
	global_load_dwordx4 v[200:203], v236, s[36:37]
	v_pk_mul_f32 v[140:141], v[68:69], v[154:155]
	s_nop 0
	v_pk_fma_f32 v[140:141], v[142:143], v[150:151], v[140:141] neg_lo:[0,0,1] neg_hi:[0,0,1]
	v_pk_mul_f32 v[142:143], v[142:143], v[154:155]
	v_mul_f32_e32 v154, v144, v156
	v_pk_fma_f32 v[68:69], v[68:69], v[150:151], v[142:143]
	v_mul_f32_e32 v142, v144, v152
	v_mul_f32_e32 v150, v70, v156
	v_mul_f32_e32 v152, v70, v152
	v_mov_b32_e32 v70, v145
	v_mov_b32_e32 v156, v153
	v_mov_b32_e32 v144, v71
	v_pk_mul_f32 v[162:163], v[70:71], v[156:157]
	v_pk_mul_f32 v[70:71], v[144:145], v[156:157]
	v_mov_b32_e32 v143, v162
	v_mov_b32_e32 v151, v163
	v_mov_b32_e32 v153, v70
	v_mov_b32_e32 v155, v71
	v_pk_add_f32 v[142:143], v[142:143], v[150:151] neg_lo:[0,1] neg_hi:[0,1]
	v_pk_add_f32 v[70:71], v[152:153], v[154:155]
	s_waitcnt vmcnt(14)
	v_mov_b32_e32 v150, v204
	v_mov_b32_e32 v151, v205
	v_mov_b32_e32 v152, v206
	v_mov_b32_e32 v153, v207
	v_mov_b32_e32 v154, v220
	v_mov_b32_e32 v155, v221
	v_mov_b32_e32 v156, v222
	v_mov_b32_e32 v157, v223
	global_load_dwordx4 v[204:207], v236, s[34:35] offset:64
	global_load_dwordx4 v[220:223], v236, s[36:37] offset:64
	v_add_u32_e32 v236, 0x1000, v236
	v_pk_mul_f32 v[144:145], v[64:65], v[154:155]
	s_nop 0
	v_pk_fma_f32 v[144:145], v[146:147], v[150:151], v[144:145] neg_lo:[0,0,1] neg_hi:[0,0,1]
	v_pk_mul_f32 v[146:147], v[146:147], v[154:155]
	v_mul_f32_e32 v154, v148, v156
	v_pk_fma_f32 v[64:65], v[64:65], v[150:151], v[146:147]
	v_mul_f32_e32 v146, v148, v152
	v_mul_f32_e32 v150, v66, v156
	v_mul_f32_e32 v152, v66, v152
	v_mov_b32_e32 v66, v149
	v_mov_b32_e32 v156, v153
	v_mov_b32_e32 v148, v67
	v_pk_mul_f32 v[158:159], v[66:67], v[156:157]
	v_pk_mul_f32 v[66:67], v[148:149], v[156:157]
	v_or_b32_e32 v148, 0xc00, v2
	v_ashrrev_i32_e32 v149, 31, v148
	v_mov_b32_e32 v147, v158
	v_mov_b32_e32 v151, v159
	v_lshlrev_b64 v[148:149], 2, v[148:149]
	v_pk_add_f32 v[146:147], v[146:147], v[150:151] neg_lo:[0,1] neg_hi:[0,1]
	v_lshl_add_u64 v[150:151], s[34:35], 0, v[148:149]
	v_lshl_add_u64 v[148:149], s[36:37], 0, v[148:149]
	v_mov_b32_e32 v153, v66
	v_mov_b32_e32 v155, v67
	v_lshl_add_u64 v[158:159], v[150:151], 0, v[0:1]
	v_lshl_add_u64 v[160:161], v[148:149], 0, v[0:1]
	v_pk_add_f32 v[66:67], v[152:153], v[154:155]
	s_waitcnt vmcnt(14)
	v_mov_b32_e32 v150, v224
	v_mov_b32_e32 v151, v225
	v_mov_b32_e32 v152, v226
	v_mov_b32_e32 v153, v227
	v_mov_b32_e32 v154, v228
	v_mov_b32_e32 v155, v229
	v_mov_b32_e32 v156, v230
	v_mov_b32_e32 v157, v231
	global_load_dwordx4 v[224:227], v236, s[34:35]
	global_load_dwordx4 v[228:231], v236, s[36:37]
	v_pk_mul_f32 v[148:149], v[60:61], v[154:155]
	s_nop 0
	v_pk_fma_f32 v[148:149], v[128:129], v[150:151], v[148:149] neg_lo:[0,0,1] neg_hi:[0,0,1]
	v_pk_mul_f32 v[128:129], v[128:129], v[154:155]
	v_mul_f32_e32 v154, v130, v156
	v_pk_fma_f32 v[60:61], v[60:61], v[150:151], v[128:129]
	v_mul_f32_e32 v128, v130, v152
	v_mul_f32_e32 v150, v62, v156
	v_mul_f32_e32 v152, v62, v152
	v_mov_b32_e32 v62, v131
	v_mov_b32_e32 v156, v153
	v_mov_b32_e32 v130, v63
	v_pk_mul_f32 v[162:163], v[62:63], v[156:157]
	v_pk_mul_f32 v[62:63], v[130:131], v[156:157]
	v_mov_b32_e32 v129, v162
	v_mov_b32_e32 v153, v62
	v_mov_b32_e32 v155, v63
	v_pk_add_f32 v[62:63], v[152:153], v[154:155]
	s_nop 0
	v_mov_b32_e32 v151, v163
	v_pk_add_f32 v[150:151], v[128:129], v[150:151] neg_lo:[0,1] neg_hi:[0,1]
	s_waitcnt vmcnt(14)
	v_mov_b32_e32 v152, v232
	v_mov_b32_e32 v153, v233
	v_mov_b32_e32 v154, v234
	v_mov_b32_e32 v155, v235
	v_mov_b32_e32 v156, v4
	v_mov_b32_e32 v157, v5
	v_mov_b32_e32 v158, v6
	v_mov_b32_e32 v159, v7
	global_load_dwordx4 v[232:235], v236, s[34:35] offset:64
	global_load_dwordx4 v[4:7], v236, s[36:37] offset:64
	v_pk_mul_f32 v[128:129], v[56:57], v[156:157]
	s_nop 0
	v_pk_fma_f32 v[128:129], v[120:121], v[152:153], v[128:129] neg_lo:[0,0,1] neg_hi:[0,0,1]
	v_pk_mul_f32 v[120:121], v[120:121], v[156:157]
	v_mul_f32_e32 v130, v58, v158
	v_pk_fma_f32 v[56:57], v[56:57], v[152:153], v[120:121]
	v_mul_f32_e32 v120, v122, v154
	v_mul_f32_e32 v152, v58, v154
	v_mul_f32_e32 v154, v122, v158
	v_mov_b32_e32 v58, v123
	v_mov_b32_e32 v158, v155
	v_pk_mul_f32 v[156:157], v[58:59], v[158:159]
	v_mov_b32_e32 v122, v59
	v_mov_b32_e32 v121, v156
	v_mov_b32_e32 v131, v157
	v_pk_add_f32 v[130:131], v[120:121], v[130:131] neg_lo:[0,1] neg_hi:[0,1]
	v_or_b32_e32 v120, 0x1000, v2
	v_ashrrev_i32_e32 v121, 31, v120
	v_lshlrev_b64 v[120:121], 2, v[120:121]
	v_pk_mul_f32 v[58:59], v[122:123], v[158:159]
	v_lshl_add_u64 v[122:123], s[34:35], 0, v[120:121]
	v_lshl_add_u64 v[120:121], s[36:37], 0, v[120:121]
	v_mov_b32_e32 v153, v58
	v_mov_b32_e32 v155, v59
	v_lshl_add_u64 v[160:161], v[122:123], 0, v[0:1]
	v_lshl_add_u64 v[162:163], v[120:121], 0, v[0:1]
	v_pk_add_f32 v[58:59], v[152:153], v[154:155]
	s_waitcnt vmcnt(14)
	v_mov_b32_e32 v152, v164
	v_mov_b32_e32 v153, v165
	v_mov_b32_e32 v154, v166
	v_mov_b32_e32 v155, v167
	v_mov_b32_e32 v156, v168
	v_mov_b32_e32 v157, v169
	v_mov_b32_e32 v158, v170
	v_mov_b32_e32 v159, v171
	v_pk_mul_f32 v[120:121], v[52:53], v[156:157]
	s_nop 0
	v_pk_fma_f32 v[120:121], v[112:113], v[152:153], v[120:121] neg_lo:[0,0,1] neg_hi:[0,0,1]
	v_pk_mul_f32 v[112:113], v[112:113], v[156:157]
	v_mul_f32_e32 v122, v54, v158
	v_pk_fma_f32 v[52:53], v[52:53], v[152:153], v[112:113]
	v_mul_f32_e32 v112, v114, v154
	v_mul_f32_e32 v152, v54, v154
	v_mul_f32_e32 v154, v114, v158
	v_mov_b32_e32 v54, v115
	v_mov_b32_e32 v158, v155
	v_mov_b32_e32 v114, v55
	v_pk_mul_f32 v[156:157], v[54:55], v[158:159]
	v_pk_mul_f32 v[54:55], v[114:115], v[158:159]
	v_mov_b32_e32 v113, v156
	v_mov_b32_e32 v153, v54
	v_mov_b32_e32 v155, v55
	v_mov_b32_e32 v123, v157
	v_pk_add_f32 v[54:55], v[152:153], v[154:155]
	v_pk_add_f32 v[122:123], v[112:113], v[122:123] neg_lo:[0,1] neg_hi:[0,1]
	s_waitcnt vmcnt(12)
; __device__ void even_in_tile(const P& p, int li_even, int tm, int tn, char* smem) {
;     ...
; #pragma unroll
;     for (int i = 0; i < MI; ++i) {
;       const int s = s0 + MROW(i);
; #pragma unroll
;       for (int jj = 0; jj < 2; ++jj) {
;         const int d = wn * 32 + jj * 16 + g * 4;
;         const f32x4 c = *(const f32x4*)(ctab + s * 64 + d);
;         const f32x4 sn = *(const f32x4*)(stab + s * 64 + d);
; #pragma unroll
;         for (int r = 0; r < 4; ++r) {
;           const float a = acc[i][jj][r], bb = acc[i][jj + 2][r];
;           acc[i][jj][r] = a * c[r] - bb * sn[r];
;           acc[i][jj + 2][r] = bb * c[r] + a * sn[r];
;         }
;       }
;     }
	v_mov_b32_e32 v152, v172
	v_mov_b32_e32 v153, v173
	v_mov_b32_e32 v154, v174
	v_mov_b32_e32 v155, v175
	v_mov_b32_e32 v156, v176
	v_mov_b32_e32 v157, v177
	v_mov_b32_e32 v158, v178
	v_mov_b32_e32 v159, v179
	v_pk_mul_f32 v[112:113], v[48:49], v[156:157]
	s_nop 0
	v_pk_fma_f32 v[112:113], v[108:109], v[152:153], v[112:113] neg_lo:[0,0,1] neg_hi:[0,0,1]
	v_pk_mul_f32 v[108:109], v[108:109], v[156:157]
	v_mul_f32_e32 v114, v50, v158
	v_pk_fma_f32 v[48:49], v[48:49], v[152:153], v[108:109]
	v_mul_f32_e32 v108, v110, v154
	v_mul_f32_e32 v152, v50, v154
	v_mul_f32_e32 v154, v110, v158
	v_mov_b32_e32 v50, v111
	v_mov_b32_e32 v158, v155
	v_pk_mul_f32 v[156:157], v[50:51], v[158:159]
	v_mov_b32_e32 v110, v51
	v_mov_b32_e32 v109, v156
	v_mov_b32_e32 v115, v157
	v_pk_add_f32 v[114:115], v[108:109], v[114:115] neg_lo:[0,1] neg_hi:[0,1]
	v_or_b32_e32 v108, 0x1400, v2
	v_ashrrev_i32_e32 v109, 31, v108
	v_lshlrev_b64 v[108:109], 2, v[108:109]
	v_pk_mul_f32 v[50:51], v[110:111], v[158:159]
	v_lshl_add_u64 v[110:111], s[34:35], 0, v[108:109]
	v_lshl_add_u64 v[108:109], s[36:37], 0, v[108:109]
	v_mov_b32_e32 v153, v50
	v_mov_b32_e32 v155, v51
	v_lshl_add_u64 v[160:161], v[110:111], 0, v[0:1]
	v_lshl_add_u64 v[162:163], v[108:109], 0, v[0:1]
	v_pk_add_f32 v[50:51], v[152:153], v[154:155]
	s_waitcnt vmcnt(10)
	v_mov_b32_e32 v152, v180
	v_mov_b32_e32 v153, v181
	v_mov_b32_e32 v154, v182
	v_mov_b32_e32 v155, v183
	v_mov_b32_e32 v156, v184
	v_mov_b32_e32 v157, v185
	v_mov_b32_e32 v158, v186
	v_mov_b32_e32 v159, v187
	v_pk_mul_f32 v[108:109], v[44:45], v[156:157]
	s_nop 0
	v_pk_fma_f32 v[108:109], v[104:105], v[152:153], v[108:109] neg_lo:[0,0,1] neg_hi:[0,0,1]
	v_pk_mul_f32 v[104:105], v[104:105], v[156:157]
	v_mul_f32_e32 v110, v46, v158
	v_pk_fma_f32 v[44:45], v[44:45], v[152:153], v[104:105]
	v_mul_f32_e32 v104, v106, v154
	v_mul_f32_e32 v152, v46, v154
	v_mul_f32_e32 v154, v106, v158
	v_mov_b32_e32 v46, v107
	v_mov_b32_e32 v158, v155
	v_mov_b32_e32 v106, v47
	v_pk_mul_f32 v[156:157], v[46:47], v[158:159]
	v_pk_mul_f32 v[46:47], v[106:107], v[158:159]
	v_mov_b32_e32 v105, v156
	v_mov_b32_e32 v153, v46
	v_mov_b32_e32 v155, v47
	v_mov_b32_e32 v111, v157
	v_pk_add_f32 v[46:47], v[152:153], v[154:155]
	v_pk_add_f32 v[110:111], v[104:105], v[110:111] neg_lo:[0,1] neg_hi:[0,1]
	s_waitcnt vmcnt(8)
	v_mov_b32_e32 v152, v188
	v_mov_b32_e32 v153, v189
	v_mov_b32_e32 v154, v190
	v_mov_b32_e32 v155, v191
	v_mov_b32_e32 v156, v192
	v_mov_b32_e32 v157, v193
	v_mov_b32_e32 v158, v194
	v_mov_b32_e32 v159, v195
	v_pk_mul_f32 v[104:105], v[40:41], v[156:157]
	s_nop 0
	v_pk_fma_f32 v[104:105], v[100:101], v[152:153], v[104:105] neg_lo:[0,0,1] neg_hi:[0,0,1]
	v_pk_mul_f32 v[100:101], v[100:101], v[156:157]
	v_mul_f32_e32 v106, v42, v158
	v_pk_fma_f32 v[40:41], v[40:41], v[152:153], v[100:101]
	v_mul_f32_e32 v100, v102, v154
	v_mul_f32_e32 v152, v42, v154
	v_mul_f32_e32 v154, v102, v158
	v_mov_b32_e32 v42, v103
	v_mov_b32_e32 v158, v155
	v_pk_mul_f32 v[156:157], v[42:43], v[158:159]
	v_mov_b32_e32 v102, v43
	v_mov_b32_e32 v101, v156
	v_mov_b32_e32 v107, v157
	v_pk_add_f32 v[106:107], v[100:101], v[106:107] neg_lo:[0,1] neg_hi:[0,1]
	v_or_b32_e32 v100, 0x1800, v2
	v_ashrrev_i32_e32 v101, 31, v100
	v_lshlrev_b64 v[100:101], 2, v[100:101]
	v_pk_mul_f32 v[42:43], v[102:103], v[158:159]
	v_lshl_add_u64 v[102:103], s[34:35], 0, v[100:101]
	v_lshl_add_u64 v[100:101], s[36:37], 0, v[100:101]
	v_mov_b32_e32 v153, v42
	v_mov_b32_e32 v155, v43
	v_lshl_add_u64 v[160:161], v[102:103], 0, v[0:1]
	v_lshl_add_u64 v[162:163], v[100:101], 0, v[0:1]
	v_pk_add_f32 v[42:43], v[152:153], v[154:155]
	v_or_b32_e32 v2, 0x1c00, v2
	v_ashrrev_i32_e32 v3, 31, v2
	v_lshlrev_b64 v[2:3], 2, v[2:3]
	s_waitcnt vmcnt(6)
	v_mov_b32_e32 v152, v196
	v_mov_b32_e32 v153, v197
	v_mov_b32_e32 v154, v198
	v_mov_b32_e32 v155, v199
	v_mov_b32_e32 v156, v200
	v_mov_b32_e32 v157, v201
	v_mov_b32_e32 v158, v202
	v_mov_b32_e32 v159, v203
	v_pk_mul_f32 v[100:101], v[36:37], v[156:157]
	s_nop 0
	v_pk_fma_f32 v[100:101], v[96:97], v[152:153], v[100:101] neg_lo:[0,0,1] neg_hi:[0,0,1]
	v_pk_mul_f32 v[96:97], v[96:97], v[156:157]
	v_mul_f32_e32 v102, v38, v158
	v_pk_fma_f32 v[36:37], v[36:37], v[152:153], v[96:97]
	v_mul_f32_e32 v96, v98, v154
	v_mul_f32_e32 v152, v38, v154
	v_mul_f32_e32 v154, v98, v158
	v_mov_b32_e32 v38, v99
	v_mov_b32_e32 v158, v155
	v_mov_b32_e32 v98, v39
	v_pk_mul_f32 v[156:157], v[38:39], v[158:159]
	v_pk_mul_f32 v[38:39], v[98:99], v[158:159]
	v_mov_b32_e32 v97, v156
	v_mov_b32_e32 v153, v38
	v_mov_b32_e32 v155, v39
	v_mov_b32_e32 v103, v157
	v_pk_add_f32 v[38:39], v[152:153], v[154:155]
	v_pk_add_f32 v[102:103], v[96:97], v[102:103] neg_lo:[0,1] neg_hi:[0,1]
	s_waitcnt vmcnt(4)
; __device__ void even_in_tile(const P& p, int li_even, int tm, int tn, char* smem) {
;     ...
; #pragma unroll
;     for (int i = 0; i < MI; ++i) {
;       const int s = s0 + MROW(i);
; #pragma unroll
;       for (int jj = 0; jj < 2; ++jj) {
;         const int d = wn * 32 + jj * 16 + g * 4;
;         const f32x4 c = *(const f32x4*)(ctab + s * 64 + d);
;         const f32x4 sn = *(const f32x4*)(stab + s * 64 + d);
; #pragma unroll
;         for (int r = 0; r < 4; ++r) {
;           const float a = acc[i][jj][r], bb = acc[i][jj + 2][r];
;           acc[i][jj][r] = a * c[r] - bb * sn[r];
;           acc[i][jj + 2][r] = bb * c[r] + a * sn[r];
;         }
;       }
;     }
;   }
;   if (seg == 1) {
	v_mov_b32_e32 v152, v204
	v_mov_b32_e32 v153, v205
	v_mov_b32_e32 v154, v206
	v_mov_b32_e32 v155, v207
	v_mov_b32_e32 v156, v220
	v_mov_b32_e32 v157, v221
	v_mov_b32_e32 v158, v222
	v_mov_b32_e32 v159, v223
	v_pk_mul_f32 v[96:97], v[32:33], v[156:157]
	s_nop 0
	v_pk_fma_f32 v[96:97], v[92:93], v[152:153], v[96:97] neg_lo:[0,0,1] neg_hi:[0,0,1]
	v_pk_mul_f32 v[92:93], v[92:93], v[156:157]
	v_mul_f32_e32 v98, v34, v158
	v_pk_fma_f32 v[32:33], v[32:33], v[152:153], v[92:93]
	v_mul_f32_e32 v92, v94, v154
	v_mul_f32_e32 v152, v34, v154
	v_mul_f32_e32 v154, v94, v158
	v_mov_b32_e32 v34, v95
	v_mov_b32_e32 v158, v155
	v_pk_mul_f32 v[156:157], v[34:35], v[158:159]
	v_mov_b32_e32 v94, v35
	v_mov_b32_e32 v93, v156
	v_mov_b32_e32 v99, v157
	v_pk_add_f32 v[98:99], v[92:93], v[98:99] neg_lo:[0,1] neg_hi:[0,1]
	v_pk_mul_f32 v[34:35], v[94:95], v[158:159]
	v_lshl_add_u64 v[92:93], s[34:35], 0, v[2:3]
	v_lshl_add_u64 v[2:3], s[36:37], 0, v[2:3]
	v_mov_b32_e32 v153, v34
	v_mov_b32_e32 v155, v35
	v_lshl_add_u64 v[160:161], v[92:93], 0, v[0:1]
	v_lshl_add_u64 v[2:3], v[2:3], 0, v[0:1]
	v_pk_add_f32 v[34:35], v[152:153], v[154:155]
	s_waitcnt vmcnt(2)
	v_mov_b32_e32 v152, v224
	v_mov_b32_e32 v153, v225
	v_mov_b32_e32 v154, v226
	v_mov_b32_e32 v155, v227
	v_mov_b32_e32 v156, v228
	v_mov_b32_e32 v157, v229
	v_mov_b32_e32 v158, v230
	v_mov_b32_e32 v159, v231
	v_pk_mul_f32 v[92:93], v[24:25], v[156:157]
	s_nop 0
	v_pk_fma_f32 v[92:93], v[76:77], v[152:153], v[92:93] neg_lo:[0,0,1] neg_hi:[0,0,1]
	v_pk_mul_f32 v[76:77], v[76:77], v[156:157]
	v_mul_f32_e32 v94, v26, v158
	v_pk_fma_f32 v[24:25], v[24:25], v[152:153], v[76:77]
	v_mul_f32_e32 v76, v78, v154
	v_mul_f32_e32 v152, v26, v154
	v_mul_f32_e32 v154, v78, v158
	v_mov_b32_e32 v26, v79
	v_mov_b32_e32 v158, v155
	v_mov_b32_e32 v78, v27
	v_pk_mul_f32 v[156:157], v[26:27], v[158:159]
	v_pk_mul_f32 v[26:27], v[78:79], v[158:159]
	v_mov_b32_e32 v77, v156
	v_mov_b32_e32 v95, v157
	v_mov_b32_e32 v153, v26
	v_mov_b32_e32 v155, v27
	v_pk_add_f32 v[94:95], v[76:77], v[94:95] neg_lo:[0,1] neg_hi:[0,1]
	v_pk_add_f32 v[26:27], v[152:153], v[154:155]
	s_waitcnt vmcnt(0)
	v_mov_b32_e32 v76, v232
	v_mov_b32_e32 v77, v233
	v_mov_b32_e32 v78, v234
	v_mov_b32_e32 v79, v235
	v_mov_b32_e32 v152, v4
	v_mov_b32_e32 v153, v5
	v_mov_b32_e32 v154, v6
	v_mov_b32_e32 v155, v7
	v_pk_mul_f32 v[2:3], v[20:21], v[152:153]
	s_nop 0
	v_pk_fma_f32 v[156:157], v[28:29], v[76:77], v[2:3] neg_lo:[0,0,1] neg_hi:[0,0,1]
	v_pk_mul_f32 v[2:3], v[28:29], v[152:153]
	v_mul_f32_e32 v28, v22, v154
	v_pk_fma_f32 v[20:21], v[20:21], v[76:77], v[2:3]
	v_mul_f32_e32 v2, v30, v78
	v_mul_f32_e32 v76, v22, v78
	v_mul_f32_e32 v78, v30, v154
	v_mov_b32_e32 v22, v31
	v_mov_b32_e32 v154, v79
	v_pk_mul_f32 v[152:153], v[22:23], v[154:155]
	v_mov_b32_e32 v30, v23
	v_mov_b32_e32 v3, v152
	v_mov_b32_e32 v29, v153
	v_pk_add_f32 v[158:159], v[2:3], v[28:29] neg_lo:[0,1] neg_hi:[0,1]
	v_pk_mul_f32 v[2:3], v[30:31], v[154:155]
	v_mov_b64_e32 v[28:29], v[156:157]
	v_mov_b32_e32 v77, v2
	v_mov_b32_e32 v79, v3
	v_pk_add_f32 v[22:23], v[76:77], v[78:79]
	v_mov_b64_e32 v[76:77], v[92:93]
	v_mov_b64_e32 v[78:79], v[94:95]
	v_mov_b64_e32 v[92:93], v[96:97]
	v_mov_b64_e32 v[94:95], v[98:99]
	v_mov_b64_e32 v[96:97], v[100:101]
	v_mov_b64_e32 v[98:99], v[102:103]
	v_mov_b64_e32 v[100:101], v[104:105]
	v_mov_b64_e32 v[102:103], v[106:107]
	v_mov_b64_e32 v[104:105], v[108:109]
	v_mov_b64_e32 v[106:107], v[110:111]
	v_mov_b64_e32 v[108:109], v[112:113]
	v_mov_b64_e32 v[110:111], v[114:115]
	v_mov_b64_e32 v[112:113], v[120:121]
	v_mov_b64_e32 v[114:115], v[122:123]
	v_mov_b64_e32 v[120:121], v[128:129]
	v_mov_b64_e32 v[122:123], v[130:131]
	v_mov_b64_e32 v[128:129], v[148:149]
	v_mov_b64_e32 v[130:131], v[150:151]
	v_mov_b64_e32 v[148:149], v[146:147]
	v_mov_b64_e32 v[146:147], v[144:145]
	v_mov_b64_e32 v[144:145], v[142:143]
	v_mov_b64_e32 v[142:143], v[140:141]
	v_mov_b64_e32 v[140:141], v[138:139]
	v_mov_b64_e32 v[152:153], v[126:127]
	v_mov_b64_e32 v[138:139], v[136:137]
	v_mov_b64_e32 v[136:137], v[134:135]
	v_mov_b64_e32 v[150:151], v[124:125]
	v_mov_b64_e32 v[126:127], v[118:119]
	v_mov_b64_e32 v[30:31], v[158:159]
	v_mov_b64_e32 v[134:135], v[132:133]
	v_mov_b64_e32 v[124:125], v[116:117]
	s_cmp_eq_u32 s42, 1
	s_cselect_b64 s[34:35], -1, 0
	s_cmp_lg_u32 s42, 1
	s_cbranch_scc0 .LBB0_316

; __device__ void peer_v(const P& p, int layer, int tok, bool dry) {
;     ...
;   {
;     const int* rt = (const int*)(ws + OFF_S) + (size_t)tok * 256;
;     eidx[0] = rt[lane]; eidx[1] = rt[64 + lane];
;     wreg[0] = ((const float*)rt)[128 + lane]; wreg[1] = ((const float*)rt)[192 + lane];
;   }
;   f32x2 oa2[8];
; #pragma unroll
;   for (int e = 0; e < 8; ++e) oa2[e] = (f32x2){0.f, 0.f};
; #pragma unroll
;   for (int h2 = 0; h2 < 2; ++h2) {
;     for (int jb = 0; jb < 64; jb += 16) {
;       u32x2 vv[16];
; #pragma unroll
;       for (int q = 0; q < 16; ++q) {
;         const int e = __builtin_amdgcn_readlane(eidx[h2], jb + q);
;         vv[q] = ((const u32x2*)(V4 + (size_t)e * 512))[lane];
;       }
; #pragma unroll
;       for (int q = 0; q < 16; ++q) {
;         const float wq = rdlane_f(wreg[h2], jb + q);
;         const f32x2 w2 = {wq, wq};
; #pragma unroll
;         for (int k = 0; k < 2; ++k) {
;           oa2[4 * k + 0] += w2 * __builtin_amdgcn_cvt_scalef32_pk_f32_fp4(vv[q][k], 1.0f, 0);
;           oa2[4 * k + 1] += w2 * __builtin_amdgcn_cvt_scalef32_pk_f32_fp4(vv[q][k], 1.0f, 1);
;           oa2[4 * k + 2] += w2 * __builtin_amdgcn_cvt_scalef32_pk_f32_fp4(vv[q][k], 1.0f, 2);
;           oa2[4 * k + 3] += w2 * __builtin_amdgcn_cvt_scalef32_pk_f32_fp4(vv[q][k], 1.0f, 3);
;         }
;       }
.LBB0_1048:
	s_mov_b64 s[8:9], 0
	s_add_u32 s8, s68, s8
	v_mov_b32_e32 v0, v208
	v_ashrrev_i32_e32 v3, 31, v2
	s_addc_u32 s9, s69, s9
	s_waitcnt vmcnt(10)
	v_lshlrev_b64 v[64:65], 10, v[2:3]
	v_and_b32_e32 v70, 63, v0
	v_lshl_add_u64 v[20:21], s[8:9], 0, v[64:65]
	v_lshlrev_b32_e32 v0, 2, v70
	v_lshl_add_u64 v[20:21], v[20:21], 0, v[0:1]
	s_mov_b64 s[10:11], 0x29a84000
	v_lshl_add_u64 v[22:23], v[20:21], 0, s[10:11]
	s_mov_b32 s10, 0x29a84000
	v_add_co_u32_e32 v20, vcc, s10, v20
	s_add_u32 s10, s8, s12
	s_nop 0
	v_addc_co_u32_e32 v21, vcc, 0, v21, vcc
	global_load_dword v12, v[20:21], off
	global_load_dword v13, v[22:23], off offset:256
	global_load_dword v14, v[22:23], off offset:512
	global_load_dword v15, v[22:23], off offset:768
	s_addc_u32 s11, s9, 0
	v_lshlrev_b32_e32 v20, 3, v70
	v_mov_b32_e32 v21, v1
	v_lshl_add_u64 v[20:21], s[10:11], 0, v[20:21]
	s_mov_b64 s[10:11], 0x5a84000
	v_lshl_add_u64 v[20:21], v[20:21], 0, s[10:11]
	s_waitcnt vmcnt(3)
	s_add_u32 s14, s8, s12
	s_addc_u32 s15, s9, 0
	s_add_u32 s14, s14, 0x5a84000
	s_addc_u32 s15, s15, 0
	v_lshlrev_b32_e32 v213, 3, v70
	v_lshlrev_b32_e32 v66, 6, v70
	v_mov_b32_e32 v67, v1
	v_lshlrev_b32_e32 v12, 9, v12
	v_mov_b32_e32 v62, 0
	v_mov_b32_e32 v63, 0
	v_mov_b32_e32 v60, 0
	v_mov_b32_e32 v61, 0
	v_mov_b32_e32 v52, 0
	v_mov_b32_e32 v53, 0
	v_mov_b32_e32 v54, 0
	v_mov_b32_e32 v55, 0
	v_mov_b32_e32 v56, 0
	v_mov_b32_e32 v57, 0
	v_mov_b32_e32 v58, 0
	v_mov_b32_e32 v59, 0
	v_mov_b32_e32 v50, 0
	v_mov_b32_e32 v51, 0
	v_mov_b32_e32 v48, 0
	v_mov_b32_e32 v49, 0
	v_readlane_b32 s22, v12, 0
	s_add_u32 s16, s14, s22
	s_addc_u32 s17, s15, 0
	global_load_dwordx2 v[80:81], v213, s[16:17]
	v_readlane_b32 s28, v12, 1
	s_add_u32 s20, s14, s28
	s_addc_u32 s21, s15, 0
	global_load_dwordx2 v[82:83], v213, s[20:21]
	v_readlane_b32 s29, v12, 2
	s_add_u32 s24, s14, s29
	s_addc_u32 s25, s15, 0
	global_load_dwordx2 v[84:85], v213, s[24:25]
	v_readlane_b32 s30, v12, 3
	s_add_u32 s26, s14, s30
	s_addc_u32 s27, s15, 0
	global_load_dwordx2 v[86:87], v213, s[26:27]
	v_readlane_b32 s22, v12, 4
	s_add_u32 s16, s14, s22
	s_addc_u32 s17, s15, 0
	global_load_dwordx2 v[88:89], v213, s[16:17]
	v_readlane_b32 s28, v12, 5
	s_add_u32 s20, s14, s28
	s_addc_u32 s21, s15, 0
	global_load_dwordx2 v[90:91], v213, s[20:21]
	v_readlane_b32 s29, v12, 6
	s_add_u32 s24, s14, s29
	s_addc_u32 s25, s15, 0
	global_load_dwordx2 v[92:93], v213, s[24:25]
	v_readlane_b32 s30, v12, 7
	s_add_u32 s26, s14, s30
	s_addc_u32 s27, s15, 0
	global_load_dwordx2 v[94:95], v213, s[26:27]
	v_readlane_b32 s22, v12, 8
	s_add_u32 s16, s14, s22
	s_addc_u32 s17, s15, 0
	global_load_dwordx2 v[96:97], v213, s[16:17]
	v_readlane_b32 s28, v12, 9
	s_add_u32 s20, s14, s28
	s_addc_u32 s21, s15, 0
	global_load_dwordx2 v[98:99], v213, s[20:21]
	v_readlane_b32 s29, v12, 10
	s_add_u32 s24, s14, s29
	s_addc_u32 s25, s15, 0
	global_load_dwordx2 v[100:101], v213, s[24:25]
	v_readlane_b32 s30, v12, 11
	s_add_u32 s26, s14, s30
	s_addc_u32 s27, s15, 0
	global_load_dwordx2 v[102:103], v213, s[26:27]
	v_readlane_b32 s22, v12, 12
	s_add_u32 s16, s14, s22
	s_addc_u32 s17, s15, 0
	global_load_dwordx2 v[104:105], v213, s[16:17]
	v_readlane_b32 s28, v12, 13
	s_add_u32 s20, s14, s28
	s_addc_u32 s21, s15, 0
	global_load_dwordx2 v[106:107], v213, s[20:21]
	v_readlane_b32 s29, v12, 14
	s_add_u32 s24, s14, s29
	s_addc_u32 s25, s15, 0
	global_load_dwordx2 v[108:109], v213, s[24:25]
	v_readlane_b32 s30, v12, 15
	s_add_u32 s26, s14, s30
	s_addc_u32 s27, s15, 0
	global_load_dwordx2 v[110:111], v213, s[26:27]
	s_waitcnt vmcnt(12)
	v_readlane_b32 s32, v14, 0
	v_cvt_scalef32_pk_f32_fp4 v[4:5], v80, 1.0
	v_cvt_scalef32_pk_f32_fp4 v[6:7], v80, 1.0 op_sel:[1,0,0]
	v_cvt_scalef32_pk_f32_fp4 v[8:9], v80, 1.0 op_sel:[0,1,0]
	v_cvt_scalef32_pk_f32_fp4 v[10:11], v80, 1.0 op_sel:[1,1,0]
	v_pk_fma_f32 v[62:63], s[32:33], v[4:5], v[62:63] op_sel_hi:[0,1,1]
	v_pk_fma_f32 v[60:61], s[32:33], v[6:7], v[60:61] op_sel_hi:[0,1,1]
	v_pk_fma_f32 v[52:53], s[32:33], v[8:9], v[52:53] op_sel_hi:[0,1,1]
	v_pk_fma_f32 v[54:55], s[32:33], v[10:11], v[54:55] op_sel_hi:[0,1,1]
	v_cvt_scalef32_pk_f32_fp4 v[4:5], v81, 1.0
	v_cvt_scalef32_pk_f32_fp4 v[6:7], v81, 1.0 op_sel:[1,0,0]
	v_cvt_scalef32_pk_f32_fp4 v[8:9], v81, 1.0 op_sel:[0,1,0]
	v_cvt_scalef32_pk_f32_fp4 v[10:11], v81, 1.0 op_sel:[1,1,0]
	v_pk_fma_f32 v[56:57], s[32:33], v[4:5], v[56:57] op_sel_hi:[0,1,1]
	v_pk_fma_f32 v[58:59], s[32:33], v[6:7], v[58:59] op_sel_hi:[0,1,1]
	v_pk_fma_f32 v[50:51], s[32:33], v[8:9], v[50:51] op_sel_hi:[0,1,1]
	v_pk_fma_f32 v[48:49], s[32:33], v[10:11], v[48:49] op_sel_hi:[0,1,1]
	v_readlane_b32 s22, v12, 16
	s_add_u32 s16, s14, s22
	s_addc_u32 s17, s15, 0
	global_load_dwordx2 v[80:81], v213, s[16:17]
	v_readlane_b32 s34, v14, 1
	v_cvt_scalef32_pk_f32_fp4 v[4:5], v82, 1.0
	v_cvt_scalef32_pk_f32_fp4 v[6:7], v82, 1.0 op_sel:[1,0,0]
	v_cvt_scalef32_pk_f32_fp4 v[8:9], v82, 1.0 op_sel:[0,1,0]
	v_cvt_scalef32_pk_f32_fp4 v[10:11], v82, 1.0 op_sel:[1,1,0]
	v_pk_fma_f32 v[62:63], s[34:35], v[4:5], v[62:63] op_sel_hi:[0,1,1]
	v_pk_fma_f32 v[60:61], s[34:35], v[6:7], v[60:61] op_sel_hi:[0,1,1]
	v_pk_fma_f32 v[52:53], s[34:35], v[8:9], v[52:53] op_sel_hi:[0,1,1]
	v_pk_fma_f32 v[54:55], s[34:35], v[10:11], v[54:55] op_sel_hi:[0,1,1]
	v_cvt_scalef32_pk_f32_fp4 v[4:5], v83, 1.0
	v_cvt_scalef32_pk_f32_fp4 v[6:7], v83, 1.0 op_sel:[1,0,0]
	v_cvt_scalef32_pk_f32_fp4 v[8:9], v83, 1.0 op_sel:[0,1,0]
	v_cvt_scalef32_pk_f32_fp4 v[10:11], v83, 1.0 op_sel:[1,1,0]
	v_pk_fma_f32 v[56:57], s[34:35], v[4:5], v[56:57] op_sel_hi:[0,1,1]
	v_pk_fma_f32 v[58:59], s[34:35], v[6:7], v[58:59] op_sel_hi:[0,1,1]
	v_pk_fma_f32 v[50:51], s[34:35], v[8:9], v[50:51] op_sel_hi:[0,1,1]
; __device__ void peer_v(const P& p, int layer, int tok, bool dry) {
;     ...
;     for (int jb = 0; jb < 64; jb += 16) {
;       u32x2 vv[16];
; #pragma unroll
;       for (int q = 0; q < 16; ++q) {
;         const int e = __builtin_amdgcn_readlane(eidx[h2], jb + q);
;         vv[q] = ((const u32x2*)(V4 + (size_t)e * 512))[lane];
;       }
; #pragma unroll
;       for (int q = 0; q < 16; ++q) {
;         const float wq = rdlane_f(wreg[h2], jb + q);
;         const f32x2 w2 = {wq, wq};
; #pragma unroll
;         for (int k = 0; k < 2; ++k) {
;           oa2[4 * k + 0] += w2 * __builtin_amdgcn_cvt_scalef32_pk_f32_fp4(vv[q][k], 1.0f, 0);
;           oa2[4 * k + 1] += w2 * __builtin_amdgcn_cvt_scalef32_pk_f32_fp4(vv[q][k], 1.0f, 1);
;           oa2[4 * k + 2] += w2 * __builtin_amdgcn_cvt_scalef32_pk_f32_fp4(vv[q][k], 1.0f, 2);
;           oa2[4 * k + 3] += w2 * __builtin_amdgcn_cvt_scalef32_pk_f32_fp4(vv[q][k], 1.0f, 3);
;         }
;       }
	v_pk_fma_f32 v[48:49], s[34:35], v[10:11], v[48:49] op_sel_hi:[0,1,1]
	v_readlane_b32 s28, v12, 17
	s_add_u32 s20, s14, s28
	s_addc_u32 s21, s15, 0
	global_load_dwordx2 v[82:83], v213, s[20:21]
	v_readlane_b32 s32, v14, 2
	v_cvt_scalef32_pk_f32_fp4 v[4:5], v84, 1.0
	v_cvt_scalef32_pk_f32_fp4 v[6:7], v84, 1.0 op_sel:[1,0,0]
	v_cvt_scalef32_pk_f32_fp4 v[8:9], v84, 1.0 op_sel:[0,1,0]
	v_cvt_scalef32_pk_f32_fp4 v[10:11], v84, 1.0 op_sel:[1,1,0]
	v_pk_fma_f32 v[62:63], s[32:33], v[4:5], v[62:63] op_sel_hi:[0,1,1]
	v_pk_fma_f32 v[60:61], s[32:33], v[6:7], v[60:61] op_sel_hi:[0,1,1]
	v_pk_fma_f32 v[52:53], s[32:33], v[8:9], v[52:53] op_sel_hi:[0,1,1]
	v_pk_fma_f32 v[54:55], s[32:33], v[10:11], v[54:55] op_sel_hi:[0,1,1]
	v_cvt_scalef32_pk_f32_fp4 v[4:5], v85, 1.0
	v_cvt_scalef32_pk_f32_fp4 v[6:7], v85, 1.0 op_sel:[1,0,0]
	v_cvt_scalef32_pk_f32_fp4 v[8:9], v85, 1.0 op_sel:[0,1,0]
	v_cvt_scalef32_pk_f32_fp4 v[10:11], v85, 1.0 op_sel:[1,1,0]
	v_pk_fma_f32 v[56:57], s[32:33], v[4:5], v[56:57] op_sel_hi:[0,1,1]
	v_pk_fma_f32 v[58:59], s[32:33], v[6:7], v[58:59] op_sel_hi:[0,1,1]
	v_pk_fma_f32 v[50:51], s[32:33], v[8:9], v[50:51] op_sel_hi:[0,1,1]
	v_pk_fma_f32 v[48:49], s[32:33], v[10:11], v[48:49] op_sel_hi:[0,1,1]
	v_readlane_b32 s29, v12, 18
	s_add_u32 s24, s14, s29
	s_addc_u32 s25, s15, 0
	global_load_dwordx2 v[84:85], v213, s[24:25]
	v_readlane_b32 s34, v14, 3
	v_cvt_scalef32_pk_f32_fp4 v[4:5], v86, 1.0
	v_cvt_scalef32_pk_f32_fp4 v[6:7], v86, 1.0 op_sel:[1,0,0]
	v_cvt_scalef32_pk_f32_fp4 v[8:9], v86, 1.0 op_sel:[0,1,0]
	v_cvt_scalef32_pk_f32_fp4 v[10:11], v86, 1.0 op_sel:[1,1,0]
	v_pk_fma_f32 v[62:63], s[34:35], v[4:5], v[62:63] op_sel_hi:[0,1,1]
	v_pk_fma_f32 v[60:61], s[34:35], v[6:7], v[60:61] op_sel_hi:[0,1,1]
	v_pk_fma_f32 v[52:53], s[34:35], v[8:9], v[52:53] op_sel_hi:[0,1,1]
	v_pk_fma_f32 v[54:55], s[34:35], v[10:11], v[54:55] op_sel_hi:[0,1,1]
	v_cvt_scalef32_pk_f32_fp4 v[4:5], v87, 1.0
	v_cvt_scalef32_pk_f32_fp4 v[6:7], v87, 1.0 op_sel:[1,0,0]
	v_cvt_scalef32_pk_f32_fp4 v[8:9], v87, 1.0 op_sel:[0,1,0]
	v_cvt_scalef32_pk_f32_fp4 v[10:11], v87, 1.0 op_sel:[1,1,0]
	v_pk_fma_f32 v[56:57], s[34:35], v[4:5], v[56:57] op_sel_hi:[0,1,1]
	v_pk_fma_f32 v[58:59], s[34:35], v[6:7], v[58:59] op_sel_hi:[0,1,1]
	v_pk_fma_f32 v[50:51], s[34:35], v[8:9], v[50:51] op_sel_hi:[0,1,1]
	v_pk_fma_f32 v[48:49], s[34:35], v[10:11], v[48:49] op_sel_hi:[0,1,1]
	v_readlane_b32 s30, v12, 19
	s_add_u32 s26, s14, s30
	s_addc_u32 s27, s15, 0
	global_load_dwordx2 v[86:87], v213, s[26:27]
	s_waitcnt vmcnt(12)
	v_readlane_b32 s32, v14, 4
	v_cvt_scalef32_pk_f32_fp4 v[4:5], v88, 1.0
	v_cvt_scalef32_pk_f32_fp4 v[6:7], v88, 1.0 op_sel:[1,0,0]
	v_cvt_scalef32_pk_f32_fp4 v[8:9], v88, 1.0 op_sel:[0,1,0]
	v_cvt_scalef32_pk_f32_fp4 v[10:11], v88, 1.0 op_sel:[1,1,0]
	v_pk_fma_f32 v[62:63], s[32:33], v[4:5], v[62:63] op_sel_hi:[0,1,1]
	v_pk_fma_f32 v[60:61], s[32:33], v[6:7], v[60:61] op_sel_hi:[0,1,1]
	v_pk_fma_f32 v[52:53], s[32:33], v[8:9], v[52:53] op_sel_hi:[0,1,1]
	v_pk_fma_f32 v[54:55], s[32:33], v[10:11], v[54:55] op_sel_hi:[0,1,1]
	v_cvt_scalef32_pk_f32_fp4 v[4:5], v89, 1.0
	v_cvt_scalef32_pk_f32_fp4 v[6:7], v89, 1.0 op_sel:[1,0,0]
	v_cvt_scalef32_pk_f32_fp4 v[8:9], v89, 1.0 op_sel:[0,1,0]
	v_cvt_scalef32_pk_f32_fp4 v[10:11], v89, 1.0 op_sel:[1,1,0]
	v_pk_fma_f32 v[56:57], s[32:33], v[4:5], v[56:57] op_sel_hi:[0,1,1]
	v_pk_fma_f32 v[58:59], s[32:33], v[6:7], v[58:59] op_sel_hi:[0,1,1]
	v_pk_fma_f32 v[50:51], s[32:33], v[8:9], v[50:51] op_sel_hi:[0,1,1]
	v_pk_fma_f32 v[48:49], s[32:33], v[10:11], v[48:49] op_sel_hi:[0,1,1]
	v_readlane_b32 s22, v12, 20
	s_add_u32 s16, s14, s22
	s_addc_u32 s17, s15, 0
	global_load_dwordx2 v[88:89], v213, s[16:17]
	v_readlane_b32 s34, v14, 5
	v_cvt_scalef32_pk_f32_fp4 v[4:5], v90, 1.0
	v_cvt_scalef32_pk_f32_fp4 v[6:7], v90, 1.0 op_sel:[1,0,0]
	v_cvt_scalef32_pk_f32_fp4 v[8:9], v90, 1.0 op_sel:[0,1,0]
	v_cvt_scalef32_pk_f32_fp4 v[10:11], v90, 1.0 op_sel:[1,1,0]
	v_pk_fma_f32 v[62:63], s[34:35], v[4:5], v[62:63] op_sel_hi:[0,1,1]
	v_pk_fma_f32 v[60:61], s[34:35], v[6:7], v[60:61] op_sel_hi:[0,1,1]
	v_pk_fma_f32 v[52:53], s[34:35], v[8:9], v[52:53] op_sel_hi:[0,1,1]
	v_pk_fma_f32 v[54:55], s[34:35], v[10:11], v[54:55] op_sel_hi:[0,1,1]
	v_cvt_scalef32_pk_f32_fp4 v[4:5], v91, 1.0
	v_cvt_scalef32_pk_f32_fp4 v[6:7], v91, 1.0 op_sel:[1,0,0]
	v_cvt_scalef32_pk_f32_fp4 v[8:9], v91, 1.0 op_sel:[0,1,0]
	v_cvt_scalef32_pk_f32_fp4 v[10:11], v91, 1.0 op_sel:[1,1,0]
	v_pk_fma_f32 v[56:57], s[34:35], v[4:5], v[56:57] op_sel_hi:[0,1,1]
	v_pk_fma_f32 v[58:59], s[34:35], v[6:7], v[58:59] op_sel_hi:[0,1,1]
	v_pk_fma_f32 v[50:51], s[34:35], v[8:9], v[50:51] op_sel_hi:[0,1,1]
	v_pk_fma_f32 v[48:49], s[34:35], v[10:11], v[48:49] op_sel_hi:[0,1,1]
	v_readlane_b32 s28, v12, 21
	s_add_u32 s20, s14, s28
	s_addc_u32 s21, s15, 0
	global_load_dwordx2 v[90:91], v213, s[20:21]
	v_readlane_b32 s32, v14, 6
	v_cvt_scalef32_pk_f32_fp4 v[4:5], v92, 1.0
	v_cvt_scalef32_pk_f32_fp4 v[6:7], v92, 1.0 op_sel:[1,0,0]
	v_cvt_scalef32_pk_f32_fp4 v[8:9], v92, 1.0 op_sel:[0,1,0]
	v_cvt_scalef32_pk_f32_fp4 v[10:11], v92, 1.0 op_sel:[1,1,0]
	v_pk_fma_f32 v[62:63], s[32:33], v[4:5], v[62:63] op_sel_hi:[0,1,1]
	v_pk_fma_f32 v[60:61], s[32:33], v[6:7], v[60:61] op_sel_hi:[0,1,1]
	v_pk_fma_f32 v[52:53], s[32:33], v[8:9], v[52:53] op_sel_hi:[0,1,1]
	v_pk_fma_f32 v[54:55], s[32:33], v[10:11], v[54:55] op_sel_hi:[0,1,1]
	v_cvt_scalef32_pk_f32_fp4 v[4:5], v93, 1.0
	v_cvt_scalef32_pk_f32_fp4 v[6:7], v93, 1.0 op_sel:[1,0,0]
	v_cvt_scalef32_pk_f32_fp4 v[8:9], v93, 1.0 op_sel:[0,1,0]
	v_cvt_scalef32_pk_f32_fp4 v[10:11], v93, 1.0 op_sel:[1,1,0]
	v_pk_fma_f32 v[56:57], s[32:33], v[4:5], v[56:57] op_sel_hi:[0,1,1]
; __device__ void peer_v(const P& p, int layer, int tok, bool dry) {
;     ...
;     for (int jb = 0; jb < 64; jb += 16) {
;       u32x2 vv[16];
; #pragma unroll
;       for (int q = 0; q < 16; ++q) {
;         const int e = __builtin_amdgcn_readlane(eidx[h2], jb + q);
;         vv[q] = ((const u32x2*)(V4 + (size_t)e * 512))[lane];
;       }
; #pragma unroll
;       for (int q = 0; q < 16; ++q) {
;         const float wq = rdlane_f(wreg[h2], jb + q);
;         const f32x2 w2 = {wq, wq};
; #pragma unroll
;         for (int k = 0; k < 2; ++k) {
;           oa2[4 * k + 0] += w2 * __builtin_amdgcn_cvt_scalef32_pk_f32_fp4(vv[q][k], 1.0f, 0);
;           oa2[4 * k + 1] += w2 * __builtin_amdgcn_cvt_scalef32_pk_f32_fp4(vv[q][k], 1.0f, 1);
;           oa2[4 * k + 2] += w2 * __builtin_amdgcn_cvt_scalef32_pk_f32_fp4(vv[q][k], 1.0f, 2);
;           oa2[4 * k + 3] += w2 * __builtin_amdgcn_cvt_scalef32_pk_f32_fp4(vv[q][k], 1.0f, 3);
;         }
;       }
	v_pk_fma_f32 v[58:59], s[32:33], v[6:7], v[58:59] op_sel_hi:[0,1,1]
	v_pk_fma_f32 v[50:51], s[32:33], v[8:9], v[50:51] op_sel_hi:[0,1,1]
	v_pk_fma_f32 v[48:49], s[32:33], v[10:11], v[48:49] op_sel_hi:[0,1,1]
	v_readlane_b32 s29, v12, 22
	s_add_u32 s24, s14, s29
	s_addc_u32 s25, s15, 0
	global_load_dwordx2 v[92:93], v213, s[24:25]
	v_readlane_b32 s34, v14, 7
	v_cvt_scalef32_pk_f32_fp4 v[4:5], v94, 1.0
	v_cvt_scalef32_pk_f32_fp4 v[6:7], v94, 1.0 op_sel:[1,0,0]
	v_cvt_scalef32_pk_f32_fp4 v[8:9], v94, 1.0 op_sel:[0,1,0]
	v_cvt_scalef32_pk_f32_fp4 v[10:11], v94, 1.0 op_sel:[1,1,0]
	v_pk_fma_f32 v[62:63], s[34:35], v[4:5], v[62:63] op_sel_hi:[0,1,1]
	v_pk_fma_f32 v[60:61], s[34:35], v[6:7], v[60:61] op_sel_hi:[0,1,1]
	v_pk_fma_f32 v[52:53], s[34:35], v[8:9], v[52:53] op_sel_hi:[0,1,1]
	v_pk_fma_f32 v[54:55], s[34:35], v[10:11], v[54:55] op_sel_hi:[0,1,1]
	v_cvt_scalef32_pk_f32_fp4 v[4:5], v95, 1.0
	v_cvt_scalef32_pk_f32_fp4 v[6:7], v95, 1.0 op_sel:[1,0,0]
	v_cvt_scalef32_pk_f32_fp4 v[8:9], v95, 1.0 op_sel:[0,1,0]
	v_cvt_scalef32_pk_f32_fp4 v[10:11], v95, 1.0 op_sel:[1,1,0]
	v_pk_fma_f32 v[56:57], s[34:35], v[4:5], v[56:57] op_sel_hi:[0,1,1]
	v_pk_fma_f32 v[58:59], s[34:35], v[6:7], v[58:59] op_sel_hi:[0,1,1]
	v_pk_fma_f32 v[50:51], s[34:35], v[8:9], v[50:51] op_sel_hi:[0,1,1]
	v_pk_fma_f32 v[48:49], s[34:35], v[10:11], v[48:49] op_sel_hi:[0,1,1]
	v_readlane_b32 s30, v12, 23
	s_add_u32 s26, s14, s30
	s_addc_u32 s27, s15, 0
	global_load_dwordx2 v[94:95], v213, s[26:27]
	s_waitcnt vmcnt(12)
	v_readlane_b32 s32, v14, 8
	v_cvt_scalef32_pk_f32_fp4 v[4:5], v96, 1.0
	v_cvt_scalef32_pk_f32_fp4 v[6:7], v96, 1.0 op_sel:[1,0,0]
	v_cvt_scalef32_pk_f32_fp4 v[8:9], v96, 1.0 op_sel:[0,1,0]
	v_cvt_scalef32_pk_f32_fp4 v[10:11], v96, 1.0 op_sel:[1,1,0]
	v_pk_fma_f32 v[62:63], s[32:33], v[4:5], v[62:63] op_sel_hi:[0,1,1]
	v_pk_fma_f32 v[60:61], s[32:33], v[6:7], v[60:61] op_sel_hi:[0,1,1]
	v_pk_fma_f32 v[52:53], s[32:33], v[8:9], v[52:53] op_sel_hi:[0,1,1]
	v_pk_fma_f32 v[54:55], s[32:33], v[10:11], v[54:55] op_sel_hi:[0,1,1]
	v_cvt_scalef32_pk_f32_fp4 v[4:5], v97, 1.0
	v_cvt_scalef32_pk_f32_fp4 v[6:7], v97, 1.0 op_sel:[1,0,0]
	v_cvt_scalef32_pk_f32_fp4 v[8:9], v97, 1.0 op_sel:[0,1,0]
	v_cvt_scalef32_pk_f32_fp4 v[10:11], v97, 1.0 op_sel:[1,1,0]
	v_pk_fma_f32 v[56:57], s[32:33], v[4:5], v[56:57] op_sel_hi:[0,1,1]
	v_pk_fma_f32 v[58:59], s[32:33], v[6:7], v[58:59] op_sel_hi:[0,1,1]
	v_pk_fma_f32 v[50:51], s[32:33], v[8:9], v[50:51] op_sel_hi:[0,1,1]
	v_pk_fma_f32 v[48:49], s[32:33], v[10:11], v[48:49] op_sel_hi:[0,1,1]
	v_readlane_b32 s22, v12, 24
	s_add_u32 s16, s14, s22
	s_addc_u32 s17, s15, 0
	global_load_dwordx2 v[96:97], v213, s[16:17]
	v_readlane_b32 s34, v14, 9
	v_cvt_scalef32_pk_f32_fp4 v[4:5], v98, 1.0
	v_cvt_scalef32_pk_f32_fp4 v[6:7], v98, 1.0 op_sel:[1,0,0]
	v_cvt_scalef32_pk_f32_fp4 v[8:9], v98, 1.0 op_sel:[0,1,0]
	v_cvt_scalef32_pk_f32_fp4 v[10:11], v98, 1.0 op_sel:[1,1,0]
	v_pk_fma_f32 v[62:63], s[34:35], v[4:5], v[62:63] op_sel_hi:[0,1,1]
	v_pk_fma_f32 v[60:61], s[34:35], v[6:7], v[60:61] op_sel_hi:[0,1,1]
	v_pk_fma_f32 v[52:53], s[34:35], v[8:9], v[52:53] op_sel_hi:[0,1,1]
	v_pk_fma_f32 v[54:55], s[34:35], v[10:11], v[54:55] op_sel_hi:[0,1,1]
	v_cvt_scalef32_pk_f32_fp4 v[4:5], v99, 1.0
	v_cvt_scalef32_pk_f32_fp4 v[6:7], v99, 1.0 op_sel:[1,0,0]
	v_cvt_scalef32_pk_f32_fp4 v[8:9], v99, 1.0 op_sel:[0,1,0]
	v_cvt_scalef32_pk_f32_fp4 v[10:11], v99, 1.0 op_sel:[1,1,0]
	v_pk_fma_f32 v[56:57], s[34:35], v[4:5], v[56:57] op_sel_hi:[0,1,1]
	v_pk_fma_f32 v[58:59], s[34:35], v[6:7], v[58:59] op_sel_hi:[0,1,1]
	v_pk_fma_f32 v[50:51], s[34:35], v[8:9], v[50:51] op_sel_hi:[0,1,1]
	v_pk_fma_f32 v[48:49], s[34:35], v[10:11], v[48:49] op_sel_hi:[0,1,1]
	v_readlane_b32 s28, v12, 25
	s_add_u32 s20, s14, s28
	s_addc_u32 s21, s15, 0
	global_load_dwordx2 v[98:99], v213, s[20:21]
	v_readlane_b32 s32, v14, 10
	v_cvt_scalef32_pk_f32_fp4 v[4:5], v100, 1.0
	v_cvt_scalef32_pk_f32_fp4 v[6:7], v100, 1.0 op_sel:[1,0,0]
	v_cvt_scalef32_pk_f32_fp4 v[8:9], v100, 1.0 op_sel:[0,1,0]
	v_cvt_scalef32_pk_f32_fp4 v[10:11], v100, 1.0 op_sel:[1,1,0]
	v_pk_fma_f32 v[62:63], s[32:33], v[4:5], v[62:63] op_sel_hi:[0,1,1]
	v_pk_fma_f32 v[60:61], s[32:33], v[6:7], v[60:61] op_sel_hi:[0,1,1]
	v_pk_fma_f32 v[52:53], s[32:33], v[8:9], v[52:53] op_sel_hi:[0,1,1]
	v_pk_fma_f32 v[54:55], s[32:33], v[10:11], v[54:55] op_sel_hi:[0,1,1]
	v_cvt_scalef32_pk_f32_fp4 v[4:5], v101, 1.0
	v_cvt_scalef32_pk_f32_fp4 v[6:7], v101, 1.0 op_sel:[1,0,0]
	v_cvt_scalef32_pk_f32_fp4 v[8:9], v101, 1.0 op_sel:[0,1,0]
	v_cvt_scalef32_pk_f32_fp4 v[10:11], v101, 1.0 op_sel:[1,1,0]
	v_pk_fma_f32 v[56:57], s[32:33], v[4:5], v[56:57] op_sel_hi:[0,1,1]
	v_pk_fma_f32 v[58:59], s[32:33], v[6:7], v[58:59] op_sel_hi:[0,1,1]
	v_pk_fma_f32 v[50:51], s[32:33], v[8:9], v[50:51] op_sel_hi:[0,1,1]
	v_pk_fma_f32 v[48:49], s[32:33], v[10:11], v[48:49] op_sel_hi:[0,1,1]
	v_readlane_b32 s29, v12, 26
	s_add_u32 s24, s14, s29
	s_addc_u32 s25, s15, 0
	global_load_dwordx2 v[100:101], v213, s[24:25]
	v_readlane_b32 s34, v14, 11
	v_cvt_scalef32_pk_f32_fp4 v[4:5], v102, 1.0
	v_cvt_scalef32_pk_f32_fp4 v[6:7], v102, 1.0 op_sel:[1,0,0]
	v_cvt_scalef32_pk_f32_fp4 v[8:9], v102, 1.0 op_sel:[0,1,0]
	v_cvt_scalef32_pk_f32_fp4 v[10:11], v102, 1.0 op_sel:[1,1,0]
	v_pk_fma_f32 v[62:63], s[34:35], v[4:5], v[62:63] op_sel_hi:[0,1,1]
	v_pk_fma_f32 v[60:61], s[34:35], v[6:7], v[60:61] op_sel_hi:[0,1,1]
	v_pk_fma_f32 v[52:53], s[34:35], v[8:9], v[52:53] op_sel_hi:[0,1,1]
	v_pk_fma_f32 v[54:55], s[34:35], v[10:11], v[54:55] op_sel_hi:[0,1,1]
	v_cvt_scalef32_pk_f32_fp4 v[4:5], v103, 1.0
	v_cvt_scalef32_pk_f32_fp4 v[6:7], v103, 1.0 op_sel:[1,0,0]
	v_cvt_scalef32_pk_f32_fp4 v[8:9], v103, 1.0 op_sel:[0,1,0]
	v_cvt_scalef32_pk_f32_fp4 v[10:11], v103, 1.0 op_sel:[1,1,0]
	v_pk_fma_f32 v[56:57], s[34:35], v[4:5], v[56:57] op_sel_hi:[0,1,1]
	v_pk_fma_f32 v[58:59], s[34:35], v[6:7], v[58:59] op_sel_hi:[0,1,1]
	v_pk_fma_f32 v[50:51], s[34:35], v[8:9], v[50:51] op_sel_hi:[0,1,1]
	v_pk_fma_f32 v[48:49], s[34:35], v[10:11], v[48:49] op_sel_hi:[0,1,1]
	v_readlane_b32 s30, v12, 27
	s_add_u32 s26, s14, s30
	s_addc_u32 s27, s15, 0
	global_load_dwordx2 v[102:103], v213, s[26:27]
	s_waitcnt vmcnt(12)
; __device__ void peer_v(const P& p, int layer, int tok, bool dry) {
;     ...
;     for (int jb = 0; jb < 64; jb += 16) {
;       u32x2 vv[16];
; #pragma unroll
;       for (int q = 0; q < 16; ++q) {
;         const int e = __builtin_amdgcn_readlane(eidx[h2], jb + q);
;         vv[q] = ((const u32x2*)(V4 + (size_t)e * 512))[lane];
;       }
; #pragma unroll
;       for (int q = 0; q < 16; ++q) {
;         const float wq = rdlane_f(wreg[h2], jb + q);
;         const f32x2 w2 = {wq, wq};
; #pragma unroll
;         for (int k = 0; k < 2; ++k) {
;           oa2[4 * k + 0] += w2 * __builtin_amdgcn_cvt_scalef32_pk_f32_fp4(vv[q][k], 1.0f, 0);
;           oa2[4 * k + 1] += w2 * __builtin_amdgcn_cvt_scalef32_pk_f32_fp4(vv[q][k], 1.0f, 1);
;           oa2[4 * k + 2] += w2 * __builtin_amdgcn_cvt_scalef32_pk_f32_fp4(vv[q][k], 1.0f, 2);
;           oa2[4 * k + 3] += w2 * __builtin_amdgcn_cvt_scalef32_pk_f32_fp4(vv[q][k], 1.0f, 3);
;         }
;       }
	v_readlane_b32 s32, v14, 12
	v_cvt_scalef32_pk_f32_fp4 v[4:5], v104, 1.0
	v_cvt_scalef32_pk_f32_fp4 v[6:7], v104, 1.0 op_sel:[1,0,0]
	v_cvt_scalef32_pk_f32_fp4 v[8:9], v104, 1.0 op_sel:[0,1,0]
	v_cvt_scalef32_pk_f32_fp4 v[10:11], v104, 1.0 op_sel:[1,1,0]
	v_pk_fma_f32 v[62:63], s[32:33], v[4:5], v[62:63] op_sel_hi:[0,1,1]
	v_pk_fma_f32 v[60:61], s[32:33], v[6:7], v[60:61] op_sel_hi:[0,1,1]
	v_pk_fma_f32 v[52:53], s[32:33], v[8:9], v[52:53] op_sel_hi:[0,1,1]
	v_pk_fma_f32 v[54:55], s[32:33], v[10:11], v[54:55] op_sel_hi:[0,1,1]
	v_cvt_scalef32_pk_f32_fp4 v[4:5], v105, 1.0
	v_cvt_scalef32_pk_f32_fp4 v[6:7], v105, 1.0 op_sel:[1,0,0]
	v_cvt_scalef32_pk_f32_fp4 v[8:9], v105, 1.0 op_sel:[0,1,0]
	v_cvt_scalef32_pk_f32_fp4 v[10:11], v105, 1.0 op_sel:[1,1,0]
	v_pk_fma_f32 v[56:57], s[32:33], v[4:5], v[56:57] op_sel_hi:[0,1,1]
	v_pk_fma_f32 v[58:59], s[32:33], v[6:7], v[58:59] op_sel_hi:[0,1,1]
	v_pk_fma_f32 v[50:51], s[32:33], v[8:9], v[50:51] op_sel_hi:[0,1,1]
	v_pk_fma_f32 v[48:49], s[32:33], v[10:11], v[48:49] op_sel_hi:[0,1,1]
	v_readlane_b32 s22, v12, 28
	s_add_u32 s16, s14, s22
	s_addc_u32 s17, s15, 0
	global_load_dwordx2 v[104:105], v213, s[16:17]
	v_readlane_b32 s34, v14, 13
	v_cvt_scalef32_pk_f32_fp4 v[4:5], v106, 1.0
	v_cvt_scalef32_pk_f32_fp4 v[6:7], v106, 1.0 op_sel:[1,0,0]
	v_cvt_scalef32_pk_f32_fp4 v[8:9], v106, 1.0 op_sel:[0,1,0]
	v_cvt_scalef32_pk_f32_fp4 v[10:11], v106, 1.0 op_sel:[1,1,0]
	v_pk_fma_f32 v[62:63], s[34:35], v[4:5], v[62:63] op_sel_hi:[0,1,1]
	v_pk_fma_f32 v[60:61], s[34:35], v[6:7], v[60:61] op_sel_hi:[0,1,1]
	v_pk_fma_f32 v[52:53], s[34:35], v[8:9], v[52:53] op_sel_hi:[0,1,1]
	v_pk_fma_f32 v[54:55], s[34:35], v[10:11], v[54:55] op_sel_hi:[0,1,1]
	v_cvt_scalef32_pk_f32_fp4 v[4:5], v107, 1.0
	v_cvt_scalef32_pk_f32_fp4 v[6:7], v107, 1.0 op_sel:[1,0,0]
	v_cvt_scalef32_pk_f32_fp4 v[8:9], v107, 1.0 op_sel:[0,1,0]
	v_cvt_scalef32_pk_f32_fp4 v[10:11], v107, 1.0 op_sel:[1,1,0]
	v_pk_fma_f32 v[56:57], s[34:35], v[4:5], v[56:57] op_sel_hi:[0,1,1]
	v_pk_fma_f32 v[58:59], s[34:35], v[6:7], v[58:59] op_sel_hi:[0,1,1]
	v_pk_fma_f32 v[50:51], s[34:35], v[8:9], v[50:51] op_sel_hi:[0,1,1]
	v_pk_fma_f32 v[48:49], s[34:35], v[10:11], v[48:49] op_sel_hi:[0,1,1]
	v_readlane_b32 s28, v12, 29
	s_add_u32 s20, s14, s28
	s_addc_u32 s21, s15, 0
	global_load_dwordx2 v[106:107], v213, s[20:21]
	v_readlane_b32 s32, v14, 14
	v_cvt_scalef32_pk_f32_fp4 v[4:5], v108, 1.0
	v_cvt_scalef32_pk_f32_fp4 v[6:7], v108, 1.0 op_sel:[1,0,0]
	v_cvt_scalef32_pk_f32_fp4 v[8:9], v108, 1.0 op_sel:[0,1,0]
	v_cvt_scalef32_pk_f32_fp4 v[10:11], v108, 1.0 op_sel:[1,1,0]
	v_pk_fma_f32 v[62:63], s[32:33], v[4:5], v[62:63] op_sel_hi:[0,1,1]
	v_pk_fma_f32 v[60:61], s[32:33], v[6:7], v[60:61] op_sel_hi:[0,1,1]
	v_pk_fma_f32 v[52:53], s[32:33], v[8:9], v[52:53] op_sel_hi:[0,1,1]
	v_pk_fma_f32 v[54:55], s[32:33], v[10:11], v[54:55] op_sel_hi:[0,1,1]
	v_cvt_scalef32_pk_f32_fp4 v[4:5], v109, 1.0
	v_cvt_scalef32_pk_f32_fp4 v[6:7], v109, 1.0 op_sel:[1,0,0]
	v_cvt_scalef32_pk_f32_fp4 v[8:9], v109, 1.0 op_sel:[0,1,0]
	v_cvt_scalef32_pk_f32_fp4 v[10:11], v109, 1.0 op_sel:[1,1,0]
	v_pk_fma_f32 v[56:57], s[32:33], v[4:5], v[56:57] op_sel_hi:[0,1,1]
	v_pk_fma_f32 v[58:59], s[32:33], v[6:7], v[58:59] op_sel_hi:[0,1,1]
	v_pk_fma_f32 v[50:51], s[32:33], v[8:9], v[50:51] op_sel_hi:[0,1,1]
	v_pk_fma_f32 v[48:49], s[32:33], v[10:11], v[48:49] op_sel_hi:[0,1,1]
	v_readlane_b32 s29, v12, 30
	s_add_u32 s24, s14, s29
	s_addc_u32 s25, s15, 0
	global_load_dwordx2 v[108:109], v213, s[24:25]
	v_readlane_b32 s34, v14, 15
	v_cvt_scalef32_pk_f32_fp4 v[4:5], v110, 1.0
	v_cvt_scalef32_pk_f32_fp4 v[6:7], v110, 1.0 op_sel:[1,0,0]
	v_cvt_scalef32_pk_f32_fp4 v[8:9], v110, 1.0 op_sel:[0,1,0]
	v_cvt_scalef32_pk_f32_fp4 v[10:11], v110, 1.0 op_sel:[1,1,0]
	v_pk_fma_f32 v[62:63], s[34:35], v[4:5], v[62:63] op_sel_hi:[0,1,1]
	v_pk_fma_f32 v[60:61], s[34:35], v[6:7], v[60:61] op_sel_hi:[0,1,1]
	v_pk_fma_f32 v[52:53], s[34:35], v[8:9], v[52:53] op_sel_hi:[0,1,1]
	v_pk_fma_f32 v[54:55], s[34:35], v[10:11], v[54:55] op_sel_hi:[0,1,1]
	v_cvt_scalef32_pk_f32_fp4 v[4:5], v111, 1.0
	v_cvt_scalef32_pk_f32_fp4 v[6:7], v111, 1.0 op_sel:[1,0,0]
	v_cvt_scalef32_pk_f32_fp4 v[8:9], v111, 1.0 op_sel:[0,1,0]
	v_cvt_scalef32_pk_f32_fp4 v[10:11], v111, 1.0 op_sel:[1,1,0]
	v_pk_fma_f32 v[56:57], s[34:35], v[4:5], v[56:57] op_sel_hi:[0,1,1]
	v_pk_fma_f32 v[58:59], s[34:35], v[6:7], v[58:59] op_sel_hi:[0,1,1]
	v_pk_fma_f32 v[50:51], s[34:35], v[8:9], v[50:51] op_sel_hi:[0,1,1]
	v_pk_fma_f32 v[48:49], s[34:35], v[10:11], v[48:49] op_sel_hi:[0,1,1]
	v_readlane_b32 s30, v12, 31
	s_add_u32 s26, s14, s30
	s_addc_u32 s27, s15, 0
	global_load_dwordx2 v[110:111], v213, s[26:27]
	s_waitcnt vmcnt(12)
; __device__ void peer_v(const P& p, int layer, int tok, bool dry) {
;     ...
;     for (int jb = 0; jb < 64; jb += 16) {
;       u32x2 vv[16];
; #pragma unroll
;       for (int q = 0; q < 16; ++q) {
;         const int e = __builtin_amdgcn_readlane(eidx[h2], jb + q);
;         vv[q] = ((const u32x2*)(V4 + (size_t)e * 512))[lane];
;       }
; #pragma unroll
;       for (int q = 0; q < 16; ++q) {
;         const float wq = rdlane_f(wreg[h2], jb + q);
;         const f32x2 w2 = {wq, wq};
; #pragma unroll
;         for (int k = 0; k < 2; ++k) {
;           oa2[4 * k + 0] += w2 * __builtin_amdgcn_cvt_scalef32_pk_f32_fp4(vv[q][k], 1.0f, 0);
;           oa2[4 * k + 1] += w2 * __builtin_amdgcn_cvt_scalef32_pk_f32_fp4(vv[q][k], 1.0f, 1);
;           oa2[4 * k + 2] += w2 * __builtin_amdgcn_cvt_scalef32_pk_f32_fp4(vv[q][k], 1.0f, 2);
;           oa2[4 * k + 3] += w2 * __builtin_amdgcn_cvt_scalef32_pk_f32_fp4(vv[q][k], 1.0f, 3);
;         }
;       }
	v_readlane_b32 s32, v14, 16
	v_cvt_scalef32_pk_f32_fp4 v[4:5], v80, 1.0
	v_cvt_scalef32_pk_f32_fp4 v[6:7], v80, 1.0 op_sel:[1,0,0]
	v_cvt_scalef32_pk_f32_fp4 v[8:9], v80, 1.0 op_sel:[0,1,0]
	v_cvt_scalef32_pk_f32_fp4 v[10:11], v80, 1.0 op_sel:[1,1,0]
	v_pk_fma_f32 v[62:63], s[32:33], v[4:5], v[62:63] op_sel_hi:[0,1,1]
	v_pk_fma_f32 v[60:61], s[32:33], v[6:7], v[60:61] op_sel_hi:[0,1,1]
	v_pk_fma_f32 v[52:53], s[32:33], v[8:9], v[52:53] op_sel_hi:[0,1,1]
	v_pk_fma_f32 v[54:55], s[32:33], v[10:11], v[54:55] op_sel_hi:[0,1,1]
	v_cvt_scalef32_pk_f32_fp4 v[4:5], v81, 1.0
	v_cvt_scalef32_pk_f32_fp4 v[6:7], v81, 1.0 op_sel:[1,0,0]
	v_cvt_scalef32_pk_f32_fp4 v[8:9], v81, 1.0 op_sel:[0,1,0]
	v_cvt_scalef32_pk_f32_fp4 v[10:11], v81, 1.0 op_sel:[1,1,0]
	v_pk_fma_f32 v[56:57], s[32:33], v[4:5], v[56:57] op_sel_hi:[0,1,1]
	v_pk_fma_f32 v[58:59], s[32:33], v[6:7], v[58:59] op_sel_hi:[0,1,1]
	v_pk_fma_f32 v[50:51], s[32:33], v[8:9], v[50:51] op_sel_hi:[0,1,1]
	v_pk_fma_f32 v[48:49], s[32:33], v[10:11], v[48:49] op_sel_hi:[0,1,1]
	v_readlane_b32 s22, v12, 32
	s_add_u32 s16, s14, s22
	s_addc_u32 s17, s15, 0
	global_load_dwordx2 v[80:81], v213, s[16:17]
	v_readlane_b32 s34, v14, 17
	v_cvt_scalef32_pk_f32_fp4 v[4:5], v82, 1.0
	v_cvt_scalef32_pk_f32_fp4 v[6:7], v82, 1.0 op_sel:[1,0,0]
	v_cvt_scalef32_pk_f32_fp4 v[8:9], v82, 1.0 op_sel:[0,1,0]
	v_cvt_scalef32_pk_f32_fp4 v[10:11], v82, 1.0 op_sel:[1,1,0]
	v_pk_fma_f32 v[62:63], s[34:35], v[4:5], v[62:63] op_sel_hi:[0,1,1]
	v_pk_fma_f32 v[60:61], s[34:35], v[6:7], v[60:61] op_sel_hi:[0,1,1]
	v_pk_fma_f32 v[52:53], s[34:35], v[8:9], v[52:53] op_sel_hi:[0,1,1]
	v_pk_fma_f32 v[54:55], s[34:35], v[10:11], v[54:55] op_sel_hi:[0,1,1]
	v_cvt_scalef32_pk_f32_fp4 v[4:5], v83, 1.0
	v_cvt_scalef32_pk_f32_fp4 v[6:7], v83, 1.0 op_sel:[1,0,0]
	v_cvt_scalef32_pk_f32_fp4 v[8:9], v83, 1.0 op_sel:[0,1,0]
	v_cvt_scalef32_pk_f32_fp4 v[10:11], v83, 1.0 op_sel:[1,1,0]
	v_pk_fma_f32 v[56:57], s[34:35], v[4:5], v[56:57] op_sel_hi:[0,1,1]
	v_pk_fma_f32 v[58:59], s[34:35], v[6:7], v[58:59] op_sel_hi:[0,1,1]
	v_pk_fma_f32 v[50:51], s[34:35], v[8:9], v[50:51] op_sel_hi:[0,1,1]
	v_pk_fma_f32 v[48:49], s[34:35], v[10:11], v[48:49] op_sel_hi:[0,1,1]
	v_readlane_b32 s28, v12, 33
	s_add_u32 s20, s14, s28
	s_addc_u32 s21, s15, 0
	global_load_dwordx2 v[82:83], v213, s[20:21]
	v_readlane_b32 s32, v14, 18
	v_cvt_scalef32_pk_f32_fp4 v[4:5], v84, 1.0
	v_cvt_scalef32_pk_f32_fp4 v[6:7], v84, 1.0 op_sel:[1,0,0]
	v_cvt_scalef32_pk_f32_fp4 v[8:9], v84, 1.0 op_sel:[0,1,0]
	v_cvt_scalef32_pk_f32_fp4 v[10:11], v84, 1.0 op_sel:[1,1,0]
	v_pk_fma_f32 v[62:63], s[32:33], v[4:5], v[62:63] op_sel_hi:[0,1,1]
	v_pk_fma_f32 v[60:61], s[32:33], v[6:7], v[60:61] op_sel_hi:[0,1,1]
	v_pk_fma_f32 v[52:53], s[32:33], v[8:9], v[52:53] op_sel_hi:[0,1,1]
	v_pk_fma_f32 v[54:55], s[32:33], v[10:11], v[54:55] op_sel_hi:[0,1,1]
	v_cvt_scalef32_pk_f32_fp4 v[4:5], v85, 1.0
	v_cvt_scalef32_pk_f32_fp4 v[6:7], v85, 1.0 op_sel:[1,0,0]
	v_cvt_scalef32_pk_f32_fp4 v[8:9], v85, 1.0 op_sel:[0,1,0]
	v_cvt_scalef32_pk_f32_fp4 v[10:11], v85, 1.0 op_sel:[1,1,0]
	v_pk_fma_f32 v[56:57], s[32:33], v[4:5], v[56:57] op_sel_hi:[0,1,1]
	v_pk_fma_f32 v[58:59], s[32:33], v[6:7], v[58:59] op_sel_hi:[0,1,1]
	v_pk_fma_f32 v[50:51], s[32:33], v[8:9], v[50:51] op_sel_hi:[0,1,1]
	v_pk_fma_f32 v[48:49], s[32:33], v[10:11], v[48:49] op_sel_hi:[0,1,1]
	v_readlane_b32 s29, v12, 34
	s_add_u32 s24, s14, s29
	s_addc_u32 s25, s15, 0
	global_load_dwordx2 v[84:85], v213, s[24:25]
	v_readlane_b32 s34, v14, 19
	v_cvt_scalef32_pk_f32_fp4 v[4:5], v86, 1.0
	v_cvt_scalef32_pk_f32_fp4 v[6:7], v86, 1.0 op_sel:[1,0,0]
	v_cvt_scalef32_pk_f32_fp4 v[8:9], v86, 1.0 op_sel:[0,1,0]
	v_cvt_scalef32_pk_f32_fp4 v[10:11], v86, 1.0 op_sel:[1,1,0]
	v_pk_fma_f32 v[62:63], s[34:35], v[4:5], v[62:63] op_sel_hi:[0,1,1]
	v_pk_fma_f32 v[60:61], s[34:35], v[6:7], v[60:61] op_sel_hi:[0,1,1]
	v_pk_fma_f32 v[52:53], s[34:35], v[8:9], v[52:53] op_sel_hi:[0,1,1]
	v_pk_fma_f32 v[54:55], s[34:35], v[10:11], v[54:55] op_sel_hi:[0,1,1]
	v_cvt_scalef32_pk_f32_fp4 v[4:5], v87, 1.0
	v_cvt_scalef32_pk_f32_fp4 v[6:7], v87, 1.0 op_sel:[1,0,0]
	v_cvt_scalef32_pk_f32_fp4 v[8:9], v87, 1.0 op_sel:[0,1,0]
	v_cvt_scalef32_pk_f32_fp4 v[10:11], v87, 1.0 op_sel:[1,1,0]
	v_pk_fma_f32 v[56:57], s[34:35], v[4:5], v[56:57] op_sel_hi:[0,1,1]
	v_pk_fma_f32 v[58:59], s[34:35], v[6:7], v[58:59] op_sel_hi:[0,1,1]
	v_pk_fma_f32 v[50:51], s[34:35], v[8:9], v[50:51] op_sel_hi:[0,1,1]
	v_pk_fma_f32 v[48:49], s[34:35], v[10:11], v[48:49] op_sel_hi:[0,1,1]
	v_readlane_b32 s30, v12, 35
	s_add_u32 s26, s14, s30
	s_addc_u32 s27, s15, 0
	global_load_dwordx2 v[86:87], v213, s[26:27]
	s_waitcnt vmcnt(12)
; __device__ void peer_v(const P& p, int layer, int tok, bool dry) {
;     ...
;     for (int jb = 0; jb < 64; jb += 16) {
;       u32x2 vv[16];
; #pragma unroll
;       for (int q = 0; q < 16; ++q) {
;         const int e = __builtin_amdgcn_readlane(eidx[h2], jb + q);
;         vv[q] = ((const u32x2*)(V4 + (size_t)e * 512))[lane];
;       }
; #pragma unroll
;       for (int q = 0; q < 16; ++q) {
;         const float wq = rdlane_f(wreg[h2], jb + q);
;         const f32x2 w2 = {wq, wq};
; #pragma unroll
;         for (int k = 0; k < 2; ++k) {
;           oa2[4 * k + 0] += w2 * __builtin_amdgcn_cvt_scalef32_pk_f32_fp4(vv[q][k], 1.0f, 0);
;           oa2[4 * k + 1] += w2 * __builtin_amdgcn_cvt_scalef32_pk_f32_fp4(vv[q][k], 1.0f, 1);
;           oa2[4 * k + 2] += w2 * __builtin_amdgcn_cvt_scalef32_pk_f32_fp4(vv[q][k], 1.0f, 2);
;           oa2[4 * k + 3] += w2 * __builtin_amdgcn_cvt_scalef32_pk_f32_fp4(vv[q][k], 1.0f, 3);
;         }
;       }
	v_readlane_b32 s32, v14, 20
	v_cvt_scalef32_pk_f32_fp4 v[4:5], v88, 1.0
	v_cvt_scalef32_pk_f32_fp4 v[6:7], v88, 1.0 op_sel:[1,0,0]
	v_cvt_scalef32_pk_f32_fp4 v[8:9], v88, 1.0 op_sel:[0,1,0]
	v_cvt_scalef32_pk_f32_fp4 v[10:11], v88, 1.0 op_sel:[1,1,0]
	v_pk_fma_f32 v[62:63], s[32:33], v[4:5], v[62:63] op_sel_hi:[0,1,1]
	v_pk_fma_f32 v[60:61], s[32:33], v[6:7], v[60:61] op_sel_hi:[0,1,1]
	v_pk_fma_f32 v[52:53], s[32:33], v[8:9], v[52:53] op_sel_hi:[0,1,1]
	v_pk_fma_f32 v[54:55], s[32:33], v[10:11], v[54:55] op_sel_hi:[0,1,1]
	v_cvt_scalef32_pk_f32_fp4 v[4:5], v89, 1.0
	v_cvt_scalef32_pk_f32_fp4 v[6:7], v89, 1.0 op_sel:[1,0,0]
	v_cvt_scalef32_pk_f32_fp4 v[8:9], v89, 1.0 op_sel:[0,1,0]
	v_cvt_scalef32_pk_f32_fp4 v[10:11], v89, 1.0 op_sel:[1,1,0]
	v_pk_fma_f32 v[56:57], s[32:33], v[4:5], v[56:57] op_sel_hi:[0,1,1]
	v_pk_fma_f32 v[58:59], s[32:33], v[6:7], v[58:59] op_sel_hi:[0,1,1]
	v_pk_fma_f32 v[50:51], s[32:33], v[8:9], v[50:51] op_sel_hi:[0,1,1]
	v_pk_fma_f32 v[48:49], s[32:33], v[10:11], v[48:49] op_sel_hi:[0,1,1]
	v_readlane_b32 s22, v12, 36
	s_add_u32 s16, s14, s22
	s_addc_u32 s17, s15, 0
	global_load_dwordx2 v[88:89], v213, s[16:17]
	v_readlane_b32 s34, v14, 21
	v_cvt_scalef32_pk_f32_fp4 v[4:5], v90, 1.0
	v_cvt_scalef32_pk_f32_fp4 v[6:7], v90, 1.0 op_sel:[1,0,0]
	v_cvt_scalef32_pk_f32_fp4 v[8:9], v90, 1.0 op_sel:[0,1,0]
	v_cvt_scalef32_pk_f32_fp4 v[10:11], v90, 1.0 op_sel:[1,1,0]
	v_pk_fma_f32 v[62:63], s[34:35], v[4:5], v[62:63] op_sel_hi:[0,1,1]
	v_pk_fma_f32 v[60:61], s[34:35], v[6:7], v[60:61] op_sel_hi:[0,1,1]
	v_pk_fma_f32 v[52:53], s[34:35], v[8:9], v[52:53] op_sel_hi:[0,1,1]
	v_pk_fma_f32 v[54:55], s[34:35], v[10:11], v[54:55] op_sel_hi:[0,1,1]
	v_cvt_scalef32_pk_f32_fp4 v[4:5], v91, 1.0
	v_cvt_scalef32_pk_f32_fp4 v[6:7], v91, 1.0 op_sel:[1,0,0]
	v_cvt_scalef32_pk_f32_fp4 v[8:9], v91, 1.0 op_sel:[0,1,0]
	v_cvt_scalef32_pk_f32_fp4 v[10:11], v91, 1.0 op_sel:[1,1,0]
	v_pk_fma_f32 v[56:57], s[34:35], v[4:5], v[56:57] op_sel_hi:[0,1,1]
	v_pk_fma_f32 v[58:59], s[34:35], v[6:7], v[58:59] op_sel_hi:[0,1,1]
	v_pk_fma_f32 v[50:51], s[34:35], v[8:9], v[50:51] op_sel_hi:[0,1,1]
	v_pk_fma_f32 v[48:49], s[34:35], v[10:11], v[48:49] op_sel_hi:[0,1,1]
	v_readlane_b32 s28, v12, 37
	s_add_u32 s20, s14, s28
	s_addc_u32 s21, s15, 0
	global_load_dwordx2 v[90:91], v213, s[20:21]
	v_readlane_b32 s32, v14, 22
	v_cvt_scalef32_pk_f32_fp4 v[4:5], v92, 1.0
	v_cvt_scalef32_pk_f32_fp4 v[6:7], v92, 1.0 op_sel:[1,0,0]
	v_cvt_scalef32_pk_f32_fp4 v[8:9], v92, 1.0 op_sel:[0,1,0]
	v_cvt_scalef32_pk_f32_fp4 v[10:11], v92, 1.0 op_sel:[1,1,0]
	v_pk_fma_f32 v[62:63], s[32:33], v[4:5], v[62:63] op_sel_hi:[0,1,1]
	v_pk_fma_f32 v[60:61], s[32:33], v[6:7], v[60:61] op_sel_hi:[0,1,1]
	v_pk_fma_f32 v[52:53], s[32:33], v[8:9], v[52:53] op_sel_hi:[0,1,1]
	v_pk_fma_f32 v[54:55], s[32:33], v[10:11], v[54:55] op_sel_hi:[0,1,1]
	v_cvt_scalef32_pk_f32_fp4 v[4:5], v93, 1.0
	v_cvt_scalef32_pk_f32_fp4 v[6:7], v93, 1.0 op_sel:[1,0,0]
	v_cvt_scalef32_pk_f32_fp4 v[8:9], v93, 1.0 op_sel:[0,1,0]
	v_cvt_scalef32_pk_f32_fp4 v[10:11], v93, 1.0 op_sel:[1,1,0]
	v_pk_fma_f32 v[56:57], s[32:33], v[4:5], v[56:57] op_sel_hi:[0,1,1]
	v_pk_fma_f32 v[58:59], s[32:33], v[6:7], v[58:59] op_sel_hi:[0,1,1]
	v_pk_fma_f32 v[50:51], s[32:33], v[8:9], v[50:51] op_sel_hi:[0,1,1]
	v_pk_fma_f32 v[48:49], s[32:33], v[10:11], v[48:49] op_sel_hi:[0,1,1]
	v_readlane_b32 s29, v12, 38
	s_add_u32 s24, s14, s29
	s_addc_u32 s25, s15, 0
	global_load_dwordx2 v[92:93], v213, s[24:25]
	v_readlane_b32 s34, v14, 23
	v_cvt_scalef32_pk_f32_fp4 v[4:5], v94, 1.0
	v_cvt_scalef32_pk_f32_fp4 v[6:7], v94, 1.0 op_sel:[1,0,0]
	v_cvt_scalef32_pk_f32_fp4 v[8:9], v94, 1.0 op_sel:[0,1,0]
	v_cvt_scalef32_pk_f32_fp4 v[10:11], v94, 1.0 op_sel:[1,1,0]
	v_pk_fma_f32 v[62:63], s[34:35], v[4:5], v[62:63] op_sel_hi:[0,1,1]
	v_pk_fma_f32 v[60:61], s[34:35], v[6:7], v[60:61] op_sel_hi:[0,1,1]
	v_pk_fma_f32 v[52:53], s[34:35], v[8:9], v[52:53] op_sel_hi:[0,1,1]
	v_pk_fma_f32 v[54:55], s[34:35], v[10:11], v[54:55] op_sel_hi:[0,1,1]
	v_cvt_scalef32_pk_f32_fp4 v[4:5], v95, 1.0
	v_cvt_scalef32_pk_f32_fp4 v[6:7], v95, 1.0 op_sel:[1,0,0]
	v_cvt_scalef32_pk_f32_fp4 v[8:9], v95, 1.0 op_sel:[0,1,0]
	v_cvt_scalef32_pk_f32_fp4 v[10:11], v95, 1.0 op_sel:[1,1,0]
	v_pk_fma_f32 v[56:57], s[34:35], v[4:5], v[56:57] op_sel_hi:[0,1,1]
	v_pk_fma_f32 v[58:59], s[34:35], v[6:7], v[58:59] op_sel_hi:[0,1,1]
	v_pk_fma_f32 v[50:51], s[34:35], v[8:9], v[50:51] op_sel_hi:[0,1,1]
	v_pk_fma_f32 v[48:49], s[34:35], v[10:11], v[48:49] op_sel_hi:[0,1,1]
	v_readlane_b32 s30, v12, 39
	s_add_u32 s26, s14, s30
	s_addc_u32 s27, s15, 0
	global_load_dwordx2 v[94:95], v213, s[26:27]
	s_waitcnt vmcnt(12)
; __device__ void peer_v(const P& p, int layer, int tok, bool dry) {
;     ...
;     for (int jb = 0; jb < 64; jb += 16) {
;       u32x2 vv[16];
; #pragma unroll
;       for (int q = 0; q < 16; ++q) {
;         const int e = __builtin_amdgcn_readlane(eidx[h2], jb + q);
;         vv[q] = ((const u32x2*)(V4 + (size_t)e * 512))[lane];
;       }
; #pragma unroll
;       for (int q = 0; q < 16; ++q) {
;         const float wq = rdlane_f(wreg[h2], jb + q);
;         const f32x2 w2 = {wq, wq};
; #pragma unroll
;         for (int k = 0; k < 2; ++k) {
;           oa2[4 * k + 0] += w2 * __builtin_amdgcn_cvt_scalef32_pk_f32_fp4(vv[q][k], 1.0f, 0);
;           oa2[4 * k + 1] += w2 * __builtin_amdgcn_cvt_scalef32_pk_f32_fp4(vv[q][k], 1.0f, 1);
;           oa2[4 * k + 2] += w2 * __builtin_amdgcn_cvt_scalef32_pk_f32_fp4(vv[q][k], 1.0f, 2);
;           oa2[4 * k + 3] += w2 * __builtin_amdgcn_cvt_scalef32_pk_f32_fp4(vv[q][k], 1.0f, 3);
;         }
;       }
	v_readlane_b32 s32, v14, 24
	v_cvt_scalef32_pk_f32_fp4 v[4:5], v96, 1.0
	v_cvt_scalef32_pk_f32_fp4 v[6:7], v96, 1.0 op_sel:[1,0,0]
	v_cvt_scalef32_pk_f32_fp4 v[8:9], v96, 1.0 op_sel:[0,1,0]
	v_cvt_scalef32_pk_f32_fp4 v[10:11], v96, 1.0 op_sel:[1,1,0]
	v_pk_fma_f32 v[62:63], s[32:33], v[4:5], v[62:63] op_sel_hi:[0,1,1]
	v_pk_fma_f32 v[60:61], s[32:33], v[6:7], v[60:61] op_sel_hi:[0,1,1]
	v_pk_fma_f32 v[52:53], s[32:33], v[8:9], v[52:53] op_sel_hi:[0,1,1]
	v_pk_fma_f32 v[54:55], s[32:33], v[10:11], v[54:55] op_sel_hi:[0,1,1]
	v_cvt_scalef32_pk_f32_fp4 v[4:5], v97, 1.0
	v_cvt_scalef32_pk_f32_fp4 v[6:7], v97, 1.0 op_sel:[1,0,0]
	v_cvt_scalef32_pk_f32_fp4 v[8:9], v97, 1.0 op_sel:[0,1,0]
	v_cvt_scalef32_pk_f32_fp4 v[10:11], v97, 1.0 op_sel:[1,1,0]
	v_pk_fma_f32 v[56:57], s[32:33], v[4:5], v[56:57] op_sel_hi:[0,1,1]
	v_pk_fma_f32 v[58:59], s[32:33], v[6:7], v[58:59] op_sel_hi:[0,1,1]
	v_pk_fma_f32 v[50:51], s[32:33], v[8:9], v[50:51] op_sel_hi:[0,1,1]
	v_pk_fma_f32 v[48:49], s[32:33], v[10:11], v[48:49] op_sel_hi:[0,1,1]
	v_readlane_b32 s22, v12, 40
	s_add_u32 s16, s14, s22
	s_addc_u32 s17, s15, 0
	global_load_dwordx2 v[96:97], v213, s[16:17]
	v_readlane_b32 s34, v14, 25
	v_cvt_scalef32_pk_f32_fp4 v[4:5], v98, 1.0
	v_cvt_scalef32_pk_f32_fp4 v[6:7], v98, 1.0 op_sel:[1,0,0]
	v_cvt_scalef32_pk_f32_fp4 v[8:9], v98, 1.0 op_sel:[0,1,0]
	v_cvt_scalef32_pk_f32_fp4 v[10:11], v98, 1.0 op_sel:[1,1,0]
	v_pk_fma_f32 v[62:63], s[34:35], v[4:5], v[62:63] op_sel_hi:[0,1,1]
	v_pk_fma_f32 v[60:61], s[34:35], v[6:7], v[60:61] op_sel_hi:[0,1,1]
	v_pk_fma_f32 v[52:53], s[34:35], v[8:9], v[52:53] op_sel_hi:[0,1,1]
	v_pk_fma_f32 v[54:55], s[34:35], v[10:11], v[54:55] op_sel_hi:[0,1,1]
	v_cvt_scalef32_pk_f32_fp4 v[4:5], v99, 1.0
	v_cvt_scalef32_pk_f32_fp4 v[6:7], v99, 1.0 op_sel:[1,0,0]
	v_cvt_scalef32_pk_f32_fp4 v[8:9], v99, 1.0 op_sel:[0,1,0]
	v_cvt_scalef32_pk_f32_fp4 v[10:11], v99, 1.0 op_sel:[1,1,0]
	v_pk_fma_f32 v[56:57], s[34:35], v[4:5], v[56:57] op_sel_hi:[0,1,1]
	v_pk_fma_f32 v[58:59], s[34:35], v[6:7], v[58:59] op_sel_hi:[0,1,1]
	v_pk_fma_f32 v[50:51], s[34:35], v[8:9], v[50:51] op_sel_hi:[0,1,1]
	v_pk_fma_f32 v[48:49], s[34:35], v[10:11], v[48:49] op_sel_hi:[0,1,1]
	v_readlane_b32 s28, v12, 41
	s_add_u32 s20, s14, s28
	s_addc_u32 s21, s15, 0
	global_load_dwordx2 v[98:99], v213, s[20:21]
	v_readlane_b32 s32, v14, 26
	v_cvt_scalef32_pk_f32_fp4 v[4:5], v100, 1.0
	v_cvt_scalef32_pk_f32_fp4 v[6:7], v100, 1.0 op_sel:[1,0,0]
	v_cvt_scalef32_pk_f32_fp4 v[8:9], v100, 1.0 op_sel:[0,1,0]
	v_cvt_scalef32_pk_f32_fp4 v[10:11], v100, 1.0 op_sel:[1,1,0]
	v_pk_fma_f32 v[62:63], s[32:33], v[4:5], v[62:63] op_sel_hi:[0,1,1]
	v_pk_fma_f32 v[60:61], s[32:33], v[6:7], v[60:61] op_sel_hi:[0,1,1]
	v_pk_fma_f32 v[52:53], s[32:33], v[8:9], v[52:53] op_sel_hi:[0,1,1]
	v_pk_fma_f32 v[54:55], s[32:33], v[10:11], v[54:55] op_sel_hi:[0,1,1]
	v_cvt_scalef32_pk_f32_fp4 v[4:5], v101, 1.0
	v_cvt_scalef32_pk_f32_fp4 v[6:7], v101, 1.0 op_sel:[1,0,0]
	v_cvt_scalef32_pk_f32_fp4 v[8:9], v101, 1.0 op_sel:[0,1,0]
	v_cvt_scalef32_pk_f32_fp4 v[10:11], v101, 1.0 op_sel:[1,1,0]
	v_pk_fma_f32 v[56:57], s[32:33], v[4:5], v[56:57] op_sel_hi:[0,1,1]
	v_pk_fma_f32 v[58:59], s[32:33], v[6:7], v[58:59] op_sel_hi:[0,1,1]
	v_pk_fma_f32 v[50:51], s[32:33], v[8:9], v[50:51] op_sel_hi:[0,1,1]
	v_pk_fma_f32 v[48:49], s[32:33], v[10:11], v[48:49] op_sel_hi:[0,1,1]
	v_readlane_b32 s29, v12, 42
	s_add_u32 s24, s14, s29
	s_addc_u32 s25, s15, 0
	global_load_dwordx2 v[100:101], v213, s[24:25]
	v_readlane_b32 s34, v14, 27
	v_cvt_scalef32_pk_f32_fp4 v[4:5], v102, 1.0
	v_cvt_scalef32_pk_f32_fp4 v[6:7], v102, 1.0 op_sel:[1,0,0]
	v_cvt_scalef32_pk_f32_fp4 v[8:9], v102, 1.0 op_sel:[0,1,0]
	v_cvt_scalef32_pk_f32_fp4 v[10:11], v102, 1.0 op_sel:[1,1,0]
	v_pk_fma_f32 v[62:63], s[34:35], v[4:5], v[62:63] op_sel_hi:[0,1,1]
	v_pk_fma_f32 v[60:61], s[34:35], v[6:7], v[60:61] op_sel_hi:[0,1,1]
	v_pk_fma_f32 v[52:53], s[34:35], v[8:9], v[52:53] op_sel_hi:[0,1,1]
	v_pk_fma_f32 v[54:55], s[34:35], v[10:11], v[54:55] op_sel_hi:[0,1,1]
	v_cvt_scalef32_pk_f32_fp4 v[4:5], v103, 1.0
	v_cvt_scalef32_pk_f32_fp4 v[6:7], v103, 1.0 op_sel:[1,0,0]
	v_cvt_scalef32_pk_f32_fp4 v[8:9], v103, 1.0 op_sel:[0,1,0]
	v_cvt_scalef32_pk_f32_fp4 v[10:11], v103, 1.0 op_sel:[1,1,0]
	v_pk_fma_f32 v[56:57], s[34:35], v[4:5], v[56:57] op_sel_hi:[0,1,1]
	v_pk_fma_f32 v[58:59], s[34:35], v[6:7], v[58:59] op_sel_hi:[0,1,1]
	v_pk_fma_f32 v[50:51], s[34:35], v[8:9], v[50:51] op_sel_hi:[0,1,1]
	v_pk_fma_f32 v[48:49], s[34:35], v[10:11], v[48:49] op_sel_hi:[0,1,1]
	v_readlane_b32 s30, v12, 43
	s_add_u32 s26, s14, s30
	s_addc_u32 s27, s15, 0
	global_load_dwordx2 v[102:103], v213, s[26:27]
	s_waitcnt vmcnt(12)
; __device__ void peer_v(const P& p, int layer, int tok, bool dry) {
;     ...
;     for (int jb = 0; jb < 64; jb += 16) {
;       u32x2 vv[16];
; #pragma unroll
;       for (int q = 0; q < 16; ++q) {
;         const int e = __builtin_amdgcn_readlane(eidx[h2], jb + q);
;         vv[q] = ((const u32x2*)(V4 + (size_t)e * 512))[lane];
;       }
; #pragma unroll
;       for (int q = 0; q < 16; ++q) {
;         const float wq = rdlane_f(wreg[h2], jb + q);
;         const f32x2 w2 = {wq, wq};
; #pragma unroll
;         for (int k = 0; k < 2; ++k) {
;           oa2[4 * k + 0] += w2 * __builtin_amdgcn_cvt_scalef32_pk_f32_fp4(vv[q][k], 1.0f, 0);
;           oa2[4 * k + 1] += w2 * __builtin_amdgcn_cvt_scalef32_pk_f32_fp4(vv[q][k], 1.0f, 1);
;           oa2[4 * k + 2] += w2 * __builtin_amdgcn_cvt_scalef32_pk_f32_fp4(vv[q][k], 1.0f, 2);
;           oa2[4 * k + 3] += w2 * __builtin_amdgcn_cvt_scalef32_pk_f32_fp4(vv[q][k], 1.0f, 3);
;         }
;       }
	v_readlane_b32 s32, v14, 28
	v_cvt_scalef32_pk_f32_fp4 v[4:5], v104, 1.0
	v_cvt_scalef32_pk_f32_fp4 v[6:7], v104, 1.0 op_sel:[1,0,0]
	v_cvt_scalef32_pk_f32_fp4 v[8:9], v104, 1.0 op_sel:[0,1,0]
	v_cvt_scalef32_pk_f32_fp4 v[10:11], v104, 1.0 op_sel:[1,1,0]
	v_pk_fma_f32 v[62:63], s[32:33], v[4:5], v[62:63] op_sel_hi:[0,1,1]
	v_pk_fma_f32 v[60:61], s[32:33], v[6:7], v[60:61] op_sel_hi:[0,1,1]
	v_pk_fma_f32 v[52:53], s[32:33], v[8:9], v[52:53] op_sel_hi:[0,1,1]
	v_pk_fma_f32 v[54:55], s[32:33], v[10:11], v[54:55] op_sel_hi:[0,1,1]
	v_cvt_scalef32_pk_f32_fp4 v[4:5], v105, 1.0
	v_cvt_scalef32_pk_f32_fp4 v[6:7], v105, 1.0 op_sel:[1,0,0]
	v_cvt_scalef32_pk_f32_fp4 v[8:9], v105, 1.0 op_sel:[0,1,0]
	v_cvt_scalef32_pk_f32_fp4 v[10:11], v105, 1.0 op_sel:[1,1,0]
	v_pk_fma_f32 v[56:57], s[32:33], v[4:5], v[56:57] op_sel_hi:[0,1,1]
	v_pk_fma_f32 v[58:59], s[32:33], v[6:7], v[58:59] op_sel_hi:[0,1,1]
	v_pk_fma_f32 v[50:51], s[32:33], v[8:9], v[50:51] op_sel_hi:[0,1,1]
	v_pk_fma_f32 v[48:49], s[32:33], v[10:11], v[48:49] op_sel_hi:[0,1,1]
	v_readlane_b32 s22, v12, 44
	s_add_u32 s16, s14, s22
	s_addc_u32 s17, s15, 0
	global_load_dwordx2 v[104:105], v213, s[16:17]
	v_readlane_b32 s34, v14, 29
	v_cvt_scalef32_pk_f32_fp4 v[4:5], v106, 1.0
	v_cvt_scalef32_pk_f32_fp4 v[6:7], v106, 1.0 op_sel:[1,0,0]
	v_cvt_scalef32_pk_f32_fp4 v[8:9], v106, 1.0 op_sel:[0,1,0]
	v_cvt_scalef32_pk_f32_fp4 v[10:11], v106, 1.0 op_sel:[1,1,0]
	v_pk_fma_f32 v[62:63], s[34:35], v[4:5], v[62:63] op_sel_hi:[0,1,1]
	v_pk_fma_f32 v[60:61], s[34:35], v[6:7], v[60:61] op_sel_hi:[0,1,1]
	v_pk_fma_f32 v[52:53], s[34:35], v[8:9], v[52:53] op_sel_hi:[0,1,1]
	v_pk_fma_f32 v[54:55], s[34:35], v[10:11], v[54:55] op_sel_hi:[0,1,1]
	v_cvt_scalef32_pk_f32_fp4 v[4:5], v107, 1.0
	v_cvt_scalef32_pk_f32_fp4 v[6:7], v107, 1.0 op_sel:[1,0,0]
	v_cvt_scalef32_pk_f32_fp4 v[8:9], v107, 1.0 op_sel:[0,1,0]
	v_cvt_scalef32_pk_f32_fp4 v[10:11], v107, 1.0 op_sel:[1,1,0]
	v_pk_fma_f32 v[56:57], s[34:35], v[4:5], v[56:57] op_sel_hi:[0,1,1]
	v_pk_fma_f32 v[58:59], s[34:35], v[6:7], v[58:59] op_sel_hi:[0,1,1]
	v_pk_fma_f32 v[50:51], s[34:35], v[8:9], v[50:51] op_sel_hi:[0,1,1]
	v_pk_fma_f32 v[48:49], s[34:35], v[10:11], v[48:49] op_sel_hi:[0,1,1]
	v_readlane_b32 s28, v12, 45
	s_add_u32 s20, s14, s28
	s_addc_u32 s21, s15, 0
	global_load_dwordx2 v[106:107], v213, s[20:21]
	v_readlane_b32 s32, v14, 30
	v_cvt_scalef32_pk_f32_fp4 v[4:5], v108, 1.0
	v_cvt_scalef32_pk_f32_fp4 v[6:7], v108, 1.0 op_sel:[1,0,0]
	v_cvt_scalef32_pk_f32_fp4 v[8:9], v108, 1.0 op_sel:[0,1,0]
	v_cvt_scalef32_pk_f32_fp4 v[10:11], v108, 1.0 op_sel:[1,1,0]
	v_pk_fma_f32 v[62:63], s[32:33], v[4:5], v[62:63] op_sel_hi:[0,1,1]
	v_pk_fma_f32 v[60:61], s[32:33], v[6:7], v[60:61] op_sel_hi:[0,1,1]
	v_pk_fma_f32 v[52:53], s[32:33], v[8:9], v[52:53] op_sel_hi:[0,1,1]
	v_pk_fma_f32 v[54:55], s[32:33], v[10:11], v[54:55] op_sel_hi:[0,1,1]
	v_cvt_scalef32_pk_f32_fp4 v[4:5], v109, 1.0
	v_cvt_scalef32_pk_f32_fp4 v[6:7], v109, 1.0 op_sel:[1,0,0]
	v_cvt_scalef32_pk_f32_fp4 v[8:9], v109, 1.0 op_sel:[0,1,0]
	v_cvt_scalef32_pk_f32_fp4 v[10:11], v109, 1.0 op_sel:[1,1,0]
	v_pk_fma_f32 v[56:57], s[32:33], v[4:5], v[56:57] op_sel_hi:[0,1,1]
	v_pk_fma_f32 v[58:59], s[32:33], v[6:7], v[58:59] op_sel_hi:[0,1,1]
	v_pk_fma_f32 v[50:51], s[32:33], v[8:9], v[50:51] op_sel_hi:[0,1,1]
	v_pk_fma_f32 v[48:49], s[32:33], v[10:11], v[48:49] op_sel_hi:[0,1,1]
	v_readlane_b32 s29, v12, 46
	s_add_u32 s24, s14, s29
	s_addc_u32 s25, s15, 0
	global_load_dwordx2 v[108:109], v213, s[24:25]
	v_readlane_b32 s34, v14, 31
	v_cvt_scalef32_pk_f32_fp4 v[4:5], v110, 1.0
	v_cvt_scalef32_pk_f32_fp4 v[6:7], v110, 1.0 op_sel:[1,0,0]
	v_cvt_scalef32_pk_f32_fp4 v[8:9], v110, 1.0 op_sel:[0,1,0]
	v_cvt_scalef32_pk_f32_fp4 v[10:11], v110, 1.0 op_sel:[1,1,0]
	v_pk_fma_f32 v[62:63], s[34:35], v[4:5], v[62:63] op_sel_hi:[0,1,1]
	v_pk_fma_f32 v[60:61], s[34:35], v[6:7], v[60:61] op_sel_hi:[0,1,1]
	v_pk_fma_f32 v[52:53], s[34:35], v[8:9], v[52:53] op_sel_hi:[0,1,1]
	v_pk_fma_f32 v[54:55], s[34:35], v[10:11], v[54:55] op_sel_hi:[0,1,1]
	v_cvt_scalef32_pk_f32_fp4 v[4:5], v111, 1.0
	v_cvt_scalef32_pk_f32_fp4 v[6:7], v111, 1.0 op_sel:[1,0,0]
	v_cvt_scalef32_pk_f32_fp4 v[8:9], v111, 1.0 op_sel:[0,1,0]
	v_cvt_scalef32_pk_f32_fp4 v[10:11], v111, 1.0 op_sel:[1,1,0]
	v_pk_fma_f32 v[56:57], s[34:35], v[4:5], v[56:57] op_sel_hi:[0,1,1]
	v_pk_fma_f32 v[58:59], s[34:35], v[6:7], v[58:59] op_sel_hi:[0,1,1]
	v_pk_fma_f32 v[50:51], s[34:35], v[8:9], v[50:51] op_sel_hi:[0,1,1]
	v_pk_fma_f32 v[48:49], s[34:35], v[10:11], v[48:49] op_sel_hi:[0,1,1]
	v_readlane_b32 s30, v12, 47
	s_add_u32 s26, s14, s30
	s_addc_u32 s27, s15, 0
	global_load_dwordx2 v[110:111], v213, s[26:27]
	s_waitcnt vmcnt(12)
; __device__ void peer_v(const P& p, int layer, int tok, bool dry) {
;     ...
;     for (int jb = 0; jb < 64; jb += 16) {
;       u32x2 vv[16];
; #pragma unroll
;       for (int q = 0; q < 16; ++q) {
;         const int e = __builtin_amdgcn_readlane(eidx[h2], jb + q);
;         vv[q] = ((const u32x2*)(V4 + (size_t)e * 512))[lane];
;       }
; #pragma unroll
;       for (int q = 0; q < 16; ++q) {
;         const float wq = rdlane_f(wreg[h2], jb + q);
;         const f32x2 w2 = {wq, wq};
; #pragma unroll
;         for (int k = 0; k < 2; ++k) {
;           oa2[4 * k + 0] += w2 * __builtin_amdgcn_cvt_scalef32_pk_f32_fp4(vv[q][k], 1.0f, 0);
;           oa2[4 * k + 1] += w2 * __builtin_amdgcn_cvt_scalef32_pk_f32_fp4(vv[q][k], 1.0f, 1);
;           oa2[4 * k + 2] += w2 * __builtin_amdgcn_cvt_scalef32_pk_f32_fp4(vv[q][k], 1.0f, 2);
;           oa2[4 * k + 3] += w2 * __builtin_amdgcn_cvt_scalef32_pk_f32_fp4(vv[q][k], 1.0f, 3);
;         }
;       }
	v_readlane_b32 s32, v14, 32
	v_cvt_scalef32_pk_f32_fp4 v[4:5], v80, 1.0
	v_cvt_scalef32_pk_f32_fp4 v[6:7], v80, 1.0 op_sel:[1,0,0]
	v_cvt_scalef32_pk_f32_fp4 v[8:9], v80, 1.0 op_sel:[0,1,0]
	v_cvt_scalef32_pk_f32_fp4 v[10:11], v80, 1.0 op_sel:[1,1,0]
	v_pk_fma_f32 v[62:63], s[32:33], v[4:5], v[62:63] op_sel_hi:[0,1,1]
	v_pk_fma_f32 v[60:61], s[32:33], v[6:7], v[60:61] op_sel_hi:[0,1,1]
	v_pk_fma_f32 v[52:53], s[32:33], v[8:9], v[52:53] op_sel_hi:[0,1,1]
	v_pk_fma_f32 v[54:55], s[32:33], v[10:11], v[54:55] op_sel_hi:[0,1,1]
	v_cvt_scalef32_pk_f32_fp4 v[4:5], v81, 1.0
	v_cvt_scalef32_pk_f32_fp4 v[6:7], v81, 1.0 op_sel:[1,0,0]
	v_cvt_scalef32_pk_f32_fp4 v[8:9], v81, 1.0 op_sel:[0,1,0]
	v_cvt_scalef32_pk_f32_fp4 v[10:11], v81, 1.0 op_sel:[1,1,0]
	v_pk_fma_f32 v[56:57], s[32:33], v[4:5], v[56:57] op_sel_hi:[0,1,1]
	v_pk_fma_f32 v[58:59], s[32:33], v[6:7], v[58:59] op_sel_hi:[0,1,1]
	v_pk_fma_f32 v[50:51], s[32:33], v[8:9], v[50:51] op_sel_hi:[0,1,1]
	v_pk_fma_f32 v[48:49], s[32:33], v[10:11], v[48:49] op_sel_hi:[0,1,1]
	v_readlane_b32 s22, v12, 48
	s_add_u32 s16, s14, s22
	s_addc_u32 s17, s15, 0
	global_load_dwordx2 v[80:81], v213, s[16:17]
	v_readlane_b32 s34, v14, 33
	v_cvt_scalef32_pk_f32_fp4 v[4:5], v82, 1.0
	v_cvt_scalef32_pk_f32_fp4 v[6:7], v82, 1.0 op_sel:[1,0,0]
	v_cvt_scalef32_pk_f32_fp4 v[8:9], v82, 1.0 op_sel:[0,1,0]
	v_cvt_scalef32_pk_f32_fp4 v[10:11], v82, 1.0 op_sel:[1,1,0]
	v_pk_fma_f32 v[62:63], s[34:35], v[4:5], v[62:63] op_sel_hi:[0,1,1]
	v_pk_fma_f32 v[60:61], s[34:35], v[6:7], v[60:61] op_sel_hi:[0,1,1]
	v_pk_fma_f32 v[52:53], s[34:35], v[8:9], v[52:53] op_sel_hi:[0,1,1]
	v_pk_fma_f32 v[54:55], s[34:35], v[10:11], v[54:55] op_sel_hi:[0,1,1]
	v_cvt_scalef32_pk_f32_fp4 v[4:5], v83, 1.0
	v_cvt_scalef32_pk_f32_fp4 v[6:7], v83, 1.0 op_sel:[1,0,0]
	v_cvt_scalef32_pk_f32_fp4 v[8:9], v83, 1.0 op_sel:[0,1,0]
	v_cvt_scalef32_pk_f32_fp4 v[10:11], v83, 1.0 op_sel:[1,1,0]
	v_pk_fma_f32 v[56:57], s[34:35], v[4:5], v[56:57] op_sel_hi:[0,1,1]
	v_pk_fma_f32 v[58:59], s[34:35], v[6:7], v[58:59] op_sel_hi:[0,1,1]
	v_pk_fma_f32 v[50:51], s[34:35], v[8:9], v[50:51] op_sel_hi:[0,1,1]
	v_pk_fma_f32 v[48:49], s[34:35], v[10:11], v[48:49] op_sel_hi:[0,1,1]
	v_readlane_b32 s28, v12, 49
	s_add_u32 s20, s14, s28
	s_addc_u32 s21, s15, 0
	global_load_dwordx2 v[82:83], v213, s[20:21]
	v_readlane_b32 s32, v14, 34
	v_cvt_scalef32_pk_f32_fp4 v[4:5], v84, 1.0
	v_cvt_scalef32_pk_f32_fp4 v[6:7], v84, 1.0 op_sel:[1,0,0]
	v_cvt_scalef32_pk_f32_fp4 v[8:9], v84, 1.0 op_sel:[0,1,0]
	v_cvt_scalef32_pk_f32_fp4 v[10:11], v84, 1.0 op_sel:[1,1,0]
	v_pk_fma_f32 v[62:63], s[32:33], v[4:5], v[62:63] op_sel_hi:[0,1,1]
	v_pk_fma_f32 v[60:61], s[32:33], v[6:7], v[60:61] op_sel_hi:[0,1,1]
	v_pk_fma_f32 v[52:53], s[32:33], v[8:9], v[52:53] op_sel_hi:[0,1,1]
	v_pk_fma_f32 v[54:55], s[32:33], v[10:11], v[54:55] op_sel_hi:[0,1,1]
	v_cvt_scalef32_pk_f32_fp4 v[4:5], v85, 1.0
	v_cvt_scalef32_pk_f32_fp4 v[6:7], v85, 1.0 op_sel:[1,0,0]
	v_cvt_scalef32_pk_f32_fp4 v[8:9], v85, 1.0 op_sel:[0,1,0]
	v_cvt_scalef32_pk_f32_fp4 v[10:11], v85, 1.0 op_sel:[1,1,0]
	v_pk_fma_f32 v[56:57], s[32:33], v[4:5], v[56:57] op_sel_hi:[0,1,1]
	v_pk_fma_f32 v[58:59], s[32:33], v[6:7], v[58:59] op_sel_hi:[0,1,1]
	v_pk_fma_f32 v[50:51], s[32:33], v[8:9], v[50:51] op_sel_hi:[0,1,1]
	v_pk_fma_f32 v[48:49], s[32:33], v[10:11], v[48:49] op_sel_hi:[0,1,1]
	v_readlane_b32 s29, v12, 50
	s_add_u32 s24, s14, s29
	s_addc_u32 s25, s15, 0
	global_load_dwordx2 v[84:85], v213, s[24:25]
	v_readlane_b32 s34, v14, 35
	v_cvt_scalef32_pk_f32_fp4 v[4:5], v86, 1.0
	v_cvt_scalef32_pk_f32_fp4 v[6:7], v86, 1.0 op_sel:[1,0,0]
	v_cvt_scalef32_pk_f32_fp4 v[8:9], v86, 1.0 op_sel:[0,1,0]
	v_cvt_scalef32_pk_f32_fp4 v[10:11], v86, 1.0 op_sel:[1,1,0]
	v_pk_fma_f32 v[62:63], s[34:35], v[4:5], v[62:63] op_sel_hi:[0,1,1]
	v_pk_fma_f32 v[60:61], s[34:35], v[6:7], v[60:61] op_sel_hi:[0,1,1]
	v_pk_fma_f32 v[52:53], s[34:35], v[8:9], v[52:53] op_sel_hi:[0,1,1]
	v_pk_fma_f32 v[54:55], s[34:35], v[10:11], v[54:55] op_sel_hi:[0,1,1]
	v_cvt_scalef32_pk_f32_fp4 v[4:5], v87, 1.0
	v_cvt_scalef32_pk_f32_fp4 v[6:7], v87, 1.0 op_sel:[1,0,0]
	v_cvt_scalef32_pk_f32_fp4 v[8:9], v87, 1.0 op_sel:[0,1,0]
	v_cvt_scalef32_pk_f32_fp4 v[10:11], v87, 1.0 op_sel:[1,1,0]
	v_pk_fma_f32 v[56:57], s[34:35], v[4:5], v[56:57] op_sel_hi:[0,1,1]
	v_pk_fma_f32 v[58:59], s[34:35], v[6:7], v[58:59] op_sel_hi:[0,1,1]
	v_pk_fma_f32 v[50:51], s[34:35], v[8:9], v[50:51] op_sel_hi:[0,1,1]
	v_pk_fma_f32 v[48:49], s[34:35], v[10:11], v[48:49] op_sel_hi:[0,1,1]
	v_readlane_b32 s30, v12, 51
	s_add_u32 s26, s14, s30
	s_addc_u32 s27, s15, 0
	global_load_dwordx2 v[86:87], v213, s[26:27]
	s_waitcnt vmcnt(12)
; __device__ void peer_v(const P& p, int layer, int tok, bool dry) {
;     ...
;     for (int jb = 0; jb < 64; jb += 16) {
;       u32x2 vv[16];
; #pragma unroll
;       for (int q = 0; q < 16; ++q) {
;         const int e = __builtin_amdgcn_readlane(eidx[h2], jb + q);
;         vv[q] = ((const u32x2*)(V4 + (size_t)e * 512))[lane];
;       }
; #pragma unroll
;       for (int q = 0; q < 16; ++q) {
;         const float wq = rdlane_f(wreg[h2], jb + q);
;         const f32x2 w2 = {wq, wq};
; #pragma unroll
;         for (int k = 0; k < 2; ++k) {
;           oa2[4 * k + 0] += w2 * __builtin_amdgcn_cvt_scalef32_pk_f32_fp4(vv[q][k], 1.0f, 0);
;           oa2[4 * k + 1] += w2 * __builtin_amdgcn_cvt_scalef32_pk_f32_fp4(vv[q][k], 1.0f, 1);
;           oa2[4 * k + 2] += w2 * __builtin_amdgcn_cvt_scalef32_pk_f32_fp4(vv[q][k], 1.0f, 2);
;           oa2[4 * k + 3] += w2 * __builtin_amdgcn_cvt_scalef32_pk_f32_fp4(vv[q][k], 1.0f, 3);
;         }
;       }
	v_readlane_b32 s32, v14, 36
	v_cvt_scalef32_pk_f32_fp4 v[4:5], v88, 1.0
	v_cvt_scalef32_pk_f32_fp4 v[6:7], v88, 1.0 op_sel:[1,0,0]
	v_cvt_scalef32_pk_f32_fp4 v[8:9], v88, 1.0 op_sel:[0,1,0]
	v_cvt_scalef32_pk_f32_fp4 v[10:11], v88, 1.0 op_sel:[1,1,0]
	v_pk_fma_f32 v[62:63], s[32:33], v[4:5], v[62:63] op_sel_hi:[0,1,1]
	v_pk_fma_f32 v[60:61], s[32:33], v[6:7], v[60:61] op_sel_hi:[0,1,1]
	v_pk_fma_f32 v[52:53], s[32:33], v[8:9], v[52:53] op_sel_hi:[0,1,1]
	v_pk_fma_f32 v[54:55], s[32:33], v[10:11], v[54:55] op_sel_hi:[0,1,1]
	v_cvt_scalef32_pk_f32_fp4 v[4:5], v89, 1.0
	v_cvt_scalef32_pk_f32_fp4 v[6:7], v89, 1.0 op_sel:[1,0,0]
	v_cvt_scalef32_pk_f32_fp4 v[8:9], v89, 1.0 op_sel:[0,1,0]
	v_cvt_scalef32_pk_f32_fp4 v[10:11], v89, 1.0 op_sel:[1,1,0]
	v_pk_fma_f32 v[56:57], s[32:33], v[4:5], v[56:57] op_sel_hi:[0,1,1]
	v_pk_fma_f32 v[58:59], s[32:33], v[6:7], v[58:59] op_sel_hi:[0,1,1]
	v_pk_fma_f32 v[50:51], s[32:33], v[8:9], v[50:51] op_sel_hi:[0,1,1]
	v_pk_fma_f32 v[48:49], s[32:33], v[10:11], v[48:49] op_sel_hi:[0,1,1]
	v_readlane_b32 s22, v12, 52
	s_add_u32 s16, s14, s22
	s_addc_u32 s17, s15, 0
	global_load_dwordx2 v[88:89], v213, s[16:17]
	v_readlane_b32 s34, v14, 37
	v_cvt_scalef32_pk_f32_fp4 v[4:5], v90, 1.0
	v_cvt_scalef32_pk_f32_fp4 v[6:7], v90, 1.0 op_sel:[1,0,0]
	v_cvt_scalef32_pk_f32_fp4 v[8:9], v90, 1.0 op_sel:[0,1,0]
	v_cvt_scalef32_pk_f32_fp4 v[10:11], v90, 1.0 op_sel:[1,1,0]
	v_pk_fma_f32 v[62:63], s[34:35], v[4:5], v[62:63] op_sel_hi:[0,1,1]
	v_pk_fma_f32 v[60:61], s[34:35], v[6:7], v[60:61] op_sel_hi:[0,1,1]
	v_pk_fma_f32 v[52:53], s[34:35], v[8:9], v[52:53] op_sel_hi:[0,1,1]
	v_pk_fma_f32 v[54:55], s[34:35], v[10:11], v[54:55] op_sel_hi:[0,1,1]
	v_cvt_scalef32_pk_f32_fp4 v[4:5], v91, 1.0
	v_cvt_scalef32_pk_f32_fp4 v[6:7], v91, 1.0 op_sel:[1,0,0]
	v_cvt_scalef32_pk_f32_fp4 v[8:9], v91, 1.0 op_sel:[0,1,0]
	v_cvt_scalef32_pk_f32_fp4 v[10:11], v91, 1.0 op_sel:[1,1,0]
	v_pk_fma_f32 v[56:57], s[34:35], v[4:5], v[56:57] op_sel_hi:[0,1,1]
	v_pk_fma_f32 v[58:59], s[34:35], v[6:7], v[58:59] op_sel_hi:[0,1,1]
	v_pk_fma_f32 v[50:51], s[34:35], v[8:9], v[50:51] op_sel_hi:[0,1,1]
	v_pk_fma_f32 v[48:49], s[34:35], v[10:11], v[48:49] op_sel_hi:[0,1,1]
	v_readlane_b32 s28, v12, 53
	s_add_u32 s20, s14, s28
	s_addc_u32 s21, s15, 0
	global_load_dwordx2 v[90:91], v213, s[20:21]
	v_readlane_b32 s32, v14, 38
	v_cvt_scalef32_pk_f32_fp4 v[4:5], v92, 1.0
	v_cvt_scalef32_pk_f32_fp4 v[6:7], v92, 1.0 op_sel:[1,0,0]
	v_cvt_scalef32_pk_f32_fp4 v[8:9], v92, 1.0 op_sel:[0,1,0]
	v_cvt_scalef32_pk_f32_fp4 v[10:11], v92, 1.0 op_sel:[1,1,0]
	v_pk_fma_f32 v[62:63], s[32:33], v[4:5], v[62:63] op_sel_hi:[0,1,1]
	v_pk_fma_f32 v[60:61], s[32:33], v[6:7], v[60:61] op_sel_hi:[0,1,1]
	v_pk_fma_f32 v[52:53], s[32:33], v[8:9], v[52:53] op_sel_hi:[0,1,1]
	v_pk_fma_f32 v[54:55], s[32:33], v[10:11], v[54:55] op_sel_hi:[0,1,1]
	v_cvt_scalef32_pk_f32_fp4 v[4:5], v93, 1.0
	v_cvt_scalef32_pk_f32_fp4 v[6:7], v93, 1.0 op_sel:[1,0,0]
	v_cvt_scalef32_pk_f32_fp4 v[8:9], v93, 1.0 op_sel:[0,1,0]
	v_cvt_scalef32_pk_f32_fp4 v[10:11], v93, 1.0 op_sel:[1,1,0]
	v_pk_fma_f32 v[56:57], s[32:33], v[4:5], v[56:57] op_sel_hi:[0,1,1]
	v_pk_fma_f32 v[58:59], s[32:33], v[6:7], v[58:59] op_sel_hi:[0,1,1]
	v_pk_fma_f32 v[50:51], s[32:33], v[8:9], v[50:51] op_sel_hi:[0,1,1]
	v_pk_fma_f32 v[48:49], s[32:33], v[10:11], v[48:49] op_sel_hi:[0,1,1]
	v_readlane_b32 s29, v12, 54
	s_add_u32 s24, s14, s29
	s_addc_u32 s25, s15, 0
	global_load_dwordx2 v[92:93], v213, s[24:25]
	v_readlane_b32 s34, v14, 39
	v_cvt_scalef32_pk_f32_fp4 v[4:5], v94, 1.0
	v_cvt_scalef32_pk_f32_fp4 v[6:7], v94, 1.0 op_sel:[1,0,0]
	v_cvt_scalef32_pk_f32_fp4 v[8:9], v94, 1.0 op_sel:[0,1,0]
	v_cvt_scalef32_pk_f32_fp4 v[10:11], v94, 1.0 op_sel:[1,1,0]
	v_pk_fma_f32 v[62:63], s[34:35], v[4:5], v[62:63] op_sel_hi:[0,1,1]
	v_pk_fma_f32 v[60:61], s[34:35], v[6:7], v[60:61] op_sel_hi:[0,1,1]
	v_pk_fma_f32 v[52:53], s[34:35], v[8:9], v[52:53] op_sel_hi:[0,1,1]
	v_pk_fma_f32 v[54:55], s[34:35], v[10:11], v[54:55] op_sel_hi:[0,1,1]
	v_cvt_scalef32_pk_f32_fp4 v[4:5], v95, 1.0
	v_cvt_scalef32_pk_f32_fp4 v[6:7], v95, 1.0 op_sel:[1,0,0]
	v_cvt_scalef32_pk_f32_fp4 v[8:9], v95, 1.0 op_sel:[0,1,0]
	v_cvt_scalef32_pk_f32_fp4 v[10:11], v95, 1.0 op_sel:[1,1,0]
	v_pk_fma_f32 v[56:57], s[34:35], v[4:5], v[56:57] op_sel_hi:[0,1,1]
	v_pk_fma_f32 v[58:59], s[34:35], v[6:7], v[58:59] op_sel_hi:[0,1,1]
	v_pk_fma_f32 v[50:51], s[34:35], v[8:9], v[50:51] op_sel_hi:[0,1,1]
	v_pk_fma_f32 v[48:49], s[34:35], v[10:11], v[48:49] op_sel_hi:[0,1,1]
	v_readlane_b32 s30, v12, 55
	s_add_u32 s26, s14, s30
	s_addc_u32 s27, s15, 0
	global_load_dwordx2 v[94:95], v213, s[26:27]
	s_waitcnt vmcnt(12)
; __device__ void peer_v(const P& p, int layer, int tok, bool dry) {
;     ...
;     for (int jb = 0; jb < 64; jb += 16) {
;       u32x2 vv[16];
; #pragma unroll
;       for (int q = 0; q < 16; ++q) {
;         const int e = __builtin_amdgcn_readlane(eidx[h2], jb + q);
;         vv[q] = ((const u32x2*)(V4 + (size_t)e * 512))[lane];
;       }
; #pragma unroll
;       for (int q = 0; q < 16; ++q) {
;         const float wq = rdlane_f(wreg[h2], jb + q);
;         const f32x2 w2 = {wq, wq};
; #pragma unroll
;         for (int k = 0; k < 2; ++k) {
;           oa2[4 * k + 0] += w2 * __builtin_amdgcn_cvt_scalef32_pk_f32_fp4(vv[q][k], 1.0f, 0);
;           oa2[4 * k + 1] += w2 * __builtin_amdgcn_cvt_scalef32_pk_f32_fp4(vv[q][k], 1.0f, 1);
;           oa2[4 * k + 2] += w2 * __builtin_amdgcn_cvt_scalef32_pk_f32_fp4(vv[q][k], 1.0f, 2);
;           oa2[4 * k + 3] += w2 * __builtin_amdgcn_cvt_scalef32_pk_f32_fp4(vv[q][k], 1.0f, 3);
;         }
;       }
	v_readlane_b32 s32, v14, 40
	v_cvt_scalef32_pk_f32_fp4 v[4:5], v96, 1.0
	v_cvt_scalef32_pk_f32_fp4 v[6:7], v96, 1.0 op_sel:[1,0,0]
	v_cvt_scalef32_pk_f32_fp4 v[8:9], v96, 1.0 op_sel:[0,1,0]
	v_cvt_scalef32_pk_f32_fp4 v[10:11], v96, 1.0 op_sel:[1,1,0]
	v_pk_fma_f32 v[62:63], s[32:33], v[4:5], v[62:63] op_sel_hi:[0,1,1]
	v_pk_fma_f32 v[60:61], s[32:33], v[6:7], v[60:61] op_sel_hi:[0,1,1]
	v_pk_fma_f32 v[52:53], s[32:33], v[8:9], v[52:53] op_sel_hi:[0,1,1]
	v_pk_fma_f32 v[54:55], s[32:33], v[10:11], v[54:55] op_sel_hi:[0,1,1]
	v_cvt_scalef32_pk_f32_fp4 v[4:5], v97, 1.0
	v_cvt_scalef32_pk_f32_fp4 v[6:7], v97, 1.0 op_sel:[1,0,0]
	v_cvt_scalef32_pk_f32_fp4 v[8:9], v97, 1.0 op_sel:[0,1,0]
	v_cvt_scalef32_pk_f32_fp4 v[10:11], v97, 1.0 op_sel:[1,1,0]
	v_pk_fma_f32 v[56:57], s[32:33], v[4:5], v[56:57] op_sel_hi:[0,1,1]
	v_pk_fma_f32 v[58:59], s[32:33], v[6:7], v[58:59] op_sel_hi:[0,1,1]
	v_pk_fma_f32 v[50:51], s[32:33], v[8:9], v[50:51] op_sel_hi:[0,1,1]
	v_pk_fma_f32 v[48:49], s[32:33], v[10:11], v[48:49] op_sel_hi:[0,1,1]
	v_readlane_b32 s22, v12, 56
	s_add_u32 s16, s14, s22
	s_addc_u32 s17, s15, 0
	global_load_dwordx2 v[96:97], v213, s[16:17]
	v_readlane_b32 s34, v14, 41
	v_cvt_scalef32_pk_f32_fp4 v[4:5], v98, 1.0
	v_cvt_scalef32_pk_f32_fp4 v[6:7], v98, 1.0 op_sel:[1,0,0]
	v_cvt_scalef32_pk_f32_fp4 v[8:9], v98, 1.0 op_sel:[0,1,0]
	v_cvt_scalef32_pk_f32_fp4 v[10:11], v98, 1.0 op_sel:[1,1,0]
	v_pk_fma_f32 v[62:63], s[34:35], v[4:5], v[62:63] op_sel_hi:[0,1,1]
	v_pk_fma_f32 v[60:61], s[34:35], v[6:7], v[60:61] op_sel_hi:[0,1,1]
	v_pk_fma_f32 v[52:53], s[34:35], v[8:9], v[52:53] op_sel_hi:[0,1,1]
	v_pk_fma_f32 v[54:55], s[34:35], v[10:11], v[54:55] op_sel_hi:[0,1,1]
	v_cvt_scalef32_pk_f32_fp4 v[4:5], v99, 1.0
	v_cvt_scalef32_pk_f32_fp4 v[6:7], v99, 1.0 op_sel:[1,0,0]
	v_cvt_scalef32_pk_f32_fp4 v[8:9], v99, 1.0 op_sel:[0,1,0]
	v_cvt_scalef32_pk_f32_fp4 v[10:11], v99, 1.0 op_sel:[1,1,0]
	v_pk_fma_f32 v[56:57], s[34:35], v[4:5], v[56:57] op_sel_hi:[0,1,1]
	v_pk_fma_f32 v[58:59], s[34:35], v[6:7], v[58:59] op_sel_hi:[0,1,1]
	v_pk_fma_f32 v[50:51], s[34:35], v[8:9], v[50:51] op_sel_hi:[0,1,1]
	v_pk_fma_f32 v[48:49], s[34:35], v[10:11], v[48:49] op_sel_hi:[0,1,1]
	v_readlane_b32 s28, v12, 57
	s_add_u32 s20, s14, s28
	s_addc_u32 s21, s15, 0
	global_load_dwordx2 v[98:99], v213, s[20:21]
	v_readlane_b32 s32, v14, 42
	v_cvt_scalef32_pk_f32_fp4 v[4:5], v100, 1.0
	v_cvt_scalef32_pk_f32_fp4 v[6:7], v100, 1.0 op_sel:[1,0,0]
	v_cvt_scalef32_pk_f32_fp4 v[8:9], v100, 1.0 op_sel:[0,1,0]
	v_cvt_scalef32_pk_f32_fp4 v[10:11], v100, 1.0 op_sel:[1,1,0]
	v_pk_fma_f32 v[62:63], s[32:33], v[4:5], v[62:63] op_sel_hi:[0,1,1]
	v_pk_fma_f32 v[60:61], s[32:33], v[6:7], v[60:61] op_sel_hi:[0,1,1]
	v_pk_fma_f32 v[52:53], s[32:33], v[8:9], v[52:53] op_sel_hi:[0,1,1]
	v_pk_fma_f32 v[54:55], s[32:33], v[10:11], v[54:55] op_sel_hi:[0,1,1]
	v_cvt_scalef32_pk_f32_fp4 v[4:5], v101, 1.0
	v_cvt_scalef32_pk_f32_fp4 v[6:7], v101, 1.0 op_sel:[1,0,0]
	v_cvt_scalef32_pk_f32_fp4 v[8:9], v101, 1.0 op_sel:[0,1,0]
	v_cvt_scalef32_pk_f32_fp4 v[10:11], v101, 1.0 op_sel:[1,1,0]
	v_pk_fma_f32 v[56:57], s[32:33], v[4:5], v[56:57] op_sel_hi:[0,1,1]
	v_pk_fma_f32 v[58:59], s[32:33], v[6:7], v[58:59] op_sel_hi:[0,1,1]
	v_pk_fma_f32 v[50:51], s[32:33], v[8:9], v[50:51] op_sel_hi:[0,1,1]
	v_pk_fma_f32 v[48:49], s[32:33], v[10:11], v[48:49] op_sel_hi:[0,1,1]
	v_readlane_b32 s29, v12, 58
	s_add_u32 s24, s14, s29
	s_addc_u32 s25, s15, 0
	global_load_dwordx2 v[100:101], v213, s[24:25]
	v_readlane_b32 s34, v14, 43
	v_cvt_scalef32_pk_f32_fp4 v[4:5], v102, 1.0
	v_cvt_scalef32_pk_f32_fp4 v[6:7], v102, 1.0 op_sel:[1,0,0]
	v_cvt_scalef32_pk_f32_fp4 v[8:9], v102, 1.0 op_sel:[0,1,0]
	v_cvt_scalef32_pk_f32_fp4 v[10:11], v102, 1.0 op_sel:[1,1,0]
	v_pk_fma_f32 v[62:63], s[34:35], v[4:5], v[62:63] op_sel_hi:[0,1,1]
	v_pk_fma_f32 v[60:61], s[34:35], v[6:7], v[60:61] op_sel_hi:[0,1,1]
	v_pk_fma_f32 v[52:53], s[34:35], v[8:9], v[52:53] op_sel_hi:[0,1,1]
	v_pk_fma_f32 v[54:55], s[34:35], v[10:11], v[54:55] op_sel_hi:[0,1,1]
	v_cvt_scalef32_pk_f32_fp4 v[4:5], v103, 1.0
	v_cvt_scalef32_pk_f32_fp4 v[6:7], v103, 1.0 op_sel:[1,0,0]
	v_cvt_scalef32_pk_f32_fp4 v[8:9], v103, 1.0 op_sel:[0,1,0]
	v_cvt_scalef32_pk_f32_fp4 v[10:11], v103, 1.0 op_sel:[1,1,0]
	v_pk_fma_f32 v[56:57], s[34:35], v[4:5], v[56:57] op_sel_hi:[0,1,1]
	v_pk_fma_f32 v[58:59], s[34:35], v[6:7], v[58:59] op_sel_hi:[0,1,1]
	v_pk_fma_f32 v[50:51], s[34:35], v[8:9], v[50:51] op_sel_hi:[0,1,1]
	v_pk_fma_f32 v[48:49], s[34:35], v[10:11], v[48:49] op_sel_hi:[0,1,1]
	v_readlane_b32 s30, v12, 59
	s_add_u32 s26, s14, s30
	s_addc_u32 s27, s15, 0
	global_load_dwordx2 v[102:103], v213, s[26:27]
	s_waitcnt vmcnt(12)
; __device__ void peer_v(const P& p, int layer, int tok, bool dry) {
;     ...
;     for (int jb = 0; jb < 64; jb += 16) {
;       u32x2 vv[16];
; #pragma unroll
;       for (int q = 0; q < 16; ++q) {
;         const int e = __builtin_amdgcn_readlane(eidx[h2], jb + q);
;         vv[q] = ((const u32x2*)(V4 + (size_t)e * 512))[lane];
;       }
; #pragma unroll
;       for (int q = 0; q < 16; ++q) {
;         const float wq = rdlane_f(wreg[h2], jb + q);
;         const f32x2 w2 = {wq, wq};
; #pragma unroll
;         for (int k = 0; k < 2; ++k) {
;           oa2[4 * k + 0] += w2 * __builtin_amdgcn_cvt_scalef32_pk_f32_fp4(vv[q][k], 1.0f, 0);
;           oa2[4 * k + 1] += w2 * __builtin_amdgcn_cvt_scalef32_pk_f32_fp4(vv[q][k], 1.0f, 1);
;           oa2[4 * k + 2] += w2 * __builtin_amdgcn_cvt_scalef32_pk_f32_fp4(vv[q][k], 1.0f, 2);
;           oa2[4 * k + 3] += w2 * __builtin_amdgcn_cvt_scalef32_pk_f32_fp4(vv[q][k], 1.0f, 3);
;         }
;       }
	v_readlane_b32 s32, v14, 44
	v_cvt_scalef32_pk_f32_fp4 v[4:5], v104, 1.0
	v_cvt_scalef32_pk_f32_fp4 v[6:7], v104, 1.0 op_sel:[1,0,0]
	v_cvt_scalef32_pk_f32_fp4 v[8:9], v104, 1.0 op_sel:[0,1,0]
	v_cvt_scalef32_pk_f32_fp4 v[10:11], v104, 1.0 op_sel:[1,1,0]
	v_pk_fma_f32 v[62:63], s[32:33], v[4:5], v[62:63] op_sel_hi:[0,1,1]
	v_pk_fma_f32 v[60:61], s[32:33], v[6:7], v[60:61] op_sel_hi:[0,1,1]
	v_pk_fma_f32 v[52:53], s[32:33], v[8:9], v[52:53] op_sel_hi:[0,1,1]
	v_pk_fma_f32 v[54:55], s[32:33], v[10:11], v[54:55] op_sel_hi:[0,1,1]
	v_cvt_scalef32_pk_f32_fp4 v[4:5], v105, 1.0
	v_cvt_scalef32_pk_f32_fp4 v[6:7], v105, 1.0 op_sel:[1,0,0]
	v_cvt_scalef32_pk_f32_fp4 v[8:9], v105, 1.0 op_sel:[0,1,0]
	v_cvt_scalef32_pk_f32_fp4 v[10:11], v105, 1.0 op_sel:[1,1,0]
	v_pk_fma_f32 v[56:57], s[32:33], v[4:5], v[56:57] op_sel_hi:[0,1,1]
	v_pk_fma_f32 v[58:59], s[32:33], v[6:7], v[58:59] op_sel_hi:[0,1,1]
	v_pk_fma_f32 v[50:51], s[32:33], v[8:9], v[50:51] op_sel_hi:[0,1,1]
	v_pk_fma_f32 v[48:49], s[32:33], v[10:11], v[48:49] op_sel_hi:[0,1,1]
	v_readlane_b32 s22, v12, 60
	s_add_u32 s16, s14, s22
	s_addc_u32 s17, s15, 0
	global_load_dwordx2 v[104:105], v213, s[16:17]
	v_readlane_b32 s34, v14, 45
	v_cvt_scalef32_pk_f32_fp4 v[4:5], v106, 1.0
	v_cvt_scalef32_pk_f32_fp4 v[6:7], v106, 1.0 op_sel:[1,0,0]
	v_cvt_scalef32_pk_f32_fp4 v[8:9], v106, 1.0 op_sel:[0,1,0]
	v_cvt_scalef32_pk_f32_fp4 v[10:11], v106, 1.0 op_sel:[1,1,0]
	v_pk_fma_f32 v[62:63], s[34:35], v[4:5], v[62:63] op_sel_hi:[0,1,1]
	v_pk_fma_f32 v[60:61], s[34:35], v[6:7], v[60:61] op_sel_hi:[0,1,1]
	v_pk_fma_f32 v[52:53], s[34:35], v[8:9], v[52:53] op_sel_hi:[0,1,1]
	v_pk_fma_f32 v[54:55], s[34:35], v[10:11], v[54:55] op_sel_hi:[0,1,1]
	v_cvt_scalef32_pk_f32_fp4 v[4:5], v107, 1.0
	v_cvt_scalef32_pk_f32_fp4 v[6:7], v107, 1.0 op_sel:[1,0,0]
	v_cvt_scalef32_pk_f32_fp4 v[8:9], v107, 1.0 op_sel:[0,1,0]
	v_cvt_scalef32_pk_f32_fp4 v[10:11], v107, 1.0 op_sel:[1,1,0]
	v_pk_fma_f32 v[56:57], s[34:35], v[4:5], v[56:57] op_sel_hi:[0,1,1]
	v_pk_fma_f32 v[58:59], s[34:35], v[6:7], v[58:59] op_sel_hi:[0,1,1]
	v_pk_fma_f32 v[50:51], s[34:35], v[8:9], v[50:51] op_sel_hi:[0,1,1]
	v_pk_fma_f32 v[48:49], s[34:35], v[10:11], v[48:49] op_sel_hi:[0,1,1]
	v_readlane_b32 s28, v12, 61
	s_add_u32 s20, s14, s28
	s_addc_u32 s21, s15, 0
	global_load_dwordx2 v[106:107], v213, s[20:21]
	v_readlane_b32 s32, v14, 46
	v_cvt_scalef32_pk_f32_fp4 v[4:5], v108, 1.0
	v_cvt_scalef32_pk_f32_fp4 v[6:7], v108, 1.0 op_sel:[1,0,0]
	v_cvt_scalef32_pk_f32_fp4 v[8:9], v108, 1.0 op_sel:[0,1,0]
	v_cvt_scalef32_pk_f32_fp4 v[10:11], v108, 1.0 op_sel:[1,1,0]
	v_pk_fma_f32 v[62:63], s[32:33], v[4:5], v[62:63] op_sel_hi:[0,1,1]
	v_pk_fma_f32 v[60:61], s[32:33], v[6:7], v[60:61] op_sel_hi:[0,1,1]
	v_pk_fma_f32 v[52:53], s[32:33], v[8:9], v[52:53] op_sel_hi:[0,1,1]
	v_pk_fma_f32 v[54:55], s[32:33], v[10:11], v[54:55] op_sel_hi:[0,1,1]
	v_cvt_scalef32_pk_f32_fp4 v[4:5], v109, 1.0
	v_cvt_scalef32_pk_f32_fp4 v[6:7], v109, 1.0 op_sel:[1,0,0]
	v_cvt_scalef32_pk_f32_fp4 v[8:9], v109, 1.0 op_sel:[0,1,0]
	v_cvt_scalef32_pk_f32_fp4 v[10:11], v109, 1.0 op_sel:[1,1,0]
	v_pk_fma_f32 v[56:57], s[32:33], v[4:5], v[56:57] op_sel_hi:[0,1,1]
	v_pk_fma_f32 v[58:59], s[32:33], v[6:7], v[58:59] op_sel_hi:[0,1,1]
	v_pk_fma_f32 v[50:51], s[32:33], v[8:9], v[50:51] op_sel_hi:[0,1,1]
	v_pk_fma_f32 v[48:49], s[32:33], v[10:11], v[48:49] op_sel_hi:[0,1,1]
	v_readlane_b32 s29, v12, 62
	s_add_u32 s24, s14, s29
	s_addc_u32 s25, s15, 0
	global_load_dwordx2 v[108:109], v213, s[24:25]
	v_readlane_b32 s34, v14, 47
	v_cvt_scalef32_pk_f32_fp4 v[4:5], v110, 1.0
	v_cvt_scalef32_pk_f32_fp4 v[6:7], v110, 1.0 op_sel:[1,0,0]
	v_cvt_scalef32_pk_f32_fp4 v[8:9], v110, 1.0 op_sel:[0,1,0]
	v_cvt_scalef32_pk_f32_fp4 v[10:11], v110, 1.0 op_sel:[1,1,0]
	v_pk_fma_f32 v[62:63], s[34:35], v[4:5], v[62:63] op_sel_hi:[0,1,1]
	v_pk_fma_f32 v[60:61], s[34:35], v[6:7], v[60:61] op_sel_hi:[0,1,1]
	v_pk_fma_f32 v[52:53], s[34:35], v[8:9], v[52:53] op_sel_hi:[0,1,1]
	v_pk_fma_f32 v[54:55], s[34:35], v[10:11], v[54:55] op_sel_hi:[0,1,1]
	v_cvt_scalef32_pk_f32_fp4 v[4:5], v111, 1.0
	v_cvt_scalef32_pk_f32_fp4 v[6:7], v111, 1.0 op_sel:[1,0,0]
	v_cvt_scalef32_pk_f32_fp4 v[8:9], v111, 1.0 op_sel:[0,1,0]
	v_cvt_scalef32_pk_f32_fp4 v[10:11], v111, 1.0 op_sel:[1,1,0]
	v_pk_fma_f32 v[56:57], s[34:35], v[4:5], v[56:57] op_sel_hi:[0,1,1]
	v_pk_fma_f32 v[58:59], s[34:35], v[6:7], v[58:59] op_sel_hi:[0,1,1]
	v_pk_fma_f32 v[50:51], s[34:35], v[8:9], v[50:51] op_sel_hi:[0,1,1]
	v_pk_fma_f32 v[48:49], s[34:35], v[10:11], v[48:49] op_sel_hi:[0,1,1]
	v_readlane_b32 s30, v12, 63
	s_add_u32 s26, s14, s30
	s_addc_u32 s27, s15, 0
	global_load_dwordx2 v[110:111], v213, s[26:27]
	s_waitcnt vmcnt(12)
; __device__ void peer_v(const P& p, int layer, int tok, bool dry) {
;     ...
; #pragma unroll
;   for (int h2 = 0; h2 < 2; ++h2) {
;     for (int jb = 0; jb < 64; jb += 16) {
;       u32x2 vv[16];
; #pragma unroll
;       for (int q = 0; q < 16; ++q) {
;         const int e = __builtin_amdgcn_readlane(eidx[h2], jb + q);
;         vv[q] = ((const u32x2*)(V4 + (size_t)e * 512))[lane];
;       }
; #pragma unroll
;       for (int q = 0; q < 16; ++q) {
;         const float wq = rdlane_f(wreg[h2], jb + q);
;         const f32x2 w2 = {wq, wq};
; #pragma unroll
;         for (int k = 0; k < 2; ++k) {
;           oa2[4 * k + 0] += w2 * __builtin_amdgcn_cvt_scalef32_pk_f32_fp4(vv[q][k], 1.0f, 0);
;           oa2[4 * k + 1] += w2 * __builtin_amdgcn_cvt_scalef32_pk_f32_fp4(vv[q][k], 1.0f, 1);
;           oa2[4 * k + 2] += w2 * __builtin_amdgcn_cvt_scalef32_pk_f32_fp4(vv[q][k], 1.0f, 2);
;           oa2[4 * k + 3] += w2 * __builtin_amdgcn_cvt_scalef32_pk_f32_fp4(vv[q][k], 1.0f, 3);
;         }
;       }
	v_readlane_b32 s32, v14, 48
	v_cvt_scalef32_pk_f32_fp4 v[4:5], v80, 1.0
	v_cvt_scalef32_pk_f32_fp4 v[6:7], v80, 1.0 op_sel:[1,0,0]
	v_cvt_scalef32_pk_f32_fp4 v[8:9], v80, 1.0 op_sel:[0,1,0]
	v_cvt_scalef32_pk_f32_fp4 v[10:11], v80, 1.0 op_sel:[1,1,0]
	v_pk_fma_f32 v[62:63], s[32:33], v[4:5], v[62:63] op_sel_hi:[0,1,1]
	v_pk_fma_f32 v[60:61], s[32:33], v[6:7], v[60:61] op_sel_hi:[0,1,1]
	v_pk_fma_f32 v[52:53], s[32:33], v[8:9], v[52:53] op_sel_hi:[0,1,1]
	v_pk_fma_f32 v[54:55], s[32:33], v[10:11], v[54:55] op_sel_hi:[0,1,1]
	v_cvt_scalef32_pk_f32_fp4 v[4:5], v81, 1.0
	v_cvt_scalef32_pk_f32_fp4 v[6:7], v81, 1.0 op_sel:[1,0,0]
	v_cvt_scalef32_pk_f32_fp4 v[8:9], v81, 1.0 op_sel:[0,1,0]
	v_cvt_scalef32_pk_f32_fp4 v[10:11], v81, 1.0 op_sel:[1,1,0]
	v_pk_fma_f32 v[56:57], s[32:33], v[4:5], v[56:57] op_sel_hi:[0,1,1]
	v_pk_fma_f32 v[58:59], s[32:33], v[6:7], v[58:59] op_sel_hi:[0,1,1]
	v_pk_fma_f32 v[50:51], s[32:33], v[8:9], v[50:51] op_sel_hi:[0,1,1]
	v_pk_fma_f32 v[48:49], s[32:33], v[10:11], v[48:49] op_sel_hi:[0,1,1]
	v_lshlrev_b32_e32 v13, 9, v13
	s_nop 0
	v_readlane_b32 s22, v13, 0
	s_add_u32 s16, s14, s22
	s_addc_u32 s17, s15, 0
	global_load_dwordx2 v[80:81], v213, s[16:17]
	v_readlane_b32 s34, v14, 49
	v_cvt_scalef32_pk_f32_fp4 v[4:5], v82, 1.0
	v_cvt_scalef32_pk_f32_fp4 v[6:7], v82, 1.0 op_sel:[1,0,0]
	v_cvt_scalef32_pk_f32_fp4 v[8:9], v82, 1.0 op_sel:[0,1,0]
	v_cvt_scalef32_pk_f32_fp4 v[10:11], v82, 1.0 op_sel:[1,1,0]
	v_pk_fma_f32 v[62:63], s[34:35], v[4:5], v[62:63] op_sel_hi:[0,1,1]
	v_pk_fma_f32 v[60:61], s[34:35], v[6:7], v[60:61] op_sel_hi:[0,1,1]
	v_pk_fma_f32 v[52:53], s[34:35], v[8:9], v[52:53] op_sel_hi:[0,1,1]
	v_pk_fma_f32 v[54:55], s[34:35], v[10:11], v[54:55] op_sel_hi:[0,1,1]
	v_cvt_scalef32_pk_f32_fp4 v[4:5], v83, 1.0
	v_cvt_scalef32_pk_f32_fp4 v[6:7], v83, 1.0 op_sel:[1,0,0]
	v_cvt_scalef32_pk_f32_fp4 v[8:9], v83, 1.0 op_sel:[0,1,0]
	v_cvt_scalef32_pk_f32_fp4 v[10:11], v83, 1.0 op_sel:[1,1,0]
	v_pk_fma_f32 v[56:57], s[34:35], v[4:5], v[56:57] op_sel_hi:[0,1,1]
	v_pk_fma_f32 v[58:59], s[34:35], v[6:7], v[58:59] op_sel_hi:[0,1,1]
	v_pk_fma_f32 v[50:51], s[34:35], v[8:9], v[50:51] op_sel_hi:[0,1,1]
	v_pk_fma_f32 v[48:49], s[34:35], v[10:11], v[48:49] op_sel_hi:[0,1,1]
	v_readlane_b32 s28, v13, 1
	s_add_u32 s20, s14, s28
	s_addc_u32 s21, s15, 0
	global_load_dwordx2 v[82:83], v213, s[20:21]
	v_readlane_b32 s32, v14, 50
	v_cvt_scalef32_pk_f32_fp4 v[4:5], v84, 1.0
	v_cvt_scalef32_pk_f32_fp4 v[6:7], v84, 1.0 op_sel:[1,0,0]
	v_cvt_scalef32_pk_f32_fp4 v[8:9], v84, 1.0 op_sel:[0,1,0]
	v_cvt_scalef32_pk_f32_fp4 v[10:11], v84, 1.0 op_sel:[1,1,0]
	v_pk_fma_f32 v[62:63], s[32:33], v[4:5], v[62:63] op_sel_hi:[0,1,1]
	v_pk_fma_f32 v[60:61], s[32:33], v[6:7], v[60:61] op_sel_hi:[0,1,1]
	v_pk_fma_f32 v[52:53], s[32:33], v[8:9], v[52:53] op_sel_hi:[0,1,1]
	v_pk_fma_f32 v[54:55], s[32:33], v[10:11], v[54:55] op_sel_hi:[0,1,1]
	v_cvt_scalef32_pk_f32_fp4 v[4:5], v85, 1.0
	v_cvt_scalef32_pk_f32_fp4 v[6:7], v85, 1.0 op_sel:[1,0,0]
	v_cvt_scalef32_pk_f32_fp4 v[8:9], v85, 1.0 op_sel:[0,1,0]
	v_cvt_scalef32_pk_f32_fp4 v[10:11], v85, 1.0 op_sel:[1,1,0]
	v_pk_fma_f32 v[56:57], s[32:33], v[4:5], v[56:57] op_sel_hi:[0,1,1]
	v_pk_fma_f32 v[58:59], s[32:33], v[6:7], v[58:59] op_sel_hi:[0,1,1]
	v_pk_fma_f32 v[50:51], s[32:33], v[8:9], v[50:51] op_sel_hi:[0,1,1]
	v_pk_fma_f32 v[48:49], s[32:33], v[10:11], v[48:49] op_sel_hi:[0,1,1]
	v_readlane_b32 s29, v13, 2
	s_add_u32 s24, s14, s29
	s_addc_u32 s25, s15, 0
	global_load_dwordx2 v[84:85], v213, s[24:25]
	v_readlane_b32 s34, v14, 51
	v_cvt_scalef32_pk_f32_fp4 v[4:5], v86, 1.0
	v_cvt_scalef32_pk_f32_fp4 v[6:7], v86, 1.0 op_sel:[1,0,0]
	v_cvt_scalef32_pk_f32_fp4 v[8:9], v86, 1.0 op_sel:[0,1,0]
	v_cvt_scalef32_pk_f32_fp4 v[10:11], v86, 1.0 op_sel:[1,1,0]
	v_pk_fma_f32 v[62:63], s[34:35], v[4:5], v[62:63] op_sel_hi:[0,1,1]
	v_pk_fma_f32 v[60:61], s[34:35], v[6:7], v[60:61] op_sel_hi:[0,1,1]
	v_pk_fma_f32 v[52:53], s[34:35], v[8:9], v[52:53] op_sel_hi:[0,1,1]
	v_pk_fma_f32 v[54:55], s[34:35], v[10:11], v[54:55] op_sel_hi:[0,1,1]
	v_cvt_scalef32_pk_f32_fp4 v[4:5], v87, 1.0
	v_cvt_scalef32_pk_f32_fp4 v[6:7], v87, 1.0 op_sel:[1,0,0]
	v_cvt_scalef32_pk_f32_fp4 v[8:9], v87, 1.0 op_sel:[0,1,0]
	v_cvt_scalef32_pk_f32_fp4 v[10:11], v87, 1.0 op_sel:[1,1,0]
	v_pk_fma_f32 v[56:57], s[34:35], v[4:5], v[56:57] op_sel_hi:[0,1,1]
	v_pk_fma_f32 v[58:59], s[34:35], v[6:7], v[58:59] op_sel_hi:[0,1,1]
	v_pk_fma_f32 v[50:51], s[34:35], v[8:9], v[50:51] op_sel_hi:[0,1,1]
	v_pk_fma_f32 v[48:49], s[34:35], v[10:11], v[48:49] op_sel_hi:[0,1,1]
	v_readlane_b32 s30, v13, 3
	s_add_u32 s26, s14, s30
	s_addc_u32 s27, s15, 0
	global_load_dwordx2 v[86:87], v213, s[26:27]
	s_waitcnt vmcnt(12)
; __device__ void peer_v(const P& p, int layer, int tok, bool dry) {
;     ...
;     for (int jb = 0; jb < 64; jb += 16) {
;       u32x2 vv[16];
; #pragma unroll
;       for (int q = 0; q < 16; ++q) {
;         const int e = __builtin_amdgcn_readlane(eidx[h2], jb + q);
;         vv[q] = ((const u32x2*)(V4 + (size_t)e * 512))[lane];
;       }
; #pragma unroll
;       for (int q = 0; q < 16; ++q) {
;         const float wq = rdlane_f(wreg[h2], jb + q);
;         const f32x2 w2 = {wq, wq};
; #pragma unroll
;         for (int k = 0; k < 2; ++k) {
;           oa2[4 * k + 0] += w2 * __builtin_amdgcn_cvt_scalef32_pk_f32_fp4(vv[q][k], 1.0f, 0);
;           oa2[4 * k + 1] += w2 * __builtin_amdgcn_cvt_scalef32_pk_f32_fp4(vv[q][k], 1.0f, 1);
;           oa2[4 * k + 2] += w2 * __builtin_amdgcn_cvt_scalef32_pk_f32_fp4(vv[q][k], 1.0f, 2);
;           oa2[4 * k + 3] += w2 * __builtin_amdgcn_cvt_scalef32_pk_f32_fp4(vv[q][k], 1.0f, 3);
;         }
;       }
	v_readlane_b32 s32, v14, 52
	v_cvt_scalef32_pk_f32_fp4 v[4:5], v88, 1.0
	v_cvt_scalef32_pk_f32_fp4 v[6:7], v88, 1.0 op_sel:[1,0,0]
	v_cvt_scalef32_pk_f32_fp4 v[8:9], v88, 1.0 op_sel:[0,1,0]
	v_cvt_scalef32_pk_f32_fp4 v[10:11], v88, 1.0 op_sel:[1,1,0]
	v_pk_fma_f32 v[62:63], s[32:33], v[4:5], v[62:63] op_sel_hi:[0,1,1]
	v_pk_fma_f32 v[60:61], s[32:33], v[6:7], v[60:61] op_sel_hi:[0,1,1]
	v_pk_fma_f32 v[52:53], s[32:33], v[8:9], v[52:53] op_sel_hi:[0,1,1]
	v_pk_fma_f32 v[54:55], s[32:33], v[10:11], v[54:55] op_sel_hi:[0,1,1]
	v_cvt_scalef32_pk_f32_fp4 v[4:5], v89, 1.0
	v_cvt_scalef32_pk_f32_fp4 v[6:7], v89, 1.0 op_sel:[1,0,0]
	v_cvt_scalef32_pk_f32_fp4 v[8:9], v89, 1.0 op_sel:[0,1,0]
	v_cvt_scalef32_pk_f32_fp4 v[10:11], v89, 1.0 op_sel:[1,1,0]
	v_pk_fma_f32 v[56:57], s[32:33], v[4:5], v[56:57] op_sel_hi:[0,1,1]
	v_pk_fma_f32 v[58:59], s[32:33], v[6:7], v[58:59] op_sel_hi:[0,1,1]
	v_pk_fma_f32 v[50:51], s[32:33], v[8:9], v[50:51] op_sel_hi:[0,1,1]
	v_pk_fma_f32 v[48:49], s[32:33], v[10:11], v[48:49] op_sel_hi:[0,1,1]
	v_readlane_b32 s22, v13, 4
	s_add_u32 s16, s14, s22
	s_addc_u32 s17, s15, 0
	global_load_dwordx2 v[88:89], v213, s[16:17]
	v_readlane_b32 s34, v14, 53
	v_cvt_scalef32_pk_f32_fp4 v[4:5], v90, 1.0
	v_cvt_scalef32_pk_f32_fp4 v[6:7], v90, 1.0 op_sel:[1,0,0]
	v_cvt_scalef32_pk_f32_fp4 v[8:9], v90, 1.0 op_sel:[0,1,0]
	v_cvt_scalef32_pk_f32_fp4 v[10:11], v90, 1.0 op_sel:[1,1,0]
	v_pk_fma_f32 v[62:63], s[34:35], v[4:5], v[62:63] op_sel_hi:[0,1,1]
	v_pk_fma_f32 v[60:61], s[34:35], v[6:7], v[60:61] op_sel_hi:[0,1,1]
	v_pk_fma_f32 v[52:53], s[34:35], v[8:9], v[52:53] op_sel_hi:[0,1,1]
	v_pk_fma_f32 v[54:55], s[34:35], v[10:11], v[54:55] op_sel_hi:[0,1,1]
	v_cvt_scalef32_pk_f32_fp4 v[4:5], v91, 1.0
	v_cvt_scalef32_pk_f32_fp4 v[6:7], v91, 1.0 op_sel:[1,0,0]
	v_cvt_scalef32_pk_f32_fp4 v[8:9], v91, 1.0 op_sel:[0,1,0]
	v_cvt_scalef32_pk_f32_fp4 v[10:11], v91, 1.0 op_sel:[1,1,0]
	v_pk_fma_f32 v[56:57], s[34:35], v[4:5], v[56:57] op_sel_hi:[0,1,1]
	v_pk_fma_f32 v[58:59], s[34:35], v[6:7], v[58:59] op_sel_hi:[0,1,1]
	v_pk_fma_f32 v[50:51], s[34:35], v[8:9], v[50:51] op_sel_hi:[0,1,1]
	v_pk_fma_f32 v[48:49], s[34:35], v[10:11], v[48:49] op_sel_hi:[0,1,1]
	v_readlane_b32 s28, v13, 5
	s_add_u32 s20, s14, s28
	s_addc_u32 s21, s15, 0
	global_load_dwordx2 v[90:91], v213, s[20:21]
	v_readlane_b32 s32, v14, 54
	v_cvt_scalef32_pk_f32_fp4 v[4:5], v92, 1.0
	v_cvt_scalef32_pk_f32_fp4 v[6:7], v92, 1.0 op_sel:[1,0,0]
	v_cvt_scalef32_pk_f32_fp4 v[8:9], v92, 1.0 op_sel:[0,1,0]
	v_cvt_scalef32_pk_f32_fp4 v[10:11], v92, 1.0 op_sel:[1,1,0]
	v_pk_fma_f32 v[62:63], s[32:33], v[4:5], v[62:63] op_sel_hi:[0,1,1]
	v_pk_fma_f32 v[60:61], s[32:33], v[6:7], v[60:61] op_sel_hi:[0,1,1]
	v_pk_fma_f32 v[52:53], s[32:33], v[8:9], v[52:53] op_sel_hi:[0,1,1]
	v_pk_fma_f32 v[54:55], s[32:33], v[10:11], v[54:55] op_sel_hi:[0,1,1]
	v_cvt_scalef32_pk_f32_fp4 v[4:5], v93, 1.0
	v_cvt_scalef32_pk_f32_fp4 v[6:7], v93, 1.0 op_sel:[1,0,0]
	v_cvt_scalef32_pk_f32_fp4 v[8:9], v93, 1.0 op_sel:[0,1,0]
	v_cvt_scalef32_pk_f32_fp4 v[10:11], v93, 1.0 op_sel:[1,1,0]
	v_pk_fma_f32 v[56:57], s[32:33], v[4:5], v[56:57] op_sel_hi:[0,1,1]
	v_pk_fma_f32 v[58:59], s[32:33], v[6:7], v[58:59] op_sel_hi:[0,1,1]
	v_pk_fma_f32 v[50:51], s[32:33], v[8:9], v[50:51] op_sel_hi:[0,1,1]
	v_pk_fma_f32 v[48:49], s[32:33], v[10:11], v[48:49] op_sel_hi:[0,1,1]
	v_readlane_b32 s29, v13, 6
	s_add_u32 s24, s14, s29
	s_addc_u32 s25, s15, 0
	global_load_dwordx2 v[92:93], v213, s[24:25]
	v_readlane_b32 s34, v14, 55
	v_cvt_scalef32_pk_f32_fp4 v[4:5], v94, 1.0
	v_cvt_scalef32_pk_f32_fp4 v[6:7], v94, 1.0 op_sel:[1,0,0]
	v_cvt_scalef32_pk_f32_fp4 v[8:9], v94, 1.0 op_sel:[0,1,0]
	v_cvt_scalef32_pk_f32_fp4 v[10:11], v94, 1.0 op_sel:[1,1,0]
	v_pk_fma_f32 v[62:63], s[34:35], v[4:5], v[62:63] op_sel_hi:[0,1,1]
	v_pk_fma_f32 v[60:61], s[34:35], v[6:7], v[60:61] op_sel_hi:[0,1,1]
	v_pk_fma_f32 v[52:53], s[34:35], v[8:9], v[52:53] op_sel_hi:[0,1,1]
	v_pk_fma_f32 v[54:55], s[34:35], v[10:11], v[54:55] op_sel_hi:[0,1,1]
	v_cvt_scalef32_pk_f32_fp4 v[4:5], v95, 1.0
	v_cvt_scalef32_pk_f32_fp4 v[6:7], v95, 1.0 op_sel:[1,0,0]
	v_cvt_scalef32_pk_f32_fp4 v[8:9], v95, 1.0 op_sel:[0,1,0]
	v_cvt_scalef32_pk_f32_fp4 v[10:11], v95, 1.0 op_sel:[1,1,0]
	v_pk_fma_f32 v[56:57], s[34:35], v[4:5], v[56:57] op_sel_hi:[0,1,1]
	v_pk_fma_f32 v[58:59], s[34:35], v[6:7], v[58:59] op_sel_hi:[0,1,1]
	v_pk_fma_f32 v[50:51], s[34:35], v[8:9], v[50:51] op_sel_hi:[0,1,1]
	v_pk_fma_f32 v[48:49], s[34:35], v[10:11], v[48:49] op_sel_hi:[0,1,1]
	v_readlane_b32 s30, v13, 7
	s_add_u32 s26, s14, s30
	s_addc_u32 s27, s15, 0
	global_load_dwordx2 v[94:95], v213, s[26:27]
	s_waitcnt vmcnt(12)
; __device__ void peer_v(const P& p, int layer, int tok, bool dry) {
;     ...
;     for (int jb = 0; jb < 64; jb += 16) {
;       u32x2 vv[16];
; #pragma unroll
;       for (int q = 0; q < 16; ++q) {
;         const int e = __builtin_amdgcn_readlane(eidx[h2], jb + q);
;         vv[q] = ((const u32x2*)(V4 + (size_t)e * 512))[lane];
;       }
; #pragma unroll
;       for (int q = 0; q < 16; ++q) {
;         const float wq = rdlane_f(wreg[h2], jb + q);
;         const f32x2 w2 = {wq, wq};
; #pragma unroll
;         for (int k = 0; k < 2; ++k) {
;           oa2[4 * k + 0] += w2 * __builtin_amdgcn_cvt_scalef32_pk_f32_fp4(vv[q][k], 1.0f, 0);
;           oa2[4 * k + 1] += w2 * __builtin_amdgcn_cvt_scalef32_pk_f32_fp4(vv[q][k], 1.0f, 1);
;           oa2[4 * k + 2] += w2 * __builtin_amdgcn_cvt_scalef32_pk_f32_fp4(vv[q][k], 1.0f, 2);
;           oa2[4 * k + 3] += w2 * __builtin_amdgcn_cvt_scalef32_pk_f32_fp4(vv[q][k], 1.0f, 3);
;         }
;       }
	v_readlane_b32 s32, v14, 56
	v_cvt_scalef32_pk_f32_fp4 v[4:5], v96, 1.0
	v_cvt_scalef32_pk_f32_fp4 v[6:7], v96, 1.0 op_sel:[1,0,0]
	v_cvt_scalef32_pk_f32_fp4 v[8:9], v96, 1.0 op_sel:[0,1,0]
	v_cvt_scalef32_pk_f32_fp4 v[10:11], v96, 1.0 op_sel:[1,1,0]
	v_pk_fma_f32 v[62:63], s[32:33], v[4:5], v[62:63] op_sel_hi:[0,1,1]
	v_pk_fma_f32 v[60:61], s[32:33], v[6:7], v[60:61] op_sel_hi:[0,1,1]
	v_pk_fma_f32 v[52:53], s[32:33], v[8:9], v[52:53] op_sel_hi:[0,1,1]
	v_pk_fma_f32 v[54:55], s[32:33], v[10:11], v[54:55] op_sel_hi:[0,1,1]
	v_cvt_scalef32_pk_f32_fp4 v[4:5], v97, 1.0
	v_cvt_scalef32_pk_f32_fp4 v[6:7], v97, 1.0 op_sel:[1,0,0]
	v_cvt_scalef32_pk_f32_fp4 v[8:9], v97, 1.0 op_sel:[0,1,0]
	v_cvt_scalef32_pk_f32_fp4 v[10:11], v97, 1.0 op_sel:[1,1,0]
	v_pk_fma_f32 v[56:57], s[32:33], v[4:5], v[56:57] op_sel_hi:[0,1,1]
	v_pk_fma_f32 v[58:59], s[32:33], v[6:7], v[58:59] op_sel_hi:[0,1,1]
	v_pk_fma_f32 v[50:51], s[32:33], v[8:9], v[50:51] op_sel_hi:[0,1,1]
	v_pk_fma_f32 v[48:49], s[32:33], v[10:11], v[48:49] op_sel_hi:[0,1,1]
	v_readlane_b32 s22, v13, 8
	s_add_u32 s16, s14, s22
	s_addc_u32 s17, s15, 0
	global_load_dwordx2 v[96:97], v213, s[16:17]
	v_readlane_b32 s34, v14, 57
	v_cvt_scalef32_pk_f32_fp4 v[4:5], v98, 1.0
	v_cvt_scalef32_pk_f32_fp4 v[6:7], v98, 1.0 op_sel:[1,0,0]
	v_cvt_scalef32_pk_f32_fp4 v[8:9], v98, 1.0 op_sel:[0,1,0]
	v_cvt_scalef32_pk_f32_fp4 v[10:11], v98, 1.0 op_sel:[1,1,0]
	v_pk_fma_f32 v[62:63], s[34:35], v[4:5], v[62:63] op_sel_hi:[0,1,1]
	v_pk_fma_f32 v[60:61], s[34:35], v[6:7], v[60:61] op_sel_hi:[0,1,1]
	v_pk_fma_f32 v[52:53], s[34:35], v[8:9], v[52:53] op_sel_hi:[0,1,1]
	v_pk_fma_f32 v[54:55], s[34:35], v[10:11], v[54:55] op_sel_hi:[0,1,1]
	v_cvt_scalef32_pk_f32_fp4 v[4:5], v99, 1.0
	v_cvt_scalef32_pk_f32_fp4 v[6:7], v99, 1.0 op_sel:[1,0,0]
	v_cvt_scalef32_pk_f32_fp4 v[8:9], v99, 1.0 op_sel:[0,1,0]
	v_cvt_scalef32_pk_f32_fp4 v[10:11], v99, 1.0 op_sel:[1,1,0]
	v_pk_fma_f32 v[56:57], s[34:35], v[4:5], v[56:57] op_sel_hi:[0,1,1]
	v_pk_fma_f32 v[58:59], s[34:35], v[6:7], v[58:59] op_sel_hi:[0,1,1]
	v_pk_fma_f32 v[50:51], s[34:35], v[8:9], v[50:51] op_sel_hi:[0,1,1]
	v_pk_fma_f32 v[48:49], s[34:35], v[10:11], v[48:49] op_sel_hi:[0,1,1]
	v_readlane_b32 s28, v13, 9
	s_add_u32 s20, s14, s28
	s_addc_u32 s21, s15, 0
	global_load_dwordx2 v[98:99], v213, s[20:21]
	v_readlane_b32 s32, v14, 58
	v_cvt_scalef32_pk_f32_fp4 v[4:5], v100, 1.0
	v_cvt_scalef32_pk_f32_fp4 v[6:7], v100, 1.0 op_sel:[1,0,0]
	v_cvt_scalef32_pk_f32_fp4 v[8:9], v100, 1.0 op_sel:[0,1,0]
	v_cvt_scalef32_pk_f32_fp4 v[10:11], v100, 1.0 op_sel:[1,1,0]
	v_pk_fma_f32 v[62:63], s[32:33], v[4:5], v[62:63] op_sel_hi:[0,1,1]
	v_pk_fma_f32 v[60:61], s[32:33], v[6:7], v[60:61] op_sel_hi:[0,1,1]
	v_pk_fma_f32 v[52:53], s[32:33], v[8:9], v[52:53] op_sel_hi:[0,1,1]
	v_pk_fma_f32 v[54:55], s[32:33], v[10:11], v[54:55] op_sel_hi:[0,1,1]
	v_cvt_scalef32_pk_f32_fp4 v[4:5], v101, 1.0
	v_cvt_scalef32_pk_f32_fp4 v[6:7], v101, 1.0 op_sel:[1,0,0]
	v_cvt_scalef32_pk_f32_fp4 v[8:9], v101, 1.0 op_sel:[0,1,0]
	v_cvt_scalef32_pk_f32_fp4 v[10:11], v101, 1.0 op_sel:[1,1,0]
	v_pk_fma_f32 v[56:57], s[32:33], v[4:5], v[56:57] op_sel_hi:[0,1,1]
	v_pk_fma_f32 v[58:59], s[32:33], v[6:7], v[58:59] op_sel_hi:[0,1,1]
	v_pk_fma_f32 v[50:51], s[32:33], v[8:9], v[50:51] op_sel_hi:[0,1,1]
	v_pk_fma_f32 v[48:49], s[32:33], v[10:11], v[48:49] op_sel_hi:[0,1,1]
	v_readlane_b32 s29, v13, 10
	s_add_u32 s24, s14, s29
	s_addc_u32 s25, s15, 0
	global_load_dwordx2 v[100:101], v213, s[24:25]
	v_readlane_b32 s34, v14, 59
	v_cvt_scalef32_pk_f32_fp4 v[4:5], v102, 1.0
	v_cvt_scalef32_pk_f32_fp4 v[6:7], v102, 1.0 op_sel:[1,0,0]
	v_cvt_scalef32_pk_f32_fp4 v[8:9], v102, 1.0 op_sel:[0,1,0]
	v_cvt_scalef32_pk_f32_fp4 v[10:11], v102, 1.0 op_sel:[1,1,0]
	v_pk_fma_f32 v[62:63], s[34:35], v[4:5], v[62:63] op_sel_hi:[0,1,1]
	v_pk_fma_f32 v[60:61], s[34:35], v[6:7], v[60:61] op_sel_hi:[0,1,1]
	v_pk_fma_f32 v[52:53], s[34:35], v[8:9], v[52:53] op_sel_hi:[0,1,1]
	v_pk_fma_f32 v[54:55], s[34:35], v[10:11], v[54:55] op_sel_hi:[0,1,1]
	v_cvt_scalef32_pk_f32_fp4 v[4:5], v103, 1.0
	v_cvt_scalef32_pk_f32_fp4 v[6:7], v103, 1.0 op_sel:[1,0,0]
	v_cvt_scalef32_pk_f32_fp4 v[8:9], v103, 1.0 op_sel:[0,1,0]
	v_cvt_scalef32_pk_f32_fp4 v[10:11], v103, 1.0 op_sel:[1,1,0]
	v_pk_fma_f32 v[56:57], s[34:35], v[4:5], v[56:57] op_sel_hi:[0,1,1]
	v_pk_fma_f32 v[58:59], s[34:35], v[6:7], v[58:59] op_sel_hi:[0,1,1]
	v_pk_fma_f32 v[50:51], s[34:35], v[8:9], v[50:51] op_sel_hi:[0,1,1]
	v_pk_fma_f32 v[48:49], s[34:35], v[10:11], v[48:49] op_sel_hi:[0,1,1]
	v_readlane_b32 s30, v13, 11
	s_add_u32 s26, s14, s30
	s_addc_u32 s27, s15, 0
	global_load_dwordx2 v[102:103], v213, s[26:27]
	s_waitcnt vmcnt(12)
; __device__ void peer_v(const P& p, int layer, int tok, bool dry) {
;     ...
;     for (int jb = 0; jb < 64; jb += 16) {
;       u32x2 vv[16];
; #pragma unroll
;       for (int q = 0; q < 16; ++q) {
;         const int e = __builtin_amdgcn_readlane(eidx[h2], jb + q);
;         vv[q] = ((const u32x2*)(V4 + (size_t)e * 512))[lane];
;       }
; #pragma unroll
;       for (int q = 0; q < 16; ++q) {
;         const float wq = rdlane_f(wreg[h2], jb + q);
;         const f32x2 w2 = {wq, wq};
; #pragma unroll
;         for (int k = 0; k < 2; ++k) {
;           oa2[4 * k + 0] += w2 * __builtin_amdgcn_cvt_scalef32_pk_f32_fp4(vv[q][k], 1.0f, 0);
;           oa2[4 * k + 1] += w2 * __builtin_amdgcn_cvt_scalef32_pk_f32_fp4(vv[q][k], 1.0f, 1);
;           oa2[4 * k + 2] += w2 * __builtin_amdgcn_cvt_scalef32_pk_f32_fp4(vv[q][k], 1.0f, 2);
;           oa2[4 * k + 3] += w2 * __builtin_amdgcn_cvt_scalef32_pk_f32_fp4(vv[q][k], 1.0f, 3);
;         }
;       }
	v_readlane_b32 s32, v14, 60
	v_cvt_scalef32_pk_f32_fp4 v[4:5], v104, 1.0
	v_cvt_scalef32_pk_f32_fp4 v[6:7], v104, 1.0 op_sel:[1,0,0]
	v_cvt_scalef32_pk_f32_fp4 v[8:9], v104, 1.0 op_sel:[0,1,0]
	v_cvt_scalef32_pk_f32_fp4 v[10:11], v104, 1.0 op_sel:[1,1,0]
	v_pk_fma_f32 v[62:63], s[32:33], v[4:5], v[62:63] op_sel_hi:[0,1,1]
	v_pk_fma_f32 v[60:61], s[32:33], v[6:7], v[60:61] op_sel_hi:[0,1,1]
	v_pk_fma_f32 v[52:53], s[32:33], v[8:9], v[52:53] op_sel_hi:[0,1,1]
	v_pk_fma_f32 v[54:55], s[32:33], v[10:11], v[54:55] op_sel_hi:[0,1,1]
	v_cvt_scalef32_pk_f32_fp4 v[4:5], v105, 1.0
	v_cvt_scalef32_pk_f32_fp4 v[6:7], v105, 1.0 op_sel:[1,0,0]
	v_cvt_scalef32_pk_f32_fp4 v[8:9], v105, 1.0 op_sel:[0,1,0]
	v_cvt_scalef32_pk_f32_fp4 v[10:11], v105, 1.0 op_sel:[1,1,0]
	v_pk_fma_f32 v[56:57], s[32:33], v[4:5], v[56:57] op_sel_hi:[0,1,1]
	v_pk_fma_f32 v[58:59], s[32:33], v[6:7], v[58:59] op_sel_hi:[0,1,1]
	v_pk_fma_f32 v[50:51], s[32:33], v[8:9], v[50:51] op_sel_hi:[0,1,1]
	v_pk_fma_f32 v[48:49], s[32:33], v[10:11], v[48:49] op_sel_hi:[0,1,1]
	v_readlane_b32 s22, v13, 12
	s_add_u32 s16, s14, s22
	s_addc_u32 s17, s15, 0
	global_load_dwordx2 v[104:105], v213, s[16:17]
	v_readlane_b32 s34, v14, 61
	v_cvt_scalef32_pk_f32_fp4 v[4:5], v106, 1.0
	v_cvt_scalef32_pk_f32_fp4 v[6:7], v106, 1.0 op_sel:[1,0,0]
	v_cvt_scalef32_pk_f32_fp4 v[8:9], v106, 1.0 op_sel:[0,1,0]
	v_cvt_scalef32_pk_f32_fp4 v[10:11], v106, 1.0 op_sel:[1,1,0]
	v_pk_fma_f32 v[62:63], s[34:35], v[4:5], v[62:63] op_sel_hi:[0,1,1]
	v_pk_fma_f32 v[60:61], s[34:35], v[6:7], v[60:61] op_sel_hi:[0,1,1]
	v_pk_fma_f32 v[52:53], s[34:35], v[8:9], v[52:53] op_sel_hi:[0,1,1]
	v_pk_fma_f32 v[54:55], s[34:35], v[10:11], v[54:55] op_sel_hi:[0,1,1]
	v_cvt_scalef32_pk_f32_fp4 v[4:5], v107, 1.0
	v_cvt_scalef32_pk_f32_fp4 v[6:7], v107, 1.0 op_sel:[1,0,0]
	v_cvt_scalef32_pk_f32_fp4 v[8:9], v107, 1.0 op_sel:[0,1,0]
	v_cvt_scalef32_pk_f32_fp4 v[10:11], v107, 1.0 op_sel:[1,1,0]
	v_pk_fma_f32 v[56:57], s[34:35], v[4:5], v[56:57] op_sel_hi:[0,1,1]
	v_pk_fma_f32 v[58:59], s[34:35], v[6:7], v[58:59] op_sel_hi:[0,1,1]
	v_pk_fma_f32 v[50:51], s[34:35], v[8:9], v[50:51] op_sel_hi:[0,1,1]
	v_pk_fma_f32 v[48:49], s[34:35], v[10:11], v[48:49] op_sel_hi:[0,1,1]
	v_readlane_b32 s28, v13, 13
	s_add_u32 s20, s14, s28
	s_addc_u32 s21, s15, 0
	global_load_dwordx2 v[106:107], v213, s[20:21]
	v_readlane_b32 s32, v14, 62
	v_cvt_scalef32_pk_f32_fp4 v[4:5], v108, 1.0
	v_cvt_scalef32_pk_f32_fp4 v[6:7], v108, 1.0 op_sel:[1,0,0]
	v_cvt_scalef32_pk_f32_fp4 v[8:9], v108, 1.0 op_sel:[0,1,0]
	v_cvt_scalef32_pk_f32_fp4 v[10:11], v108, 1.0 op_sel:[1,1,0]
	v_pk_fma_f32 v[62:63], s[32:33], v[4:5], v[62:63] op_sel_hi:[0,1,1]
	v_pk_fma_f32 v[60:61], s[32:33], v[6:7], v[60:61] op_sel_hi:[0,1,1]
	v_pk_fma_f32 v[52:53], s[32:33], v[8:9], v[52:53] op_sel_hi:[0,1,1]
	v_pk_fma_f32 v[54:55], s[32:33], v[10:11], v[54:55] op_sel_hi:[0,1,1]
	v_cvt_scalef32_pk_f32_fp4 v[4:5], v109, 1.0
	v_cvt_scalef32_pk_f32_fp4 v[6:7], v109, 1.0 op_sel:[1,0,0]
	v_cvt_scalef32_pk_f32_fp4 v[8:9], v109, 1.0 op_sel:[0,1,0]
	v_cvt_scalef32_pk_f32_fp4 v[10:11], v109, 1.0 op_sel:[1,1,0]
	v_pk_fma_f32 v[56:57], s[32:33], v[4:5], v[56:57] op_sel_hi:[0,1,1]
	v_pk_fma_f32 v[58:59], s[32:33], v[6:7], v[58:59] op_sel_hi:[0,1,1]
	v_pk_fma_f32 v[50:51], s[32:33], v[8:9], v[50:51] op_sel_hi:[0,1,1]
	v_pk_fma_f32 v[48:49], s[32:33], v[10:11], v[48:49] op_sel_hi:[0,1,1]
	v_readlane_b32 s29, v13, 14
	s_add_u32 s24, s14, s29
	s_addc_u32 s25, s15, 0
	global_load_dwordx2 v[108:109], v213, s[24:25]
	v_readlane_b32 s34, v14, 63
	v_cvt_scalef32_pk_f32_fp4 v[4:5], v110, 1.0
	v_cvt_scalef32_pk_f32_fp4 v[6:7], v110, 1.0 op_sel:[1,0,0]
	v_cvt_scalef32_pk_f32_fp4 v[8:9], v110, 1.0 op_sel:[0,1,0]
	v_cvt_scalef32_pk_f32_fp4 v[10:11], v110, 1.0 op_sel:[1,1,0]
	v_pk_fma_f32 v[62:63], s[34:35], v[4:5], v[62:63] op_sel_hi:[0,1,1]
	v_pk_fma_f32 v[60:61], s[34:35], v[6:7], v[60:61] op_sel_hi:[0,1,1]
	v_pk_fma_f32 v[52:53], s[34:35], v[8:9], v[52:53] op_sel_hi:[0,1,1]
	v_pk_fma_f32 v[54:55], s[34:35], v[10:11], v[54:55] op_sel_hi:[0,1,1]
	v_cvt_scalef32_pk_f32_fp4 v[4:5], v111, 1.0
	v_cvt_scalef32_pk_f32_fp4 v[6:7], v111, 1.0 op_sel:[1,0,0]
	v_cvt_scalef32_pk_f32_fp4 v[8:9], v111, 1.0 op_sel:[0,1,0]
	v_cvt_scalef32_pk_f32_fp4 v[10:11], v111, 1.0 op_sel:[1,1,0]
	v_pk_fma_f32 v[56:57], s[34:35], v[4:5], v[56:57] op_sel_hi:[0,1,1]
	v_pk_fma_f32 v[58:59], s[34:35], v[6:7], v[58:59] op_sel_hi:[0,1,1]
	v_pk_fma_f32 v[50:51], s[34:35], v[8:9], v[50:51] op_sel_hi:[0,1,1]
	v_pk_fma_f32 v[48:49], s[34:35], v[10:11], v[48:49] op_sel_hi:[0,1,1]
	v_readlane_b32 s30, v13, 15
	s_add_u32 s26, s14, s30
	s_addc_u32 s27, s15, 0
	global_load_dwordx2 v[110:111], v213, s[26:27]
	s_waitcnt vmcnt(12)
; __device__ void peer_v(const P& p, int layer, int tok, bool dry) {
;     ...
;     for (int jb = 0; jb < 64; jb += 16) {
;       u32x2 vv[16];
; #pragma unroll
;       for (int q = 0; q < 16; ++q) {
;         const int e = __builtin_amdgcn_readlane(eidx[h2], jb + q);
;         vv[q] = ((const u32x2*)(V4 + (size_t)e * 512))[lane];
;       }
; #pragma unroll
;       for (int q = 0; q < 16; ++q) {
;         const float wq = rdlane_f(wreg[h2], jb + q);
;         const f32x2 w2 = {wq, wq};
; #pragma unroll
;         for (int k = 0; k < 2; ++k) {
;           oa2[4 * k + 0] += w2 * __builtin_amdgcn_cvt_scalef32_pk_f32_fp4(vv[q][k], 1.0f, 0);
;           oa2[4 * k + 1] += w2 * __builtin_amdgcn_cvt_scalef32_pk_f32_fp4(vv[q][k], 1.0f, 1);
;           oa2[4 * k + 2] += w2 * __builtin_amdgcn_cvt_scalef32_pk_f32_fp4(vv[q][k], 1.0f, 2);
;           oa2[4 * k + 3] += w2 * __builtin_amdgcn_cvt_scalef32_pk_f32_fp4(vv[q][k], 1.0f, 3);
;         }
;       }
	v_readlane_b32 s32, v15, 0
	v_cvt_scalef32_pk_f32_fp4 v[4:5], v80, 1.0
	v_cvt_scalef32_pk_f32_fp4 v[6:7], v80, 1.0 op_sel:[1,0,0]
	v_cvt_scalef32_pk_f32_fp4 v[8:9], v80, 1.0 op_sel:[0,1,0]
	v_cvt_scalef32_pk_f32_fp4 v[10:11], v80, 1.0 op_sel:[1,1,0]
	v_pk_fma_f32 v[62:63], s[32:33], v[4:5], v[62:63] op_sel_hi:[0,1,1]
	v_pk_fma_f32 v[60:61], s[32:33], v[6:7], v[60:61] op_sel_hi:[0,1,1]
	v_pk_fma_f32 v[52:53], s[32:33], v[8:9], v[52:53] op_sel_hi:[0,1,1]
	v_pk_fma_f32 v[54:55], s[32:33], v[10:11], v[54:55] op_sel_hi:[0,1,1]
	v_cvt_scalef32_pk_f32_fp4 v[4:5], v81, 1.0
	v_cvt_scalef32_pk_f32_fp4 v[6:7], v81, 1.0 op_sel:[1,0,0]
	v_cvt_scalef32_pk_f32_fp4 v[8:9], v81, 1.0 op_sel:[0,1,0]
	v_cvt_scalef32_pk_f32_fp4 v[10:11], v81, 1.0 op_sel:[1,1,0]
	v_pk_fma_f32 v[56:57], s[32:33], v[4:5], v[56:57] op_sel_hi:[0,1,1]
	v_pk_fma_f32 v[58:59], s[32:33], v[6:7], v[58:59] op_sel_hi:[0,1,1]
	v_pk_fma_f32 v[50:51], s[32:33], v[8:9], v[50:51] op_sel_hi:[0,1,1]
	v_pk_fma_f32 v[48:49], s[32:33], v[10:11], v[48:49] op_sel_hi:[0,1,1]
	v_readlane_b32 s22, v13, 16
	s_add_u32 s16, s14, s22
	s_addc_u32 s17, s15, 0
	global_load_dwordx2 v[80:81], v213, s[16:17]
	v_readlane_b32 s34, v15, 1
	v_cvt_scalef32_pk_f32_fp4 v[4:5], v82, 1.0
	v_cvt_scalef32_pk_f32_fp4 v[6:7], v82, 1.0 op_sel:[1,0,0]
	v_cvt_scalef32_pk_f32_fp4 v[8:9], v82, 1.0 op_sel:[0,1,0]
	v_cvt_scalef32_pk_f32_fp4 v[10:11], v82, 1.0 op_sel:[1,1,0]
	v_pk_fma_f32 v[62:63], s[34:35], v[4:5], v[62:63] op_sel_hi:[0,1,1]
	v_pk_fma_f32 v[60:61], s[34:35], v[6:7], v[60:61] op_sel_hi:[0,1,1]
	v_pk_fma_f32 v[52:53], s[34:35], v[8:9], v[52:53] op_sel_hi:[0,1,1]
	v_pk_fma_f32 v[54:55], s[34:35], v[10:11], v[54:55] op_sel_hi:[0,1,1]
	v_cvt_scalef32_pk_f32_fp4 v[4:5], v83, 1.0
	v_cvt_scalef32_pk_f32_fp4 v[6:7], v83, 1.0 op_sel:[1,0,0]
	v_cvt_scalef32_pk_f32_fp4 v[8:9], v83, 1.0 op_sel:[0,1,0]
	v_cvt_scalef32_pk_f32_fp4 v[10:11], v83, 1.0 op_sel:[1,1,0]
	v_pk_fma_f32 v[56:57], s[34:35], v[4:5], v[56:57] op_sel_hi:[0,1,1]
	v_pk_fma_f32 v[58:59], s[34:35], v[6:7], v[58:59] op_sel_hi:[0,1,1]
	v_pk_fma_f32 v[50:51], s[34:35], v[8:9], v[50:51] op_sel_hi:[0,1,1]
	v_pk_fma_f32 v[48:49], s[34:35], v[10:11], v[48:49] op_sel_hi:[0,1,1]
	v_readlane_b32 s28, v13, 17
	s_add_u32 s20, s14, s28
	s_addc_u32 s21, s15, 0
	global_load_dwordx2 v[82:83], v213, s[20:21]
	v_readlane_b32 s32, v15, 2
	v_cvt_scalef32_pk_f32_fp4 v[4:5], v84, 1.0
	v_cvt_scalef32_pk_f32_fp4 v[6:7], v84, 1.0 op_sel:[1,0,0]
	v_cvt_scalef32_pk_f32_fp4 v[8:9], v84, 1.0 op_sel:[0,1,0]
	v_cvt_scalef32_pk_f32_fp4 v[10:11], v84, 1.0 op_sel:[1,1,0]
	v_pk_fma_f32 v[62:63], s[32:33], v[4:5], v[62:63] op_sel_hi:[0,1,1]
	v_pk_fma_f32 v[60:61], s[32:33], v[6:7], v[60:61] op_sel_hi:[0,1,1]
	v_pk_fma_f32 v[52:53], s[32:33], v[8:9], v[52:53] op_sel_hi:[0,1,1]
	v_pk_fma_f32 v[54:55], s[32:33], v[10:11], v[54:55] op_sel_hi:[0,1,1]
	v_cvt_scalef32_pk_f32_fp4 v[4:5], v85, 1.0
	v_cvt_scalef32_pk_f32_fp4 v[6:7], v85, 1.0 op_sel:[1,0,0]
	v_cvt_scalef32_pk_f32_fp4 v[8:9], v85, 1.0 op_sel:[0,1,0]
	v_cvt_scalef32_pk_f32_fp4 v[10:11], v85, 1.0 op_sel:[1,1,0]
	v_pk_fma_f32 v[56:57], s[32:33], v[4:5], v[56:57] op_sel_hi:[0,1,1]
	v_pk_fma_f32 v[58:59], s[32:33], v[6:7], v[58:59] op_sel_hi:[0,1,1]
	v_pk_fma_f32 v[50:51], s[32:33], v[8:9], v[50:51] op_sel_hi:[0,1,1]
	v_pk_fma_f32 v[48:49], s[32:33], v[10:11], v[48:49] op_sel_hi:[0,1,1]
	v_readlane_b32 s29, v13, 18
	s_add_u32 s24, s14, s29
	s_addc_u32 s25, s15, 0
	global_load_dwordx2 v[84:85], v213, s[24:25]
	v_readlane_b32 s34, v15, 3
	v_cvt_scalef32_pk_f32_fp4 v[4:5], v86, 1.0
	v_cvt_scalef32_pk_f32_fp4 v[6:7], v86, 1.0 op_sel:[1,0,0]
	v_cvt_scalef32_pk_f32_fp4 v[8:9], v86, 1.0 op_sel:[0,1,0]
	v_cvt_scalef32_pk_f32_fp4 v[10:11], v86, 1.0 op_sel:[1,1,0]
	v_pk_fma_f32 v[62:63], s[34:35], v[4:5], v[62:63] op_sel_hi:[0,1,1]
	v_pk_fma_f32 v[60:61], s[34:35], v[6:7], v[60:61] op_sel_hi:[0,1,1]
	v_pk_fma_f32 v[52:53], s[34:35], v[8:9], v[52:53] op_sel_hi:[0,1,1]
	v_pk_fma_f32 v[54:55], s[34:35], v[10:11], v[54:55] op_sel_hi:[0,1,1]
	v_cvt_scalef32_pk_f32_fp4 v[4:5], v87, 1.0
	v_cvt_scalef32_pk_f32_fp4 v[6:7], v87, 1.0 op_sel:[1,0,0]
	v_cvt_scalef32_pk_f32_fp4 v[8:9], v87, 1.0 op_sel:[0,1,0]
	v_cvt_scalef32_pk_f32_fp4 v[10:11], v87, 1.0 op_sel:[1,1,0]
	v_pk_fma_f32 v[56:57], s[34:35], v[4:5], v[56:57] op_sel_hi:[0,1,1]
	v_pk_fma_f32 v[58:59], s[34:35], v[6:7], v[58:59] op_sel_hi:[0,1,1]
	v_pk_fma_f32 v[50:51], s[34:35], v[8:9], v[50:51] op_sel_hi:[0,1,1]
	v_pk_fma_f32 v[48:49], s[34:35], v[10:11], v[48:49] op_sel_hi:[0,1,1]
	v_readlane_b32 s30, v13, 19
	s_add_u32 s26, s14, s30
	s_addc_u32 s27, s15, 0
	global_load_dwordx2 v[86:87], v213, s[26:27]
	s_waitcnt vmcnt(12)
; __device__ void peer_v(const P& p, int layer, int tok, bool dry) {
;     ...
;     for (int jb = 0; jb < 64; jb += 16) {
;       u32x2 vv[16];
; #pragma unroll
;       for (int q = 0; q < 16; ++q) {
;         const int e = __builtin_amdgcn_readlane(eidx[h2], jb + q);
;         vv[q] = ((const u32x2*)(V4 + (size_t)e * 512))[lane];
;       }
; #pragma unroll
;       for (int q = 0; q < 16; ++q) {
;         const float wq = rdlane_f(wreg[h2], jb + q);
;         const f32x2 w2 = {wq, wq};
; #pragma unroll
;         for (int k = 0; k < 2; ++k) {
;           oa2[4 * k + 0] += w2 * __builtin_amdgcn_cvt_scalef32_pk_f32_fp4(vv[q][k], 1.0f, 0);
;           oa2[4 * k + 1] += w2 * __builtin_amdgcn_cvt_scalef32_pk_f32_fp4(vv[q][k], 1.0f, 1);
;           oa2[4 * k + 2] += w2 * __builtin_amdgcn_cvt_scalef32_pk_f32_fp4(vv[q][k], 1.0f, 2);
;           oa2[4 * k + 3] += w2 * __builtin_amdgcn_cvt_scalef32_pk_f32_fp4(vv[q][k], 1.0f, 3);
;         }
;       }
	v_readlane_b32 s32, v15, 4
	v_cvt_scalef32_pk_f32_fp4 v[4:5], v88, 1.0
	v_cvt_scalef32_pk_f32_fp4 v[6:7], v88, 1.0 op_sel:[1,0,0]
	v_cvt_scalef32_pk_f32_fp4 v[8:9], v88, 1.0 op_sel:[0,1,0]
	v_cvt_scalef32_pk_f32_fp4 v[10:11], v88, 1.0 op_sel:[1,1,0]
	v_pk_fma_f32 v[62:63], s[32:33], v[4:5], v[62:63] op_sel_hi:[0,1,1]
	v_pk_fma_f32 v[60:61], s[32:33], v[6:7], v[60:61] op_sel_hi:[0,1,1]
	v_pk_fma_f32 v[52:53], s[32:33], v[8:9], v[52:53] op_sel_hi:[0,1,1]
	v_pk_fma_f32 v[54:55], s[32:33], v[10:11], v[54:55] op_sel_hi:[0,1,1]
	v_cvt_scalef32_pk_f32_fp4 v[4:5], v89, 1.0
	v_cvt_scalef32_pk_f32_fp4 v[6:7], v89, 1.0 op_sel:[1,0,0]
	v_cvt_scalef32_pk_f32_fp4 v[8:9], v89, 1.0 op_sel:[0,1,0]
	v_cvt_scalef32_pk_f32_fp4 v[10:11], v89, 1.0 op_sel:[1,1,0]
	v_pk_fma_f32 v[56:57], s[32:33], v[4:5], v[56:57] op_sel_hi:[0,1,1]
	v_pk_fma_f32 v[58:59], s[32:33], v[6:7], v[58:59] op_sel_hi:[0,1,1]
	v_pk_fma_f32 v[50:51], s[32:33], v[8:9], v[50:51] op_sel_hi:[0,1,1]
	v_pk_fma_f32 v[48:49], s[32:33], v[10:11], v[48:49] op_sel_hi:[0,1,1]
	v_readlane_b32 s22, v13, 20
	s_add_u32 s16, s14, s22
	s_addc_u32 s17, s15, 0
	global_load_dwordx2 v[88:89], v213, s[16:17]
	v_readlane_b32 s34, v15, 5
	v_cvt_scalef32_pk_f32_fp4 v[4:5], v90, 1.0
	v_cvt_scalef32_pk_f32_fp4 v[6:7], v90, 1.0 op_sel:[1,0,0]
	v_cvt_scalef32_pk_f32_fp4 v[8:9], v90, 1.0 op_sel:[0,1,0]
	v_cvt_scalef32_pk_f32_fp4 v[10:11], v90, 1.0 op_sel:[1,1,0]
	v_pk_fma_f32 v[62:63], s[34:35], v[4:5], v[62:63] op_sel_hi:[0,1,1]
	v_pk_fma_f32 v[60:61], s[34:35], v[6:7], v[60:61] op_sel_hi:[0,1,1]
	v_pk_fma_f32 v[52:53], s[34:35], v[8:9], v[52:53] op_sel_hi:[0,1,1]
	v_pk_fma_f32 v[54:55], s[34:35], v[10:11], v[54:55] op_sel_hi:[0,1,1]
	v_cvt_scalef32_pk_f32_fp4 v[4:5], v91, 1.0
	v_cvt_scalef32_pk_f32_fp4 v[6:7], v91, 1.0 op_sel:[1,0,0]
	v_cvt_scalef32_pk_f32_fp4 v[8:9], v91, 1.0 op_sel:[0,1,0]
	v_cvt_scalef32_pk_f32_fp4 v[10:11], v91, 1.0 op_sel:[1,1,0]
	v_pk_fma_f32 v[56:57], s[34:35], v[4:5], v[56:57] op_sel_hi:[0,1,1]
	v_pk_fma_f32 v[58:59], s[34:35], v[6:7], v[58:59] op_sel_hi:[0,1,1]
	v_pk_fma_f32 v[50:51], s[34:35], v[8:9], v[50:51] op_sel_hi:[0,1,1]
	v_pk_fma_f32 v[48:49], s[34:35], v[10:11], v[48:49] op_sel_hi:[0,1,1]
	v_readlane_b32 s28, v13, 21
	s_add_u32 s20, s14, s28
	s_addc_u32 s21, s15, 0
	global_load_dwordx2 v[90:91], v213, s[20:21]
	v_readlane_b32 s32, v15, 6
	v_cvt_scalef32_pk_f32_fp4 v[4:5], v92, 1.0
	v_cvt_scalef32_pk_f32_fp4 v[6:7], v92, 1.0 op_sel:[1,0,0]
	v_cvt_scalef32_pk_f32_fp4 v[8:9], v92, 1.0 op_sel:[0,1,0]
	v_cvt_scalef32_pk_f32_fp4 v[10:11], v92, 1.0 op_sel:[1,1,0]
	v_pk_fma_f32 v[62:63], s[32:33], v[4:5], v[62:63] op_sel_hi:[0,1,1]
	v_pk_fma_f32 v[60:61], s[32:33], v[6:7], v[60:61] op_sel_hi:[0,1,1]
	v_pk_fma_f32 v[52:53], s[32:33], v[8:9], v[52:53] op_sel_hi:[0,1,1]
	v_pk_fma_f32 v[54:55], s[32:33], v[10:11], v[54:55] op_sel_hi:[0,1,1]
	v_cvt_scalef32_pk_f32_fp4 v[4:5], v93, 1.0
	v_cvt_scalef32_pk_f32_fp4 v[6:7], v93, 1.0 op_sel:[1,0,0]
	v_cvt_scalef32_pk_f32_fp4 v[8:9], v93, 1.0 op_sel:[0,1,0]
	v_cvt_scalef32_pk_f32_fp4 v[10:11], v93, 1.0 op_sel:[1,1,0]
	v_pk_fma_f32 v[56:57], s[32:33], v[4:5], v[56:57] op_sel_hi:[0,1,1]
	v_pk_fma_f32 v[58:59], s[32:33], v[6:7], v[58:59] op_sel_hi:[0,1,1]
	v_pk_fma_f32 v[50:51], s[32:33], v[8:9], v[50:51] op_sel_hi:[0,1,1]
	v_pk_fma_f32 v[48:49], s[32:33], v[10:11], v[48:49] op_sel_hi:[0,1,1]
	v_readlane_b32 s29, v13, 22
	s_add_u32 s24, s14, s29
	s_addc_u32 s25, s15, 0
	global_load_dwordx2 v[92:93], v213, s[24:25]
	v_readlane_b32 s34, v15, 7
	v_cvt_scalef32_pk_f32_fp4 v[4:5], v94, 1.0
	v_cvt_scalef32_pk_f32_fp4 v[6:7], v94, 1.0 op_sel:[1,0,0]
	v_cvt_scalef32_pk_f32_fp4 v[8:9], v94, 1.0 op_sel:[0,1,0]
	v_cvt_scalef32_pk_f32_fp4 v[10:11], v94, 1.0 op_sel:[1,1,0]
	v_pk_fma_f32 v[62:63], s[34:35], v[4:5], v[62:63] op_sel_hi:[0,1,1]
	v_pk_fma_f32 v[60:61], s[34:35], v[6:7], v[60:61] op_sel_hi:[0,1,1]
	v_pk_fma_f32 v[52:53], s[34:35], v[8:9], v[52:53] op_sel_hi:[0,1,1]
	v_pk_fma_f32 v[54:55], s[34:35], v[10:11], v[54:55] op_sel_hi:[0,1,1]
	v_cvt_scalef32_pk_f32_fp4 v[4:5], v95, 1.0
	v_cvt_scalef32_pk_f32_fp4 v[6:7], v95, 1.0 op_sel:[1,0,0]
	v_cvt_scalef32_pk_f32_fp4 v[8:9], v95, 1.0 op_sel:[0,1,0]
	v_cvt_scalef32_pk_f32_fp4 v[10:11], v95, 1.0 op_sel:[1,1,0]
	v_pk_fma_f32 v[56:57], s[34:35], v[4:5], v[56:57] op_sel_hi:[0,1,1]
	v_pk_fma_f32 v[58:59], s[34:35], v[6:7], v[58:59] op_sel_hi:[0,1,1]
	v_pk_fma_f32 v[50:51], s[34:35], v[8:9], v[50:51] op_sel_hi:[0,1,1]
	v_pk_fma_f32 v[48:49], s[34:35], v[10:11], v[48:49] op_sel_hi:[0,1,1]
	v_readlane_b32 s30, v13, 23
	s_add_u32 s26, s14, s30
	s_addc_u32 s27, s15, 0
	global_load_dwordx2 v[94:95], v213, s[26:27]
	s_waitcnt vmcnt(12)
; __device__ void peer_v(const P& p, int layer, int tok, bool dry) {
;     ...
;     for (int jb = 0; jb < 64; jb += 16) {
;       u32x2 vv[16];
; #pragma unroll
;       for (int q = 0; q < 16; ++q) {
;         const int e = __builtin_amdgcn_readlane(eidx[h2], jb + q);
;         vv[q] = ((const u32x2*)(V4 + (size_t)e * 512))[lane];
;       }
; #pragma unroll
;       for (int q = 0; q < 16; ++q) {
;         const float wq = rdlane_f(wreg[h2], jb + q);
;         const f32x2 w2 = {wq, wq};
; #pragma unroll
;         for (int k = 0; k < 2; ++k) {
;           oa2[4 * k + 0] += w2 * __builtin_amdgcn_cvt_scalef32_pk_f32_fp4(vv[q][k], 1.0f, 0);
;           oa2[4 * k + 1] += w2 * __builtin_amdgcn_cvt_scalef32_pk_f32_fp4(vv[q][k], 1.0f, 1);
;           oa2[4 * k + 2] += w2 * __builtin_amdgcn_cvt_scalef32_pk_f32_fp4(vv[q][k], 1.0f, 2);
;           oa2[4 * k + 3] += w2 * __builtin_amdgcn_cvt_scalef32_pk_f32_fp4(vv[q][k], 1.0f, 3);
;         }
;       }
	v_readlane_b32 s32, v15, 8
	v_cvt_scalef32_pk_f32_fp4 v[4:5], v96, 1.0
	v_cvt_scalef32_pk_f32_fp4 v[6:7], v96, 1.0 op_sel:[1,0,0]
	v_cvt_scalef32_pk_f32_fp4 v[8:9], v96, 1.0 op_sel:[0,1,0]
	v_cvt_scalef32_pk_f32_fp4 v[10:11], v96, 1.0 op_sel:[1,1,0]
	v_pk_fma_f32 v[62:63], s[32:33], v[4:5], v[62:63] op_sel_hi:[0,1,1]
	v_pk_fma_f32 v[60:61], s[32:33], v[6:7], v[60:61] op_sel_hi:[0,1,1]
	v_pk_fma_f32 v[52:53], s[32:33], v[8:9], v[52:53] op_sel_hi:[0,1,1]
	v_pk_fma_f32 v[54:55], s[32:33], v[10:11], v[54:55] op_sel_hi:[0,1,1]
	v_cvt_scalef32_pk_f32_fp4 v[4:5], v97, 1.0
	v_cvt_scalef32_pk_f32_fp4 v[6:7], v97, 1.0 op_sel:[1,0,0]
	v_cvt_scalef32_pk_f32_fp4 v[8:9], v97, 1.0 op_sel:[0,1,0]
	v_cvt_scalef32_pk_f32_fp4 v[10:11], v97, 1.0 op_sel:[1,1,0]
	v_pk_fma_f32 v[56:57], s[32:33], v[4:5], v[56:57] op_sel_hi:[0,1,1]
	v_pk_fma_f32 v[58:59], s[32:33], v[6:7], v[58:59] op_sel_hi:[0,1,1]
	v_pk_fma_f32 v[50:51], s[32:33], v[8:9], v[50:51] op_sel_hi:[0,1,1]
	v_pk_fma_f32 v[48:49], s[32:33], v[10:11], v[48:49] op_sel_hi:[0,1,1]
	v_readlane_b32 s22, v13, 24
	s_add_u32 s16, s14, s22
	s_addc_u32 s17, s15, 0
	global_load_dwordx2 v[96:97], v213, s[16:17]
	v_readlane_b32 s34, v15, 9
	v_cvt_scalef32_pk_f32_fp4 v[4:5], v98, 1.0
	v_cvt_scalef32_pk_f32_fp4 v[6:7], v98, 1.0 op_sel:[1,0,0]
	v_cvt_scalef32_pk_f32_fp4 v[8:9], v98, 1.0 op_sel:[0,1,0]
	v_cvt_scalef32_pk_f32_fp4 v[10:11], v98, 1.0 op_sel:[1,1,0]
	v_pk_fma_f32 v[62:63], s[34:35], v[4:5], v[62:63] op_sel_hi:[0,1,1]
	v_pk_fma_f32 v[60:61], s[34:35], v[6:7], v[60:61] op_sel_hi:[0,1,1]
	v_pk_fma_f32 v[52:53], s[34:35], v[8:9], v[52:53] op_sel_hi:[0,1,1]
	v_pk_fma_f32 v[54:55], s[34:35], v[10:11], v[54:55] op_sel_hi:[0,1,1]
	v_cvt_scalef32_pk_f32_fp4 v[4:5], v99, 1.0
	v_cvt_scalef32_pk_f32_fp4 v[6:7], v99, 1.0 op_sel:[1,0,0]
	v_cvt_scalef32_pk_f32_fp4 v[8:9], v99, 1.0 op_sel:[0,1,0]
	v_cvt_scalef32_pk_f32_fp4 v[10:11], v99, 1.0 op_sel:[1,1,0]
	v_pk_fma_f32 v[56:57], s[34:35], v[4:5], v[56:57] op_sel_hi:[0,1,1]
	v_pk_fma_f32 v[58:59], s[34:35], v[6:7], v[58:59] op_sel_hi:[0,1,1]
	v_pk_fma_f32 v[50:51], s[34:35], v[8:9], v[50:51] op_sel_hi:[0,1,1]
	v_pk_fma_f32 v[48:49], s[34:35], v[10:11], v[48:49] op_sel_hi:[0,1,1]
	v_readlane_b32 s28, v13, 25
	s_add_u32 s20, s14, s28
	s_addc_u32 s21, s15, 0
	global_load_dwordx2 v[98:99], v213, s[20:21]
	v_readlane_b32 s32, v15, 10
	v_cvt_scalef32_pk_f32_fp4 v[4:5], v100, 1.0
	v_cvt_scalef32_pk_f32_fp4 v[6:7], v100, 1.0 op_sel:[1,0,0]
	v_cvt_scalef32_pk_f32_fp4 v[8:9], v100, 1.0 op_sel:[0,1,0]
	v_cvt_scalef32_pk_f32_fp4 v[10:11], v100, 1.0 op_sel:[1,1,0]
	v_pk_fma_f32 v[62:63], s[32:33], v[4:5], v[62:63] op_sel_hi:[0,1,1]
	v_pk_fma_f32 v[60:61], s[32:33], v[6:7], v[60:61] op_sel_hi:[0,1,1]
	v_pk_fma_f32 v[52:53], s[32:33], v[8:9], v[52:53] op_sel_hi:[0,1,1]
	v_pk_fma_f32 v[54:55], s[32:33], v[10:11], v[54:55] op_sel_hi:[0,1,1]
	v_cvt_scalef32_pk_f32_fp4 v[4:5], v101, 1.0
	v_cvt_scalef32_pk_f32_fp4 v[6:7], v101, 1.0 op_sel:[1,0,0]
	v_cvt_scalef32_pk_f32_fp4 v[8:9], v101, 1.0 op_sel:[0,1,0]
	v_cvt_scalef32_pk_f32_fp4 v[10:11], v101, 1.0 op_sel:[1,1,0]
	v_pk_fma_f32 v[56:57], s[32:33], v[4:5], v[56:57] op_sel_hi:[0,1,1]
	v_pk_fma_f32 v[58:59], s[32:33], v[6:7], v[58:59] op_sel_hi:[0,1,1]
	v_pk_fma_f32 v[50:51], s[32:33], v[8:9], v[50:51] op_sel_hi:[0,1,1]
	v_pk_fma_f32 v[48:49], s[32:33], v[10:11], v[48:49] op_sel_hi:[0,1,1]
	v_readlane_b32 s29, v13, 26
	s_add_u32 s24, s14, s29
	s_addc_u32 s25, s15, 0
	global_load_dwordx2 v[100:101], v213, s[24:25]
	v_readlane_b32 s34, v15, 11
	v_cvt_scalef32_pk_f32_fp4 v[4:5], v102, 1.0
	v_cvt_scalef32_pk_f32_fp4 v[6:7], v102, 1.0 op_sel:[1,0,0]
	v_cvt_scalef32_pk_f32_fp4 v[8:9], v102, 1.0 op_sel:[0,1,0]
	v_cvt_scalef32_pk_f32_fp4 v[10:11], v102, 1.0 op_sel:[1,1,0]
	v_pk_fma_f32 v[62:63], s[34:35], v[4:5], v[62:63] op_sel_hi:[0,1,1]
	v_pk_fma_f32 v[60:61], s[34:35], v[6:7], v[60:61] op_sel_hi:[0,1,1]
	v_pk_fma_f32 v[52:53], s[34:35], v[8:9], v[52:53] op_sel_hi:[0,1,1]
	v_pk_fma_f32 v[54:55], s[34:35], v[10:11], v[54:55] op_sel_hi:[0,1,1]
	v_cvt_scalef32_pk_f32_fp4 v[4:5], v103, 1.0
	v_cvt_scalef32_pk_f32_fp4 v[6:7], v103, 1.0 op_sel:[1,0,0]
	v_cvt_scalef32_pk_f32_fp4 v[8:9], v103, 1.0 op_sel:[0,1,0]
	v_cvt_scalef32_pk_f32_fp4 v[10:11], v103, 1.0 op_sel:[1,1,0]
	v_pk_fma_f32 v[56:57], s[34:35], v[4:5], v[56:57] op_sel_hi:[0,1,1]
	v_pk_fma_f32 v[58:59], s[34:35], v[6:7], v[58:59] op_sel_hi:[0,1,1]
	v_pk_fma_f32 v[50:51], s[34:35], v[8:9], v[50:51] op_sel_hi:[0,1,1]
	v_pk_fma_f32 v[48:49], s[34:35], v[10:11], v[48:49] op_sel_hi:[0,1,1]
	v_readlane_b32 s30, v13, 27
	s_add_u32 s26, s14, s30
	s_addc_u32 s27, s15, 0
	global_load_dwordx2 v[102:103], v213, s[26:27]
	s_waitcnt vmcnt(12)
; __device__ void peer_v(const P& p, int layer, int tok, bool dry) {
;     ...
;     for (int jb = 0; jb < 64; jb += 16) {
;       u32x2 vv[16];
; #pragma unroll
;       for (int q = 0; q < 16; ++q) {
;         const int e = __builtin_amdgcn_readlane(eidx[h2], jb + q);
;         vv[q] = ((const u32x2*)(V4 + (size_t)e * 512))[lane];
;       }
; #pragma unroll
;       for (int q = 0; q < 16; ++q) {
;         const float wq = rdlane_f(wreg[h2], jb + q);
;         const f32x2 w2 = {wq, wq};
; #pragma unroll
;         for (int k = 0; k < 2; ++k) {
;           oa2[4 * k + 0] += w2 * __builtin_amdgcn_cvt_scalef32_pk_f32_fp4(vv[q][k], 1.0f, 0);
;           oa2[4 * k + 1] += w2 * __builtin_amdgcn_cvt_scalef32_pk_f32_fp4(vv[q][k], 1.0f, 1);
;           oa2[4 * k + 2] += w2 * __builtin_amdgcn_cvt_scalef32_pk_f32_fp4(vv[q][k], 1.0f, 2);
;           oa2[4 * k + 3] += w2 * __builtin_amdgcn_cvt_scalef32_pk_f32_fp4(vv[q][k], 1.0f, 3);
;         }
;       }
	v_readlane_b32 s32, v15, 12
	v_cvt_scalef32_pk_f32_fp4 v[4:5], v104, 1.0
	v_cvt_scalef32_pk_f32_fp4 v[6:7], v104, 1.0 op_sel:[1,0,0]
	v_cvt_scalef32_pk_f32_fp4 v[8:9], v104, 1.0 op_sel:[0,1,0]
	v_cvt_scalef32_pk_f32_fp4 v[10:11], v104, 1.0 op_sel:[1,1,0]
	v_pk_fma_f32 v[62:63], s[32:33], v[4:5], v[62:63] op_sel_hi:[0,1,1]
	v_pk_fma_f32 v[60:61], s[32:33], v[6:7], v[60:61] op_sel_hi:[0,1,1]
	v_pk_fma_f32 v[52:53], s[32:33], v[8:9], v[52:53] op_sel_hi:[0,1,1]
	v_pk_fma_f32 v[54:55], s[32:33], v[10:11], v[54:55] op_sel_hi:[0,1,1]
	v_cvt_scalef32_pk_f32_fp4 v[4:5], v105, 1.0
	v_cvt_scalef32_pk_f32_fp4 v[6:7], v105, 1.0 op_sel:[1,0,0]
	v_cvt_scalef32_pk_f32_fp4 v[8:9], v105, 1.0 op_sel:[0,1,0]
	v_cvt_scalef32_pk_f32_fp4 v[10:11], v105, 1.0 op_sel:[1,1,0]
	v_pk_fma_f32 v[56:57], s[32:33], v[4:5], v[56:57] op_sel_hi:[0,1,1]
	v_pk_fma_f32 v[58:59], s[32:33], v[6:7], v[58:59] op_sel_hi:[0,1,1]
	v_pk_fma_f32 v[50:51], s[32:33], v[8:9], v[50:51] op_sel_hi:[0,1,1]
	v_pk_fma_f32 v[48:49], s[32:33], v[10:11], v[48:49] op_sel_hi:[0,1,1]
	v_readlane_b32 s22, v13, 28
	s_add_u32 s16, s14, s22
	s_addc_u32 s17, s15, 0
	global_load_dwordx2 v[104:105], v213, s[16:17]
	v_readlane_b32 s34, v15, 13
	v_cvt_scalef32_pk_f32_fp4 v[4:5], v106, 1.0
	v_cvt_scalef32_pk_f32_fp4 v[6:7], v106, 1.0 op_sel:[1,0,0]
	v_cvt_scalef32_pk_f32_fp4 v[8:9], v106, 1.0 op_sel:[0,1,0]
	v_cvt_scalef32_pk_f32_fp4 v[10:11], v106, 1.0 op_sel:[1,1,0]
	v_pk_fma_f32 v[62:63], s[34:35], v[4:5], v[62:63] op_sel_hi:[0,1,1]
	v_pk_fma_f32 v[60:61], s[34:35], v[6:7], v[60:61] op_sel_hi:[0,1,1]
	v_pk_fma_f32 v[52:53], s[34:35], v[8:9], v[52:53] op_sel_hi:[0,1,1]
	v_pk_fma_f32 v[54:55], s[34:35], v[10:11], v[54:55] op_sel_hi:[0,1,1]
	v_cvt_scalef32_pk_f32_fp4 v[4:5], v107, 1.0
	v_cvt_scalef32_pk_f32_fp4 v[6:7], v107, 1.0 op_sel:[1,0,0]
	v_cvt_scalef32_pk_f32_fp4 v[8:9], v107, 1.0 op_sel:[0,1,0]
	v_cvt_scalef32_pk_f32_fp4 v[10:11], v107, 1.0 op_sel:[1,1,0]
	v_pk_fma_f32 v[56:57], s[34:35], v[4:5], v[56:57] op_sel_hi:[0,1,1]
	v_pk_fma_f32 v[58:59], s[34:35], v[6:7], v[58:59] op_sel_hi:[0,1,1]
	v_pk_fma_f32 v[50:51], s[34:35], v[8:9], v[50:51] op_sel_hi:[0,1,1]
	v_pk_fma_f32 v[48:49], s[34:35], v[10:11], v[48:49] op_sel_hi:[0,1,1]
	v_readlane_b32 s28, v13, 29
	s_add_u32 s20, s14, s28
	s_addc_u32 s21, s15, 0
	global_load_dwordx2 v[106:107], v213, s[20:21]
	v_readlane_b32 s32, v15, 14
	v_cvt_scalef32_pk_f32_fp4 v[4:5], v108, 1.0
	v_cvt_scalef32_pk_f32_fp4 v[6:7], v108, 1.0 op_sel:[1,0,0]
	v_cvt_scalef32_pk_f32_fp4 v[8:9], v108, 1.0 op_sel:[0,1,0]
	v_cvt_scalef32_pk_f32_fp4 v[10:11], v108, 1.0 op_sel:[1,1,0]
	v_pk_fma_f32 v[62:63], s[32:33], v[4:5], v[62:63] op_sel_hi:[0,1,1]
	v_pk_fma_f32 v[60:61], s[32:33], v[6:7], v[60:61] op_sel_hi:[0,1,1]
	v_pk_fma_f32 v[52:53], s[32:33], v[8:9], v[52:53] op_sel_hi:[0,1,1]
	v_pk_fma_f32 v[54:55], s[32:33], v[10:11], v[54:55] op_sel_hi:[0,1,1]
	v_cvt_scalef32_pk_f32_fp4 v[4:5], v109, 1.0
	v_cvt_scalef32_pk_f32_fp4 v[6:7], v109, 1.0 op_sel:[1,0,0]
	v_cvt_scalef32_pk_f32_fp4 v[8:9], v109, 1.0 op_sel:[0,1,0]
	v_cvt_scalef32_pk_f32_fp4 v[10:11], v109, 1.0 op_sel:[1,1,0]
	v_pk_fma_f32 v[56:57], s[32:33], v[4:5], v[56:57] op_sel_hi:[0,1,1]
	v_pk_fma_f32 v[58:59], s[32:33], v[6:7], v[58:59] op_sel_hi:[0,1,1]
	v_pk_fma_f32 v[50:51], s[32:33], v[8:9], v[50:51] op_sel_hi:[0,1,1]
	v_pk_fma_f32 v[48:49], s[32:33], v[10:11], v[48:49] op_sel_hi:[0,1,1]
	v_readlane_b32 s29, v13, 30
	s_add_u32 s24, s14, s29
	s_addc_u32 s25, s15, 0
	global_load_dwordx2 v[108:109], v213, s[24:25]
	v_readlane_b32 s34, v15, 15
	v_cvt_scalef32_pk_f32_fp4 v[4:5], v110, 1.0
	v_cvt_scalef32_pk_f32_fp4 v[6:7], v110, 1.0 op_sel:[1,0,0]
	v_cvt_scalef32_pk_f32_fp4 v[8:9], v110, 1.0 op_sel:[0,1,0]
	v_cvt_scalef32_pk_f32_fp4 v[10:11], v110, 1.0 op_sel:[1,1,0]
	v_pk_fma_f32 v[62:63], s[34:35], v[4:5], v[62:63] op_sel_hi:[0,1,1]
	v_pk_fma_f32 v[60:61], s[34:35], v[6:7], v[60:61] op_sel_hi:[0,1,1]
	v_pk_fma_f32 v[52:53], s[34:35], v[8:9], v[52:53] op_sel_hi:[0,1,1]
	v_pk_fma_f32 v[54:55], s[34:35], v[10:11], v[54:55] op_sel_hi:[0,1,1]
	v_cvt_scalef32_pk_f32_fp4 v[4:5], v111, 1.0
	v_cvt_scalef32_pk_f32_fp4 v[6:7], v111, 1.0 op_sel:[1,0,0]
	v_cvt_scalef32_pk_f32_fp4 v[8:9], v111, 1.0 op_sel:[0,1,0]
	v_cvt_scalef32_pk_f32_fp4 v[10:11], v111, 1.0 op_sel:[1,1,0]
	v_pk_fma_f32 v[56:57], s[34:35], v[4:5], v[56:57] op_sel_hi:[0,1,1]
	v_pk_fma_f32 v[58:59], s[34:35], v[6:7], v[58:59] op_sel_hi:[0,1,1]
	v_pk_fma_f32 v[50:51], s[34:35], v[8:9], v[50:51] op_sel_hi:[0,1,1]
	v_pk_fma_f32 v[48:49], s[34:35], v[10:11], v[48:49] op_sel_hi:[0,1,1]
	v_readlane_b32 s30, v13, 31
	s_add_u32 s26, s14, s30
	s_addc_u32 s27, s15, 0
	global_load_dwordx2 v[110:111], v213, s[26:27]
	s_waitcnt vmcnt(12)
; __device__ void peer_v(const P& p, int layer, int tok, bool dry) {
;     ...
;     for (int jb = 0; jb < 64; jb += 16) {
;       u32x2 vv[16];
; #pragma unroll
;       for (int q = 0; q < 16; ++q) {
;         const int e = __builtin_amdgcn_readlane(eidx[h2], jb + q);
;         vv[q] = ((const u32x2*)(V4 + (size_t)e * 512))[lane];
;       }
; #pragma unroll
;       for (int q = 0; q < 16; ++q) {
;         const float wq = rdlane_f(wreg[h2], jb + q);
;         const f32x2 w2 = {wq, wq};
; #pragma unroll
;         for (int k = 0; k < 2; ++k) {
;           oa2[4 * k + 0] += w2 * __builtin_amdgcn_cvt_scalef32_pk_f32_fp4(vv[q][k], 1.0f, 0);
;           oa2[4 * k + 1] += w2 * __builtin_amdgcn_cvt_scalef32_pk_f32_fp4(vv[q][k], 1.0f, 1);
;           oa2[4 * k + 2] += w2 * __builtin_amdgcn_cvt_scalef32_pk_f32_fp4(vv[q][k], 1.0f, 2);
;           oa2[4 * k + 3] += w2 * __builtin_amdgcn_cvt_scalef32_pk_f32_fp4(vv[q][k], 1.0f, 3);
;         }
;       }
	v_readlane_b32 s32, v15, 16
	v_cvt_scalef32_pk_f32_fp4 v[4:5], v80, 1.0
	v_cvt_scalef32_pk_f32_fp4 v[6:7], v80, 1.0 op_sel:[1,0,0]
	v_cvt_scalef32_pk_f32_fp4 v[8:9], v80, 1.0 op_sel:[0,1,0]
	v_cvt_scalef32_pk_f32_fp4 v[10:11], v80, 1.0 op_sel:[1,1,0]
	v_pk_fma_f32 v[62:63], s[32:33], v[4:5], v[62:63] op_sel_hi:[0,1,1]
	v_pk_fma_f32 v[60:61], s[32:33], v[6:7], v[60:61] op_sel_hi:[0,1,1]
	v_pk_fma_f32 v[52:53], s[32:33], v[8:9], v[52:53] op_sel_hi:[0,1,1]
	v_pk_fma_f32 v[54:55], s[32:33], v[10:11], v[54:55] op_sel_hi:[0,1,1]
	v_cvt_scalef32_pk_f32_fp4 v[4:5], v81, 1.0
	v_cvt_scalef32_pk_f32_fp4 v[6:7], v81, 1.0 op_sel:[1,0,0]
	v_cvt_scalef32_pk_f32_fp4 v[8:9], v81, 1.0 op_sel:[0,1,0]
	v_cvt_scalef32_pk_f32_fp4 v[10:11], v81, 1.0 op_sel:[1,1,0]
	v_pk_fma_f32 v[56:57], s[32:33], v[4:5], v[56:57] op_sel_hi:[0,1,1]
	v_pk_fma_f32 v[58:59], s[32:33], v[6:7], v[58:59] op_sel_hi:[0,1,1]
	v_pk_fma_f32 v[50:51], s[32:33], v[8:9], v[50:51] op_sel_hi:[0,1,1]
	v_pk_fma_f32 v[48:49], s[32:33], v[10:11], v[48:49] op_sel_hi:[0,1,1]
	v_readlane_b32 s22, v13, 32
	s_add_u32 s16, s14, s22
	s_addc_u32 s17, s15, 0
	global_load_dwordx2 v[80:81], v213, s[16:17]
	v_readlane_b32 s34, v15, 17
	v_cvt_scalef32_pk_f32_fp4 v[4:5], v82, 1.0
	v_cvt_scalef32_pk_f32_fp4 v[6:7], v82, 1.0 op_sel:[1,0,0]
	v_cvt_scalef32_pk_f32_fp4 v[8:9], v82, 1.0 op_sel:[0,1,0]
	v_cvt_scalef32_pk_f32_fp4 v[10:11], v82, 1.0 op_sel:[1,1,0]
	v_pk_fma_f32 v[62:63], s[34:35], v[4:5], v[62:63] op_sel_hi:[0,1,1]
	v_pk_fma_f32 v[60:61], s[34:35], v[6:7], v[60:61] op_sel_hi:[0,1,1]
	v_pk_fma_f32 v[52:53], s[34:35], v[8:9], v[52:53] op_sel_hi:[0,1,1]
	v_pk_fma_f32 v[54:55], s[34:35], v[10:11], v[54:55] op_sel_hi:[0,1,1]
	v_cvt_scalef32_pk_f32_fp4 v[4:5], v83, 1.0
	v_cvt_scalef32_pk_f32_fp4 v[6:7], v83, 1.0 op_sel:[1,0,0]
	v_cvt_scalef32_pk_f32_fp4 v[8:9], v83, 1.0 op_sel:[0,1,0]
	v_cvt_scalef32_pk_f32_fp4 v[10:11], v83, 1.0 op_sel:[1,1,0]
	v_pk_fma_f32 v[56:57], s[34:35], v[4:5], v[56:57] op_sel_hi:[0,1,1]
	v_pk_fma_f32 v[58:59], s[34:35], v[6:7], v[58:59] op_sel_hi:[0,1,1]
	v_pk_fma_f32 v[50:51], s[34:35], v[8:9], v[50:51] op_sel_hi:[0,1,1]
	v_pk_fma_f32 v[48:49], s[34:35], v[10:11], v[48:49] op_sel_hi:[0,1,1]
	v_readlane_b32 s28, v13, 33
	s_add_u32 s20, s14, s28
	s_addc_u32 s21, s15, 0
	global_load_dwordx2 v[82:83], v213, s[20:21]
	v_readlane_b32 s32, v15, 18
	v_cvt_scalef32_pk_f32_fp4 v[4:5], v84, 1.0
	v_cvt_scalef32_pk_f32_fp4 v[6:7], v84, 1.0 op_sel:[1,0,0]
	v_cvt_scalef32_pk_f32_fp4 v[8:9], v84, 1.0 op_sel:[0,1,0]
	v_cvt_scalef32_pk_f32_fp4 v[10:11], v84, 1.0 op_sel:[1,1,0]
	v_pk_fma_f32 v[62:63], s[32:33], v[4:5], v[62:63] op_sel_hi:[0,1,1]
	v_pk_fma_f32 v[60:61], s[32:33], v[6:7], v[60:61] op_sel_hi:[0,1,1]
	v_pk_fma_f32 v[52:53], s[32:33], v[8:9], v[52:53] op_sel_hi:[0,1,1]
	v_pk_fma_f32 v[54:55], s[32:33], v[10:11], v[54:55] op_sel_hi:[0,1,1]
	v_cvt_scalef32_pk_f32_fp4 v[4:5], v85, 1.0
	v_cvt_scalef32_pk_f32_fp4 v[6:7], v85, 1.0 op_sel:[1,0,0]
	v_cvt_scalef32_pk_f32_fp4 v[8:9], v85, 1.0 op_sel:[0,1,0]
	v_cvt_scalef32_pk_f32_fp4 v[10:11], v85, 1.0 op_sel:[1,1,0]
	v_pk_fma_f32 v[56:57], s[32:33], v[4:5], v[56:57] op_sel_hi:[0,1,1]
	v_pk_fma_f32 v[58:59], s[32:33], v[6:7], v[58:59] op_sel_hi:[0,1,1]
	v_pk_fma_f32 v[50:51], s[32:33], v[8:9], v[50:51] op_sel_hi:[0,1,1]
	v_pk_fma_f32 v[48:49], s[32:33], v[10:11], v[48:49] op_sel_hi:[0,1,1]
	v_readlane_b32 s29, v13, 34
	s_add_u32 s24, s14, s29
	s_addc_u32 s25, s15, 0
	global_load_dwordx2 v[84:85], v213, s[24:25]
	v_readlane_b32 s34, v15, 19
	v_cvt_scalef32_pk_f32_fp4 v[4:5], v86, 1.0
	v_cvt_scalef32_pk_f32_fp4 v[6:7], v86, 1.0 op_sel:[1,0,0]
	v_cvt_scalef32_pk_f32_fp4 v[8:9], v86, 1.0 op_sel:[0,1,0]
	v_cvt_scalef32_pk_f32_fp4 v[10:11], v86, 1.0 op_sel:[1,1,0]
	v_pk_fma_f32 v[62:63], s[34:35], v[4:5], v[62:63] op_sel_hi:[0,1,1]
	v_pk_fma_f32 v[60:61], s[34:35], v[6:7], v[60:61] op_sel_hi:[0,1,1]
	v_pk_fma_f32 v[52:53], s[34:35], v[8:9], v[52:53] op_sel_hi:[0,1,1]
	v_pk_fma_f32 v[54:55], s[34:35], v[10:11], v[54:55] op_sel_hi:[0,1,1]
	v_cvt_scalef32_pk_f32_fp4 v[4:5], v87, 1.0
	v_cvt_scalef32_pk_f32_fp4 v[6:7], v87, 1.0 op_sel:[1,0,0]
	v_cvt_scalef32_pk_f32_fp4 v[8:9], v87, 1.0 op_sel:[0,1,0]
	v_cvt_scalef32_pk_f32_fp4 v[10:11], v87, 1.0 op_sel:[1,1,0]
	v_pk_fma_f32 v[56:57], s[34:35], v[4:5], v[56:57] op_sel_hi:[0,1,1]
	v_pk_fma_f32 v[58:59], s[34:35], v[6:7], v[58:59] op_sel_hi:[0,1,1]
	v_pk_fma_f32 v[50:51], s[34:35], v[8:9], v[50:51] op_sel_hi:[0,1,1]
	v_pk_fma_f32 v[48:49], s[34:35], v[10:11], v[48:49] op_sel_hi:[0,1,1]
	v_readlane_b32 s30, v13, 35
	s_add_u32 s26, s14, s30
	s_addc_u32 s27, s15, 0
	global_load_dwordx2 v[86:87], v213, s[26:27]
	s_waitcnt vmcnt(12)
; __device__ void peer_v(const P& p, int layer, int tok, bool dry) {
;     ...
;     for (int jb = 0; jb < 64; jb += 16) {
;       u32x2 vv[16];
; #pragma unroll
;       for (int q = 0; q < 16; ++q) {
;         const int e = __builtin_amdgcn_readlane(eidx[h2], jb + q);
;         vv[q] = ((const u32x2*)(V4 + (size_t)e * 512))[lane];
;       }
; #pragma unroll
;       for (int q = 0; q < 16; ++q) {
;         const float wq = rdlane_f(wreg[h2], jb + q);
;         const f32x2 w2 = {wq, wq};
; #pragma unroll
;         for (int k = 0; k < 2; ++k) {
;           oa2[4 * k + 0] += w2 * __builtin_amdgcn_cvt_scalef32_pk_f32_fp4(vv[q][k], 1.0f, 0);
;           oa2[4 * k + 1] += w2 * __builtin_amdgcn_cvt_scalef32_pk_f32_fp4(vv[q][k], 1.0f, 1);
;           oa2[4 * k + 2] += w2 * __builtin_amdgcn_cvt_scalef32_pk_f32_fp4(vv[q][k], 1.0f, 2);
;           oa2[4 * k + 3] += w2 * __builtin_amdgcn_cvt_scalef32_pk_f32_fp4(vv[q][k], 1.0f, 3);
;         }
;       }
	v_readlane_b32 s32, v15, 20
	v_cvt_scalef32_pk_f32_fp4 v[4:5], v88, 1.0
	v_cvt_scalef32_pk_f32_fp4 v[6:7], v88, 1.0 op_sel:[1,0,0]
	v_cvt_scalef32_pk_f32_fp4 v[8:9], v88, 1.0 op_sel:[0,1,0]
	v_cvt_scalef32_pk_f32_fp4 v[10:11], v88, 1.0 op_sel:[1,1,0]
	v_pk_fma_f32 v[62:63], s[32:33], v[4:5], v[62:63] op_sel_hi:[0,1,1]
	v_pk_fma_f32 v[60:61], s[32:33], v[6:7], v[60:61] op_sel_hi:[0,1,1]
	v_pk_fma_f32 v[52:53], s[32:33], v[8:9], v[52:53] op_sel_hi:[0,1,1]
	v_pk_fma_f32 v[54:55], s[32:33], v[10:11], v[54:55] op_sel_hi:[0,1,1]
	v_cvt_scalef32_pk_f32_fp4 v[4:5], v89, 1.0
	v_cvt_scalef32_pk_f32_fp4 v[6:7], v89, 1.0 op_sel:[1,0,0]
	v_cvt_scalef32_pk_f32_fp4 v[8:9], v89, 1.0 op_sel:[0,1,0]
	v_cvt_scalef32_pk_f32_fp4 v[10:11], v89, 1.0 op_sel:[1,1,0]
	v_pk_fma_f32 v[56:57], s[32:33], v[4:5], v[56:57] op_sel_hi:[0,1,1]
	v_pk_fma_f32 v[58:59], s[32:33], v[6:7], v[58:59] op_sel_hi:[0,1,1]
	v_pk_fma_f32 v[50:51], s[32:33], v[8:9], v[50:51] op_sel_hi:[0,1,1]
	v_pk_fma_f32 v[48:49], s[32:33], v[10:11], v[48:49] op_sel_hi:[0,1,1]
	v_readlane_b32 s22, v13, 36
	s_add_u32 s16, s14, s22
	s_addc_u32 s17, s15, 0
	global_load_dwordx2 v[88:89], v213, s[16:17]
	v_readlane_b32 s34, v15, 21
	v_cvt_scalef32_pk_f32_fp4 v[4:5], v90, 1.0
	v_cvt_scalef32_pk_f32_fp4 v[6:7], v90, 1.0 op_sel:[1,0,0]
	v_cvt_scalef32_pk_f32_fp4 v[8:9], v90, 1.0 op_sel:[0,1,0]
	v_cvt_scalef32_pk_f32_fp4 v[10:11], v90, 1.0 op_sel:[1,1,0]
	v_pk_fma_f32 v[62:63], s[34:35], v[4:5], v[62:63] op_sel_hi:[0,1,1]
	v_pk_fma_f32 v[60:61], s[34:35], v[6:7], v[60:61] op_sel_hi:[0,1,1]
	v_pk_fma_f32 v[52:53], s[34:35], v[8:9], v[52:53] op_sel_hi:[0,1,1]
	v_pk_fma_f32 v[54:55], s[34:35], v[10:11], v[54:55] op_sel_hi:[0,1,1]
	v_cvt_scalef32_pk_f32_fp4 v[4:5], v91, 1.0
	v_cvt_scalef32_pk_f32_fp4 v[6:7], v91, 1.0 op_sel:[1,0,0]
	v_cvt_scalef32_pk_f32_fp4 v[8:9], v91, 1.0 op_sel:[0,1,0]
	v_cvt_scalef32_pk_f32_fp4 v[10:11], v91, 1.0 op_sel:[1,1,0]
	v_pk_fma_f32 v[56:57], s[34:35], v[4:5], v[56:57] op_sel_hi:[0,1,1]
	v_pk_fma_f32 v[58:59], s[34:35], v[6:7], v[58:59] op_sel_hi:[0,1,1]
	v_pk_fma_f32 v[50:51], s[34:35], v[8:9], v[50:51] op_sel_hi:[0,1,1]
	v_pk_fma_f32 v[48:49], s[34:35], v[10:11], v[48:49] op_sel_hi:[0,1,1]
	v_readlane_b32 s28, v13, 37
	s_add_u32 s20, s14, s28
	s_addc_u32 s21, s15, 0
	global_load_dwordx2 v[90:91], v213, s[20:21]
	v_readlane_b32 s32, v15, 22
	v_cvt_scalef32_pk_f32_fp4 v[4:5], v92, 1.0
	v_cvt_scalef32_pk_f32_fp4 v[6:7], v92, 1.0 op_sel:[1,0,0]
	v_cvt_scalef32_pk_f32_fp4 v[8:9], v92, 1.0 op_sel:[0,1,0]
	v_cvt_scalef32_pk_f32_fp4 v[10:11], v92, 1.0 op_sel:[1,1,0]
	v_pk_fma_f32 v[62:63], s[32:33], v[4:5], v[62:63] op_sel_hi:[0,1,1]
	v_pk_fma_f32 v[60:61], s[32:33], v[6:7], v[60:61] op_sel_hi:[0,1,1]
	v_pk_fma_f32 v[52:53], s[32:33], v[8:9], v[52:53] op_sel_hi:[0,1,1]
	v_pk_fma_f32 v[54:55], s[32:33], v[10:11], v[54:55] op_sel_hi:[0,1,1]
	v_cvt_scalef32_pk_f32_fp4 v[4:5], v93, 1.0
	v_cvt_scalef32_pk_f32_fp4 v[6:7], v93, 1.0 op_sel:[1,0,0]
	v_cvt_scalef32_pk_f32_fp4 v[8:9], v93, 1.0 op_sel:[0,1,0]
	v_cvt_scalef32_pk_f32_fp4 v[10:11], v93, 1.0 op_sel:[1,1,0]
	v_pk_fma_f32 v[56:57], s[32:33], v[4:5], v[56:57] op_sel_hi:[0,1,1]
	v_pk_fma_f32 v[58:59], s[32:33], v[6:7], v[58:59] op_sel_hi:[0,1,1]
	v_pk_fma_f32 v[50:51], s[32:33], v[8:9], v[50:51] op_sel_hi:[0,1,1]
	v_pk_fma_f32 v[48:49], s[32:33], v[10:11], v[48:49] op_sel_hi:[0,1,1]
	v_readlane_b32 s29, v13, 38
	s_add_u32 s24, s14, s29
	s_addc_u32 s25, s15, 0
	global_load_dwordx2 v[92:93], v213, s[24:25]
	v_readlane_b32 s34, v15, 23
	v_cvt_scalef32_pk_f32_fp4 v[4:5], v94, 1.0
	v_cvt_scalef32_pk_f32_fp4 v[6:7], v94, 1.0 op_sel:[1,0,0]
	v_cvt_scalef32_pk_f32_fp4 v[8:9], v94, 1.0 op_sel:[0,1,0]
	v_cvt_scalef32_pk_f32_fp4 v[10:11], v94, 1.0 op_sel:[1,1,0]
	v_pk_fma_f32 v[62:63], s[34:35], v[4:5], v[62:63] op_sel_hi:[0,1,1]
	v_pk_fma_f32 v[60:61], s[34:35], v[6:7], v[60:61] op_sel_hi:[0,1,1]
	v_pk_fma_f32 v[52:53], s[34:35], v[8:9], v[52:53] op_sel_hi:[0,1,1]
	v_pk_fma_f32 v[54:55], s[34:35], v[10:11], v[54:55] op_sel_hi:[0,1,1]
	v_cvt_scalef32_pk_f32_fp4 v[4:5], v95, 1.0
	v_cvt_scalef32_pk_f32_fp4 v[6:7], v95, 1.0 op_sel:[1,0,0]
	v_cvt_scalef32_pk_f32_fp4 v[8:9], v95, 1.0 op_sel:[0,1,0]
	v_cvt_scalef32_pk_f32_fp4 v[10:11], v95, 1.0 op_sel:[1,1,0]
	v_pk_fma_f32 v[56:57], s[34:35], v[4:5], v[56:57] op_sel_hi:[0,1,1]
	v_pk_fma_f32 v[58:59], s[34:35], v[6:7], v[58:59] op_sel_hi:[0,1,1]
	v_pk_fma_f32 v[50:51], s[34:35], v[8:9], v[50:51] op_sel_hi:[0,1,1]
	v_pk_fma_f32 v[48:49], s[34:35], v[10:11], v[48:49] op_sel_hi:[0,1,1]
	v_readlane_b32 s30, v13, 39
	s_add_u32 s26, s14, s30
	s_addc_u32 s27, s15, 0
	global_load_dwordx2 v[94:95], v213, s[26:27]
	s_waitcnt vmcnt(12)
; __device__ void peer_v(const P& p, int layer, int tok, bool dry) {
;     ...
;     for (int jb = 0; jb < 64; jb += 16) {
;       u32x2 vv[16];
; #pragma unroll
;       for (int q = 0; q < 16; ++q) {
;         const int e = __builtin_amdgcn_readlane(eidx[h2], jb + q);
;         vv[q] = ((const u32x2*)(V4 + (size_t)e * 512))[lane];
;       }
; #pragma unroll
;       for (int q = 0; q < 16; ++q) {
;         const float wq = rdlane_f(wreg[h2], jb + q);
;         const f32x2 w2 = {wq, wq};
; #pragma unroll
;         for (int k = 0; k < 2; ++k) {
;           oa2[4 * k + 0] += w2 * __builtin_amdgcn_cvt_scalef32_pk_f32_fp4(vv[q][k], 1.0f, 0);
;           oa2[4 * k + 1] += w2 * __builtin_amdgcn_cvt_scalef32_pk_f32_fp4(vv[q][k], 1.0f, 1);
;           oa2[4 * k + 2] += w2 * __builtin_amdgcn_cvt_scalef32_pk_f32_fp4(vv[q][k], 1.0f, 2);
;           oa2[4 * k + 3] += w2 * __builtin_amdgcn_cvt_scalef32_pk_f32_fp4(vv[q][k], 1.0f, 3);
;         }
;       }
	v_readlane_b32 s32, v15, 24
	v_cvt_scalef32_pk_f32_fp4 v[4:5], v96, 1.0
	v_cvt_scalef32_pk_f32_fp4 v[6:7], v96, 1.0 op_sel:[1,0,0]
	v_cvt_scalef32_pk_f32_fp4 v[8:9], v96, 1.0 op_sel:[0,1,0]
	v_cvt_scalef32_pk_f32_fp4 v[10:11], v96, 1.0 op_sel:[1,1,0]
	v_pk_fma_f32 v[62:63], s[32:33], v[4:5], v[62:63] op_sel_hi:[0,1,1]
	v_pk_fma_f32 v[60:61], s[32:33], v[6:7], v[60:61] op_sel_hi:[0,1,1]
	v_pk_fma_f32 v[52:53], s[32:33], v[8:9], v[52:53] op_sel_hi:[0,1,1]
	v_pk_fma_f32 v[54:55], s[32:33], v[10:11], v[54:55] op_sel_hi:[0,1,1]
	v_cvt_scalef32_pk_f32_fp4 v[4:5], v97, 1.0
	v_cvt_scalef32_pk_f32_fp4 v[6:7], v97, 1.0 op_sel:[1,0,0]
	v_cvt_scalef32_pk_f32_fp4 v[8:9], v97, 1.0 op_sel:[0,1,0]
	v_cvt_scalef32_pk_f32_fp4 v[10:11], v97, 1.0 op_sel:[1,1,0]
	v_pk_fma_f32 v[56:57], s[32:33], v[4:5], v[56:57] op_sel_hi:[0,1,1]
	v_pk_fma_f32 v[58:59], s[32:33], v[6:7], v[58:59] op_sel_hi:[0,1,1]
	v_pk_fma_f32 v[50:51], s[32:33], v[8:9], v[50:51] op_sel_hi:[0,1,1]
	v_pk_fma_f32 v[48:49], s[32:33], v[10:11], v[48:49] op_sel_hi:[0,1,1]
	v_readlane_b32 s22, v13, 40
	s_add_u32 s16, s14, s22
	s_addc_u32 s17, s15, 0
	global_load_dwordx2 v[96:97], v213, s[16:17]
	v_readlane_b32 s34, v15, 25
	v_cvt_scalef32_pk_f32_fp4 v[4:5], v98, 1.0
	v_cvt_scalef32_pk_f32_fp4 v[6:7], v98, 1.0 op_sel:[1,0,0]
	v_cvt_scalef32_pk_f32_fp4 v[8:9], v98, 1.0 op_sel:[0,1,0]
	v_cvt_scalef32_pk_f32_fp4 v[10:11], v98, 1.0 op_sel:[1,1,0]
	v_pk_fma_f32 v[62:63], s[34:35], v[4:5], v[62:63] op_sel_hi:[0,1,1]
	v_pk_fma_f32 v[60:61], s[34:35], v[6:7], v[60:61] op_sel_hi:[0,1,1]
	v_pk_fma_f32 v[52:53], s[34:35], v[8:9], v[52:53] op_sel_hi:[0,1,1]
	v_pk_fma_f32 v[54:55], s[34:35], v[10:11], v[54:55] op_sel_hi:[0,1,1]
	v_cvt_scalef32_pk_f32_fp4 v[4:5], v99, 1.0
	v_cvt_scalef32_pk_f32_fp4 v[6:7], v99, 1.0 op_sel:[1,0,0]
	v_cvt_scalef32_pk_f32_fp4 v[8:9], v99, 1.0 op_sel:[0,1,0]
	v_cvt_scalef32_pk_f32_fp4 v[10:11], v99, 1.0 op_sel:[1,1,0]
	v_pk_fma_f32 v[56:57], s[34:35], v[4:5], v[56:57] op_sel_hi:[0,1,1]
	v_pk_fma_f32 v[58:59], s[34:35], v[6:7], v[58:59] op_sel_hi:[0,1,1]
	v_pk_fma_f32 v[50:51], s[34:35], v[8:9], v[50:51] op_sel_hi:[0,1,1]
	v_pk_fma_f32 v[48:49], s[34:35], v[10:11], v[48:49] op_sel_hi:[0,1,1]
	v_readlane_b32 s28, v13, 41
	s_add_u32 s20, s14, s28
	s_addc_u32 s21, s15, 0
	global_load_dwordx2 v[98:99], v213, s[20:21]
	v_readlane_b32 s32, v15, 26
	v_cvt_scalef32_pk_f32_fp4 v[4:5], v100, 1.0
	v_cvt_scalef32_pk_f32_fp4 v[6:7], v100, 1.0 op_sel:[1,0,0]
	v_cvt_scalef32_pk_f32_fp4 v[8:9], v100, 1.0 op_sel:[0,1,0]
	v_cvt_scalef32_pk_f32_fp4 v[10:11], v100, 1.0 op_sel:[1,1,0]
	v_pk_fma_f32 v[62:63], s[32:33], v[4:5], v[62:63] op_sel_hi:[0,1,1]
	v_pk_fma_f32 v[60:61], s[32:33], v[6:7], v[60:61] op_sel_hi:[0,1,1]
	v_pk_fma_f32 v[52:53], s[32:33], v[8:9], v[52:53] op_sel_hi:[0,1,1]
	v_pk_fma_f32 v[54:55], s[32:33], v[10:11], v[54:55] op_sel_hi:[0,1,1]
	v_cvt_scalef32_pk_f32_fp4 v[4:5], v101, 1.0
	v_cvt_scalef32_pk_f32_fp4 v[6:7], v101, 1.0 op_sel:[1,0,0]
	v_cvt_scalef32_pk_f32_fp4 v[8:9], v101, 1.0 op_sel:[0,1,0]
	v_cvt_scalef32_pk_f32_fp4 v[10:11], v101, 1.0 op_sel:[1,1,0]
	v_pk_fma_f32 v[56:57], s[32:33], v[4:5], v[56:57] op_sel_hi:[0,1,1]
	v_pk_fma_f32 v[58:59], s[32:33], v[6:7], v[58:59] op_sel_hi:[0,1,1]
	v_pk_fma_f32 v[50:51], s[32:33], v[8:9], v[50:51] op_sel_hi:[0,1,1]
	v_pk_fma_f32 v[48:49], s[32:33], v[10:11], v[48:49] op_sel_hi:[0,1,1]
	v_readlane_b32 s29, v13, 42
	s_add_u32 s24, s14, s29
	s_addc_u32 s25, s15, 0
	global_load_dwordx2 v[100:101], v213, s[24:25]
	v_readlane_b32 s34, v15, 27
	v_cvt_scalef32_pk_f32_fp4 v[4:5], v102, 1.0
	v_cvt_scalef32_pk_f32_fp4 v[6:7], v102, 1.0 op_sel:[1,0,0]
	v_cvt_scalef32_pk_f32_fp4 v[8:9], v102, 1.0 op_sel:[0,1,0]
	v_cvt_scalef32_pk_f32_fp4 v[10:11], v102, 1.0 op_sel:[1,1,0]
	v_pk_fma_f32 v[62:63], s[34:35], v[4:5], v[62:63] op_sel_hi:[0,1,1]
	v_pk_fma_f32 v[60:61], s[34:35], v[6:7], v[60:61] op_sel_hi:[0,1,1]
	v_pk_fma_f32 v[52:53], s[34:35], v[8:9], v[52:53] op_sel_hi:[0,1,1]
	v_pk_fma_f32 v[54:55], s[34:35], v[10:11], v[54:55] op_sel_hi:[0,1,1]
	v_cvt_scalef32_pk_f32_fp4 v[4:5], v103, 1.0
	v_cvt_scalef32_pk_f32_fp4 v[6:7], v103, 1.0 op_sel:[1,0,0]
	v_cvt_scalef32_pk_f32_fp4 v[8:9], v103, 1.0 op_sel:[0,1,0]
	v_cvt_scalef32_pk_f32_fp4 v[10:11], v103, 1.0 op_sel:[1,1,0]
	v_pk_fma_f32 v[56:57], s[34:35], v[4:5], v[56:57] op_sel_hi:[0,1,1]
	v_pk_fma_f32 v[58:59], s[34:35], v[6:7], v[58:59] op_sel_hi:[0,1,1]
	v_pk_fma_f32 v[50:51], s[34:35], v[8:9], v[50:51] op_sel_hi:[0,1,1]
	v_pk_fma_f32 v[48:49], s[34:35], v[10:11], v[48:49] op_sel_hi:[0,1,1]
	v_readlane_b32 s30, v13, 43
	s_add_u32 s26, s14, s30
	s_addc_u32 s27, s15, 0
	global_load_dwordx2 v[102:103], v213, s[26:27]
	s_waitcnt vmcnt(12)
; __device__ void peer_v(const P& p, int layer, int tok, bool dry) {
;     ...
;     for (int jb = 0; jb < 64; jb += 16) {
;       u32x2 vv[16];
; #pragma unroll
;       for (int q = 0; q < 16; ++q) {
;         const int e = __builtin_amdgcn_readlane(eidx[h2], jb + q);
;         vv[q] = ((const u32x2*)(V4 + (size_t)e * 512))[lane];
;       }
; #pragma unroll
;       for (int q = 0; q < 16; ++q) {
;         const float wq = rdlane_f(wreg[h2], jb + q);
;         const f32x2 w2 = {wq, wq};
; #pragma unroll
;         for (int k = 0; k < 2; ++k) {
;           oa2[4 * k + 0] += w2 * __builtin_amdgcn_cvt_scalef32_pk_f32_fp4(vv[q][k], 1.0f, 0);
;           oa2[4 * k + 1] += w2 * __builtin_amdgcn_cvt_scalef32_pk_f32_fp4(vv[q][k], 1.0f, 1);
;           oa2[4 * k + 2] += w2 * __builtin_amdgcn_cvt_scalef32_pk_f32_fp4(vv[q][k], 1.0f, 2);
;           oa2[4 * k + 3] += w2 * __builtin_amdgcn_cvt_scalef32_pk_f32_fp4(vv[q][k], 1.0f, 3);
;         }
;       }
	v_readlane_b32 s32, v15, 28
	v_cvt_scalef32_pk_f32_fp4 v[4:5], v104, 1.0
	v_cvt_scalef32_pk_f32_fp4 v[6:7], v104, 1.0 op_sel:[1,0,0]
	v_cvt_scalef32_pk_f32_fp4 v[8:9], v104, 1.0 op_sel:[0,1,0]
	v_cvt_scalef32_pk_f32_fp4 v[10:11], v104, 1.0 op_sel:[1,1,0]
	v_pk_fma_f32 v[62:63], s[32:33], v[4:5], v[62:63] op_sel_hi:[0,1,1]
	v_pk_fma_f32 v[60:61], s[32:33], v[6:7], v[60:61] op_sel_hi:[0,1,1]
	v_pk_fma_f32 v[52:53], s[32:33], v[8:9], v[52:53] op_sel_hi:[0,1,1]
	v_pk_fma_f32 v[54:55], s[32:33], v[10:11], v[54:55] op_sel_hi:[0,1,1]
	v_cvt_scalef32_pk_f32_fp4 v[4:5], v105, 1.0
	v_cvt_scalef32_pk_f32_fp4 v[6:7], v105, 1.0 op_sel:[1,0,0]
	v_cvt_scalef32_pk_f32_fp4 v[8:9], v105, 1.0 op_sel:[0,1,0]
	v_cvt_scalef32_pk_f32_fp4 v[10:11], v105, 1.0 op_sel:[1,1,0]
	v_pk_fma_f32 v[56:57], s[32:33], v[4:5], v[56:57] op_sel_hi:[0,1,1]
	v_pk_fma_f32 v[58:59], s[32:33], v[6:7], v[58:59] op_sel_hi:[0,1,1]
	v_pk_fma_f32 v[50:51], s[32:33], v[8:9], v[50:51] op_sel_hi:[0,1,1]
	v_pk_fma_f32 v[48:49], s[32:33], v[10:11], v[48:49] op_sel_hi:[0,1,1]
	v_readlane_b32 s22, v13, 44
	s_add_u32 s16, s14, s22
	s_addc_u32 s17, s15, 0
	global_load_dwordx2 v[104:105], v213, s[16:17]
	v_readlane_b32 s34, v15, 29
	v_cvt_scalef32_pk_f32_fp4 v[4:5], v106, 1.0
	v_cvt_scalef32_pk_f32_fp4 v[6:7], v106, 1.0 op_sel:[1,0,0]
	v_cvt_scalef32_pk_f32_fp4 v[8:9], v106, 1.0 op_sel:[0,1,0]
	v_cvt_scalef32_pk_f32_fp4 v[10:11], v106, 1.0 op_sel:[1,1,0]
	v_pk_fma_f32 v[62:63], s[34:35], v[4:5], v[62:63] op_sel_hi:[0,1,1]
	v_pk_fma_f32 v[60:61], s[34:35], v[6:7], v[60:61] op_sel_hi:[0,1,1]
	v_pk_fma_f32 v[52:53], s[34:35], v[8:9], v[52:53] op_sel_hi:[0,1,1]
	v_pk_fma_f32 v[54:55], s[34:35], v[10:11], v[54:55] op_sel_hi:[0,1,1]
	v_cvt_scalef32_pk_f32_fp4 v[4:5], v107, 1.0
	v_cvt_scalef32_pk_f32_fp4 v[6:7], v107, 1.0 op_sel:[1,0,0]
	v_cvt_scalef32_pk_f32_fp4 v[8:9], v107, 1.0 op_sel:[0,1,0]
	v_cvt_scalef32_pk_f32_fp4 v[10:11], v107, 1.0 op_sel:[1,1,0]
	v_pk_fma_f32 v[56:57], s[34:35], v[4:5], v[56:57] op_sel_hi:[0,1,1]
	v_pk_fma_f32 v[58:59], s[34:35], v[6:7], v[58:59] op_sel_hi:[0,1,1]
	v_pk_fma_f32 v[50:51], s[34:35], v[8:9], v[50:51] op_sel_hi:[0,1,1]
	v_pk_fma_f32 v[48:49], s[34:35], v[10:11], v[48:49] op_sel_hi:[0,1,1]
	v_readlane_b32 s28, v13, 45
	s_add_u32 s20, s14, s28
	s_addc_u32 s21, s15, 0
	global_load_dwordx2 v[106:107], v213, s[20:21]
	v_readlane_b32 s32, v15, 30
	v_cvt_scalef32_pk_f32_fp4 v[4:5], v108, 1.0
	v_cvt_scalef32_pk_f32_fp4 v[6:7], v108, 1.0 op_sel:[1,0,0]
	v_cvt_scalef32_pk_f32_fp4 v[8:9], v108, 1.0 op_sel:[0,1,0]
	v_cvt_scalef32_pk_f32_fp4 v[10:11], v108, 1.0 op_sel:[1,1,0]
	v_pk_fma_f32 v[62:63], s[32:33], v[4:5], v[62:63] op_sel_hi:[0,1,1]
	v_pk_fma_f32 v[60:61], s[32:33], v[6:7], v[60:61] op_sel_hi:[0,1,1]
	v_pk_fma_f32 v[52:53], s[32:33], v[8:9], v[52:53] op_sel_hi:[0,1,1]
	v_pk_fma_f32 v[54:55], s[32:33], v[10:11], v[54:55] op_sel_hi:[0,1,1]
	v_cvt_scalef32_pk_f32_fp4 v[4:5], v109, 1.0
	v_cvt_scalef32_pk_f32_fp4 v[6:7], v109, 1.0 op_sel:[1,0,0]
	v_cvt_scalef32_pk_f32_fp4 v[8:9], v109, 1.0 op_sel:[0,1,0]
	v_cvt_scalef32_pk_f32_fp4 v[10:11], v109, 1.0 op_sel:[1,1,0]
	v_pk_fma_f32 v[56:57], s[32:33], v[4:5], v[56:57] op_sel_hi:[0,1,1]
	v_pk_fma_f32 v[58:59], s[32:33], v[6:7], v[58:59] op_sel_hi:[0,1,1]
	v_pk_fma_f32 v[50:51], s[32:33], v[8:9], v[50:51] op_sel_hi:[0,1,1]
	v_pk_fma_f32 v[48:49], s[32:33], v[10:11], v[48:49] op_sel_hi:[0,1,1]
	v_readlane_b32 s29, v13, 46
	s_add_u32 s24, s14, s29
	s_addc_u32 s25, s15, 0
	global_load_dwordx2 v[108:109], v213, s[24:25]
	v_readlane_b32 s34, v15, 31
	v_cvt_scalef32_pk_f32_fp4 v[4:5], v110, 1.0
	v_cvt_scalef32_pk_f32_fp4 v[6:7], v110, 1.0 op_sel:[1,0,0]
	v_cvt_scalef32_pk_f32_fp4 v[8:9], v110, 1.0 op_sel:[0,1,0]
	v_cvt_scalef32_pk_f32_fp4 v[10:11], v110, 1.0 op_sel:[1,1,0]
	v_pk_fma_f32 v[62:63], s[34:35], v[4:5], v[62:63] op_sel_hi:[0,1,1]
	v_pk_fma_f32 v[60:61], s[34:35], v[6:7], v[60:61] op_sel_hi:[0,1,1]
	v_pk_fma_f32 v[52:53], s[34:35], v[8:9], v[52:53] op_sel_hi:[0,1,1]
	v_pk_fma_f32 v[54:55], s[34:35], v[10:11], v[54:55] op_sel_hi:[0,1,1]
	v_cvt_scalef32_pk_f32_fp4 v[4:5], v111, 1.0
	v_cvt_scalef32_pk_f32_fp4 v[6:7], v111, 1.0 op_sel:[1,0,0]
	v_cvt_scalef32_pk_f32_fp4 v[8:9], v111, 1.0 op_sel:[0,1,0]
	v_cvt_scalef32_pk_f32_fp4 v[10:11], v111, 1.0 op_sel:[1,1,0]
	v_pk_fma_f32 v[56:57], s[34:35], v[4:5], v[56:57] op_sel_hi:[0,1,1]
	v_pk_fma_f32 v[58:59], s[34:35], v[6:7], v[58:59] op_sel_hi:[0,1,1]
	v_pk_fma_f32 v[50:51], s[34:35], v[8:9], v[50:51] op_sel_hi:[0,1,1]
	v_pk_fma_f32 v[48:49], s[34:35], v[10:11], v[48:49] op_sel_hi:[0,1,1]
	v_readlane_b32 s30, v13, 47
	s_add_u32 s26, s14, s30
	s_addc_u32 s27, s15, 0
	global_load_dwordx2 v[110:111], v213, s[26:27]
	s_waitcnt vmcnt(12)
; __device__ void peer_v(const P& p, int layer, int tok, bool dry) {
;     ...
;     for (int jb = 0; jb < 64; jb += 16) {
;       u32x2 vv[16];
; #pragma unroll
;       for (int q = 0; q < 16; ++q) {
;         const int e = __builtin_amdgcn_readlane(eidx[h2], jb + q);
;         vv[q] = ((const u32x2*)(V4 + (size_t)e * 512))[lane];
;       }
; #pragma unroll
;       for (int q = 0; q < 16; ++q) {
;         const float wq = rdlane_f(wreg[h2], jb + q);
;         const f32x2 w2 = {wq, wq};
; #pragma unroll
;         for (int k = 0; k < 2; ++k) {
;           oa2[4 * k + 0] += w2 * __builtin_amdgcn_cvt_scalef32_pk_f32_fp4(vv[q][k], 1.0f, 0);
;           oa2[4 * k + 1] += w2 * __builtin_amdgcn_cvt_scalef32_pk_f32_fp4(vv[q][k], 1.0f, 1);
;           oa2[4 * k + 2] += w2 * __builtin_amdgcn_cvt_scalef32_pk_f32_fp4(vv[q][k], 1.0f, 2);
;           oa2[4 * k + 3] += w2 * __builtin_amdgcn_cvt_scalef32_pk_f32_fp4(vv[q][k], 1.0f, 3);
;         }
;       }
	v_readlane_b32 s32, v15, 32
	v_cvt_scalef32_pk_f32_fp4 v[4:5], v80, 1.0
	v_cvt_scalef32_pk_f32_fp4 v[6:7], v80, 1.0 op_sel:[1,0,0]
	v_cvt_scalef32_pk_f32_fp4 v[8:9], v80, 1.0 op_sel:[0,1,0]
	v_cvt_scalef32_pk_f32_fp4 v[10:11], v80, 1.0 op_sel:[1,1,0]
	v_pk_fma_f32 v[62:63], s[32:33], v[4:5], v[62:63] op_sel_hi:[0,1,1]
	v_pk_fma_f32 v[60:61], s[32:33], v[6:7], v[60:61] op_sel_hi:[0,1,1]
	v_pk_fma_f32 v[52:53], s[32:33], v[8:9], v[52:53] op_sel_hi:[0,1,1]
	v_pk_fma_f32 v[54:55], s[32:33], v[10:11], v[54:55] op_sel_hi:[0,1,1]
	v_cvt_scalef32_pk_f32_fp4 v[4:5], v81, 1.0
	v_cvt_scalef32_pk_f32_fp4 v[6:7], v81, 1.0 op_sel:[1,0,0]
	v_cvt_scalef32_pk_f32_fp4 v[8:9], v81, 1.0 op_sel:[0,1,0]
	v_cvt_scalef32_pk_f32_fp4 v[10:11], v81, 1.0 op_sel:[1,1,0]
	v_pk_fma_f32 v[56:57], s[32:33], v[4:5], v[56:57] op_sel_hi:[0,1,1]
	v_pk_fma_f32 v[58:59], s[32:33], v[6:7], v[58:59] op_sel_hi:[0,1,1]
	v_pk_fma_f32 v[50:51], s[32:33], v[8:9], v[50:51] op_sel_hi:[0,1,1]
	v_pk_fma_f32 v[48:49], s[32:33], v[10:11], v[48:49] op_sel_hi:[0,1,1]
	v_readlane_b32 s22, v13, 48
	s_add_u32 s16, s14, s22
	s_addc_u32 s17, s15, 0
	global_load_dwordx2 v[80:81], v213, s[16:17]
	v_readlane_b32 s34, v15, 33
	v_cvt_scalef32_pk_f32_fp4 v[4:5], v82, 1.0
	v_cvt_scalef32_pk_f32_fp4 v[6:7], v82, 1.0 op_sel:[1,0,0]
	v_cvt_scalef32_pk_f32_fp4 v[8:9], v82, 1.0 op_sel:[0,1,0]
	v_cvt_scalef32_pk_f32_fp4 v[10:11], v82, 1.0 op_sel:[1,1,0]
	v_pk_fma_f32 v[62:63], s[34:35], v[4:5], v[62:63] op_sel_hi:[0,1,1]
	v_pk_fma_f32 v[60:61], s[34:35], v[6:7], v[60:61] op_sel_hi:[0,1,1]
	v_pk_fma_f32 v[52:53], s[34:35], v[8:9], v[52:53] op_sel_hi:[0,1,1]
	v_pk_fma_f32 v[54:55], s[34:35], v[10:11], v[54:55] op_sel_hi:[0,1,1]
	v_cvt_scalef32_pk_f32_fp4 v[4:5], v83, 1.0
	v_cvt_scalef32_pk_f32_fp4 v[6:7], v83, 1.0 op_sel:[1,0,0]
	v_cvt_scalef32_pk_f32_fp4 v[8:9], v83, 1.0 op_sel:[0,1,0]
	v_cvt_scalef32_pk_f32_fp4 v[10:11], v83, 1.0 op_sel:[1,1,0]
	v_pk_fma_f32 v[56:57], s[34:35], v[4:5], v[56:57] op_sel_hi:[0,1,1]
	v_pk_fma_f32 v[58:59], s[34:35], v[6:7], v[58:59] op_sel_hi:[0,1,1]
	v_pk_fma_f32 v[50:51], s[34:35], v[8:9], v[50:51] op_sel_hi:[0,1,1]
	v_pk_fma_f32 v[48:49], s[34:35], v[10:11], v[48:49] op_sel_hi:[0,1,1]
	v_readlane_b32 s28, v13, 49
	s_add_u32 s20, s14, s28
	s_addc_u32 s21, s15, 0
	global_load_dwordx2 v[82:83], v213, s[20:21]
	v_readlane_b32 s32, v15, 34
	v_cvt_scalef32_pk_f32_fp4 v[4:5], v84, 1.0
	v_cvt_scalef32_pk_f32_fp4 v[6:7], v84, 1.0 op_sel:[1,0,0]
	v_cvt_scalef32_pk_f32_fp4 v[8:9], v84, 1.0 op_sel:[0,1,0]
	v_cvt_scalef32_pk_f32_fp4 v[10:11], v84, 1.0 op_sel:[1,1,0]
	v_pk_fma_f32 v[62:63], s[32:33], v[4:5], v[62:63] op_sel_hi:[0,1,1]
	v_pk_fma_f32 v[60:61], s[32:33], v[6:7], v[60:61] op_sel_hi:[0,1,1]
	v_pk_fma_f32 v[52:53], s[32:33], v[8:9], v[52:53] op_sel_hi:[0,1,1]
	v_pk_fma_f32 v[54:55], s[32:33], v[10:11], v[54:55] op_sel_hi:[0,1,1]
	v_cvt_scalef32_pk_f32_fp4 v[4:5], v85, 1.0
	v_cvt_scalef32_pk_f32_fp4 v[6:7], v85, 1.0 op_sel:[1,0,0]
	v_cvt_scalef32_pk_f32_fp4 v[8:9], v85, 1.0 op_sel:[0,1,0]
	v_cvt_scalef32_pk_f32_fp4 v[10:11], v85, 1.0 op_sel:[1,1,0]
	v_pk_fma_f32 v[56:57], s[32:33], v[4:5], v[56:57] op_sel_hi:[0,1,1]
	v_pk_fma_f32 v[58:59], s[32:33], v[6:7], v[58:59] op_sel_hi:[0,1,1]
	v_pk_fma_f32 v[50:51], s[32:33], v[8:9], v[50:51] op_sel_hi:[0,1,1]
	v_pk_fma_f32 v[48:49], s[32:33], v[10:11], v[48:49] op_sel_hi:[0,1,1]
	v_readlane_b32 s29, v13, 50
	s_add_u32 s24, s14, s29
	s_addc_u32 s25, s15, 0
	global_load_dwordx2 v[84:85], v213, s[24:25]
	v_readlane_b32 s34, v15, 35
	v_cvt_scalef32_pk_f32_fp4 v[4:5], v86, 1.0
	v_cvt_scalef32_pk_f32_fp4 v[6:7], v86, 1.0 op_sel:[1,0,0]
	v_cvt_scalef32_pk_f32_fp4 v[8:9], v86, 1.0 op_sel:[0,1,0]
	v_cvt_scalef32_pk_f32_fp4 v[10:11], v86, 1.0 op_sel:[1,1,0]
	v_pk_fma_f32 v[62:63], s[34:35], v[4:5], v[62:63] op_sel_hi:[0,1,1]
	v_pk_fma_f32 v[60:61], s[34:35], v[6:7], v[60:61] op_sel_hi:[0,1,1]
	v_pk_fma_f32 v[52:53], s[34:35], v[8:9], v[52:53] op_sel_hi:[0,1,1]
	v_pk_fma_f32 v[54:55], s[34:35], v[10:11], v[54:55] op_sel_hi:[0,1,1]
	v_cvt_scalef32_pk_f32_fp4 v[4:5], v87, 1.0
	v_cvt_scalef32_pk_f32_fp4 v[6:7], v87, 1.0 op_sel:[1,0,0]
	v_cvt_scalef32_pk_f32_fp4 v[8:9], v87, 1.0 op_sel:[0,1,0]
	v_cvt_scalef32_pk_f32_fp4 v[10:11], v87, 1.0 op_sel:[1,1,0]
	v_pk_fma_f32 v[56:57], s[34:35], v[4:5], v[56:57] op_sel_hi:[0,1,1]
	v_pk_fma_f32 v[58:59], s[34:35], v[6:7], v[58:59] op_sel_hi:[0,1,1]
	v_pk_fma_f32 v[50:51], s[34:35], v[8:9], v[50:51] op_sel_hi:[0,1,1]
	v_pk_fma_f32 v[48:49], s[34:35], v[10:11], v[48:49] op_sel_hi:[0,1,1]
	v_readlane_b32 s30, v13, 51
	s_add_u32 s26, s14, s30
	s_addc_u32 s27, s15, 0
	global_load_dwordx2 v[86:87], v213, s[26:27]
	s_waitcnt vmcnt(12)
; __device__ void peer_v(const P& p, int layer, int tok, bool dry) {
;     ...
;     for (int jb = 0; jb < 64; jb += 16) {
;       u32x2 vv[16];
; #pragma unroll
;       for (int q = 0; q < 16; ++q) {
;         const int e = __builtin_amdgcn_readlane(eidx[h2], jb + q);
;         vv[q] = ((const u32x2*)(V4 + (size_t)e * 512))[lane];
;       }
; #pragma unroll
;       for (int q = 0; q < 16; ++q) {
;         const float wq = rdlane_f(wreg[h2], jb + q);
;         const f32x2 w2 = {wq, wq};
; #pragma unroll
;         for (int k = 0; k < 2; ++k) {
;           oa2[4 * k + 0] += w2 * __builtin_amdgcn_cvt_scalef32_pk_f32_fp4(vv[q][k], 1.0f, 0);
;           oa2[4 * k + 1] += w2 * __builtin_amdgcn_cvt_scalef32_pk_f32_fp4(vv[q][k], 1.0f, 1);
;           oa2[4 * k + 2] += w2 * __builtin_amdgcn_cvt_scalef32_pk_f32_fp4(vv[q][k], 1.0f, 2);
;           oa2[4 * k + 3] += w2 * __builtin_amdgcn_cvt_scalef32_pk_f32_fp4(vv[q][k], 1.0f, 3);
;         }
;       }
	v_readlane_b32 s32, v15, 36
	v_cvt_scalef32_pk_f32_fp4 v[4:5], v88, 1.0
	v_cvt_scalef32_pk_f32_fp4 v[6:7], v88, 1.0 op_sel:[1,0,0]
	v_cvt_scalef32_pk_f32_fp4 v[8:9], v88, 1.0 op_sel:[0,1,0]
	v_cvt_scalef32_pk_f32_fp4 v[10:11], v88, 1.0 op_sel:[1,1,0]
	v_pk_fma_f32 v[62:63], s[32:33], v[4:5], v[62:63] op_sel_hi:[0,1,1]
	v_pk_fma_f32 v[60:61], s[32:33], v[6:7], v[60:61] op_sel_hi:[0,1,1]
	v_pk_fma_f32 v[52:53], s[32:33], v[8:9], v[52:53] op_sel_hi:[0,1,1]
	v_pk_fma_f32 v[54:55], s[32:33], v[10:11], v[54:55] op_sel_hi:[0,1,1]
	v_cvt_scalef32_pk_f32_fp4 v[4:5], v89, 1.0
	v_cvt_scalef32_pk_f32_fp4 v[6:7], v89, 1.0 op_sel:[1,0,0]
	v_cvt_scalef32_pk_f32_fp4 v[8:9], v89, 1.0 op_sel:[0,1,0]
	v_cvt_scalef32_pk_f32_fp4 v[10:11], v89, 1.0 op_sel:[1,1,0]
	v_pk_fma_f32 v[56:57], s[32:33], v[4:5], v[56:57] op_sel_hi:[0,1,1]
	v_pk_fma_f32 v[58:59], s[32:33], v[6:7], v[58:59] op_sel_hi:[0,1,1]
	v_pk_fma_f32 v[50:51], s[32:33], v[8:9], v[50:51] op_sel_hi:[0,1,1]
	v_pk_fma_f32 v[48:49], s[32:33], v[10:11], v[48:49] op_sel_hi:[0,1,1]
	v_readlane_b32 s22, v13, 52
	s_add_u32 s16, s14, s22
	s_addc_u32 s17, s15, 0
	global_load_dwordx2 v[88:89], v213, s[16:17]
	v_readlane_b32 s34, v15, 37
	v_cvt_scalef32_pk_f32_fp4 v[4:5], v90, 1.0
	v_cvt_scalef32_pk_f32_fp4 v[6:7], v90, 1.0 op_sel:[1,0,0]
	v_cvt_scalef32_pk_f32_fp4 v[8:9], v90, 1.0 op_sel:[0,1,0]
	v_cvt_scalef32_pk_f32_fp4 v[10:11], v90, 1.0 op_sel:[1,1,0]
	v_pk_fma_f32 v[62:63], s[34:35], v[4:5], v[62:63] op_sel_hi:[0,1,1]
	v_pk_fma_f32 v[60:61], s[34:35], v[6:7], v[60:61] op_sel_hi:[0,1,1]
	v_pk_fma_f32 v[52:53], s[34:35], v[8:9], v[52:53] op_sel_hi:[0,1,1]
	v_pk_fma_f32 v[54:55], s[34:35], v[10:11], v[54:55] op_sel_hi:[0,1,1]
	v_cvt_scalef32_pk_f32_fp4 v[4:5], v91, 1.0
	v_cvt_scalef32_pk_f32_fp4 v[6:7], v91, 1.0 op_sel:[1,0,0]
	v_cvt_scalef32_pk_f32_fp4 v[8:9], v91, 1.0 op_sel:[0,1,0]
	v_cvt_scalef32_pk_f32_fp4 v[10:11], v91, 1.0 op_sel:[1,1,0]
	v_pk_fma_f32 v[56:57], s[34:35], v[4:5], v[56:57] op_sel_hi:[0,1,1]
	v_pk_fma_f32 v[58:59], s[34:35], v[6:7], v[58:59] op_sel_hi:[0,1,1]
	v_pk_fma_f32 v[50:51], s[34:35], v[8:9], v[50:51] op_sel_hi:[0,1,1]
	v_pk_fma_f32 v[48:49], s[34:35], v[10:11], v[48:49] op_sel_hi:[0,1,1]
	v_readlane_b32 s28, v13, 53
	s_add_u32 s20, s14, s28
	s_addc_u32 s21, s15, 0
	global_load_dwordx2 v[90:91], v213, s[20:21]
	v_readlane_b32 s32, v15, 38
	v_cvt_scalef32_pk_f32_fp4 v[4:5], v92, 1.0
	v_cvt_scalef32_pk_f32_fp4 v[6:7], v92, 1.0 op_sel:[1,0,0]
	v_cvt_scalef32_pk_f32_fp4 v[8:9], v92, 1.0 op_sel:[0,1,0]
	v_cvt_scalef32_pk_f32_fp4 v[10:11], v92, 1.0 op_sel:[1,1,0]
	v_pk_fma_f32 v[62:63], s[32:33], v[4:5], v[62:63] op_sel_hi:[0,1,1]
	v_pk_fma_f32 v[60:61], s[32:33], v[6:7], v[60:61] op_sel_hi:[0,1,1]
	v_pk_fma_f32 v[52:53], s[32:33], v[8:9], v[52:53] op_sel_hi:[0,1,1]
	v_pk_fma_f32 v[54:55], s[32:33], v[10:11], v[54:55] op_sel_hi:[0,1,1]
	v_cvt_scalef32_pk_f32_fp4 v[4:5], v93, 1.0
	v_cvt_scalef32_pk_f32_fp4 v[6:7], v93, 1.0 op_sel:[1,0,0]
	v_cvt_scalef32_pk_f32_fp4 v[8:9], v93, 1.0 op_sel:[0,1,0]
	v_cvt_scalef32_pk_f32_fp4 v[10:11], v93, 1.0 op_sel:[1,1,0]
	v_pk_fma_f32 v[56:57], s[32:33], v[4:5], v[56:57] op_sel_hi:[0,1,1]
	v_pk_fma_f32 v[58:59], s[32:33], v[6:7], v[58:59] op_sel_hi:[0,1,1]
	v_pk_fma_f32 v[50:51], s[32:33], v[8:9], v[50:51] op_sel_hi:[0,1,1]
	v_pk_fma_f32 v[48:49], s[32:33], v[10:11], v[48:49] op_sel_hi:[0,1,1]
	v_readlane_b32 s29, v13, 54
	s_add_u32 s24, s14, s29
	s_addc_u32 s25, s15, 0
	global_load_dwordx2 v[92:93], v213, s[24:25]
	v_readlane_b32 s34, v15, 39
	v_cvt_scalef32_pk_f32_fp4 v[4:5], v94, 1.0
	v_cvt_scalef32_pk_f32_fp4 v[6:7], v94, 1.0 op_sel:[1,0,0]
	v_cvt_scalef32_pk_f32_fp4 v[8:9], v94, 1.0 op_sel:[0,1,0]
	v_cvt_scalef32_pk_f32_fp4 v[10:11], v94, 1.0 op_sel:[1,1,0]
	v_pk_fma_f32 v[62:63], s[34:35], v[4:5], v[62:63] op_sel_hi:[0,1,1]
	v_pk_fma_f32 v[60:61], s[34:35], v[6:7], v[60:61] op_sel_hi:[0,1,1]
	v_pk_fma_f32 v[52:53], s[34:35], v[8:9], v[52:53] op_sel_hi:[0,1,1]
	v_pk_fma_f32 v[54:55], s[34:35], v[10:11], v[54:55] op_sel_hi:[0,1,1]
	v_cvt_scalef32_pk_f32_fp4 v[4:5], v95, 1.0
	v_cvt_scalef32_pk_f32_fp4 v[6:7], v95, 1.0 op_sel:[1,0,0]
	v_cvt_scalef32_pk_f32_fp4 v[8:9], v95, 1.0 op_sel:[0,1,0]
	v_cvt_scalef32_pk_f32_fp4 v[10:11], v95, 1.0 op_sel:[1,1,0]
	v_pk_fma_f32 v[56:57], s[34:35], v[4:5], v[56:57] op_sel_hi:[0,1,1]
	v_pk_fma_f32 v[58:59], s[34:35], v[6:7], v[58:59] op_sel_hi:[0,1,1]
	v_pk_fma_f32 v[50:51], s[34:35], v[8:9], v[50:51] op_sel_hi:[0,1,1]
	v_pk_fma_f32 v[48:49], s[34:35], v[10:11], v[48:49] op_sel_hi:[0,1,1]
	v_readlane_b32 s30, v13, 55
	s_add_u32 s26, s14, s30
	s_addc_u32 s27, s15, 0
	global_load_dwordx2 v[94:95], v213, s[26:27]
	s_waitcnt vmcnt(12)
; __device__ void peer_v(const P& p, int layer, int tok, bool dry) {
;     ...
;     for (int jb = 0; jb < 64; jb += 16) {
;       u32x2 vv[16];
; #pragma unroll
;       for (int q = 0; q < 16; ++q) {
;         const int e = __builtin_amdgcn_readlane(eidx[h2], jb + q);
;         vv[q] = ((const u32x2*)(V4 + (size_t)e * 512))[lane];
;       }
; #pragma unroll
;       for (int q = 0; q < 16; ++q) {
;         const float wq = rdlane_f(wreg[h2], jb + q);
;         const f32x2 w2 = {wq, wq};
; #pragma unroll
;         for (int k = 0; k < 2; ++k) {
;           oa2[4 * k + 0] += w2 * __builtin_amdgcn_cvt_scalef32_pk_f32_fp4(vv[q][k], 1.0f, 0);
;           oa2[4 * k + 1] += w2 * __builtin_amdgcn_cvt_scalef32_pk_f32_fp4(vv[q][k], 1.0f, 1);
;           oa2[4 * k + 2] += w2 * __builtin_amdgcn_cvt_scalef32_pk_f32_fp4(vv[q][k], 1.0f, 2);
;           oa2[4 * k + 3] += w2 * __builtin_amdgcn_cvt_scalef32_pk_f32_fp4(vv[q][k], 1.0f, 3);
;         }
;       }
	v_readlane_b32 s32, v15, 40
	v_cvt_scalef32_pk_f32_fp4 v[4:5], v96, 1.0
	v_cvt_scalef32_pk_f32_fp4 v[6:7], v96, 1.0 op_sel:[1,0,0]
	v_cvt_scalef32_pk_f32_fp4 v[8:9], v96, 1.0 op_sel:[0,1,0]
	v_cvt_scalef32_pk_f32_fp4 v[10:11], v96, 1.0 op_sel:[1,1,0]
	v_pk_fma_f32 v[62:63], s[32:33], v[4:5], v[62:63] op_sel_hi:[0,1,1]
	v_pk_fma_f32 v[60:61], s[32:33], v[6:7], v[60:61] op_sel_hi:[0,1,1]
	v_pk_fma_f32 v[52:53], s[32:33], v[8:9], v[52:53] op_sel_hi:[0,1,1]
	v_pk_fma_f32 v[54:55], s[32:33], v[10:11], v[54:55] op_sel_hi:[0,1,1]
	v_cvt_scalef32_pk_f32_fp4 v[4:5], v97, 1.0
	v_cvt_scalef32_pk_f32_fp4 v[6:7], v97, 1.0 op_sel:[1,0,0]
	v_cvt_scalef32_pk_f32_fp4 v[8:9], v97, 1.0 op_sel:[0,1,0]
	v_cvt_scalef32_pk_f32_fp4 v[10:11], v97, 1.0 op_sel:[1,1,0]
	v_pk_fma_f32 v[56:57], s[32:33], v[4:5], v[56:57] op_sel_hi:[0,1,1]
	v_pk_fma_f32 v[58:59], s[32:33], v[6:7], v[58:59] op_sel_hi:[0,1,1]
	v_pk_fma_f32 v[50:51], s[32:33], v[8:9], v[50:51] op_sel_hi:[0,1,1]
	v_pk_fma_f32 v[48:49], s[32:33], v[10:11], v[48:49] op_sel_hi:[0,1,1]
	v_readlane_b32 s22, v13, 56
	s_add_u32 s16, s14, s22
	s_addc_u32 s17, s15, 0
	global_load_dwordx2 v[96:97], v213, s[16:17]
	v_readlane_b32 s34, v15, 41
	v_cvt_scalef32_pk_f32_fp4 v[4:5], v98, 1.0
	v_cvt_scalef32_pk_f32_fp4 v[6:7], v98, 1.0 op_sel:[1,0,0]
	v_cvt_scalef32_pk_f32_fp4 v[8:9], v98, 1.0 op_sel:[0,1,0]
	v_cvt_scalef32_pk_f32_fp4 v[10:11], v98, 1.0 op_sel:[1,1,0]
	v_pk_fma_f32 v[62:63], s[34:35], v[4:5], v[62:63] op_sel_hi:[0,1,1]
	v_pk_fma_f32 v[60:61], s[34:35], v[6:7], v[60:61] op_sel_hi:[0,1,1]
	v_pk_fma_f32 v[52:53], s[34:35], v[8:9], v[52:53] op_sel_hi:[0,1,1]
	v_pk_fma_f32 v[54:55], s[34:35], v[10:11], v[54:55] op_sel_hi:[0,1,1]
	v_cvt_scalef32_pk_f32_fp4 v[4:5], v99, 1.0
	v_cvt_scalef32_pk_f32_fp4 v[6:7], v99, 1.0 op_sel:[1,0,0]
	v_cvt_scalef32_pk_f32_fp4 v[8:9], v99, 1.0 op_sel:[0,1,0]
	v_cvt_scalef32_pk_f32_fp4 v[10:11], v99, 1.0 op_sel:[1,1,0]
	v_pk_fma_f32 v[56:57], s[34:35], v[4:5], v[56:57] op_sel_hi:[0,1,1]
	v_pk_fma_f32 v[58:59], s[34:35], v[6:7], v[58:59] op_sel_hi:[0,1,1]
	v_pk_fma_f32 v[50:51], s[34:35], v[8:9], v[50:51] op_sel_hi:[0,1,1]
	v_pk_fma_f32 v[48:49], s[34:35], v[10:11], v[48:49] op_sel_hi:[0,1,1]
	v_readlane_b32 s28, v13, 57
	s_add_u32 s20, s14, s28
	s_addc_u32 s21, s15, 0
	global_load_dwordx2 v[98:99], v213, s[20:21]
	v_readlane_b32 s32, v15, 42
	v_cvt_scalef32_pk_f32_fp4 v[4:5], v100, 1.0
	v_cvt_scalef32_pk_f32_fp4 v[6:7], v100, 1.0 op_sel:[1,0,0]
	v_cvt_scalef32_pk_f32_fp4 v[8:9], v100, 1.0 op_sel:[0,1,0]
	v_cvt_scalef32_pk_f32_fp4 v[10:11], v100, 1.0 op_sel:[1,1,0]
	v_pk_fma_f32 v[62:63], s[32:33], v[4:5], v[62:63] op_sel_hi:[0,1,1]
	v_pk_fma_f32 v[60:61], s[32:33], v[6:7], v[60:61] op_sel_hi:[0,1,1]
	v_pk_fma_f32 v[52:53], s[32:33], v[8:9], v[52:53] op_sel_hi:[0,1,1]
	v_pk_fma_f32 v[54:55], s[32:33], v[10:11], v[54:55] op_sel_hi:[0,1,1]
	v_cvt_scalef32_pk_f32_fp4 v[4:5], v101, 1.0
	v_cvt_scalef32_pk_f32_fp4 v[6:7], v101, 1.0 op_sel:[1,0,0]
	v_cvt_scalef32_pk_f32_fp4 v[8:9], v101, 1.0 op_sel:[0,1,0]
	v_cvt_scalef32_pk_f32_fp4 v[10:11], v101, 1.0 op_sel:[1,1,0]
	v_pk_fma_f32 v[56:57], s[32:33], v[4:5], v[56:57] op_sel_hi:[0,1,1]
	v_pk_fma_f32 v[58:59], s[32:33], v[6:7], v[58:59] op_sel_hi:[0,1,1]
	v_pk_fma_f32 v[50:51], s[32:33], v[8:9], v[50:51] op_sel_hi:[0,1,1]
	v_pk_fma_f32 v[48:49], s[32:33], v[10:11], v[48:49] op_sel_hi:[0,1,1]
	v_readlane_b32 s29, v13, 58
	s_add_u32 s24, s14, s29
	s_addc_u32 s25, s15, 0
	global_load_dwordx2 v[100:101], v213, s[24:25]
	v_readlane_b32 s34, v15, 43
	v_cvt_scalef32_pk_f32_fp4 v[4:5], v102, 1.0
	v_cvt_scalef32_pk_f32_fp4 v[6:7], v102, 1.0 op_sel:[1,0,0]
	v_cvt_scalef32_pk_f32_fp4 v[8:9], v102, 1.0 op_sel:[0,1,0]
	v_cvt_scalef32_pk_f32_fp4 v[10:11], v102, 1.0 op_sel:[1,1,0]
	v_pk_fma_f32 v[62:63], s[34:35], v[4:5], v[62:63] op_sel_hi:[0,1,1]
	v_pk_fma_f32 v[60:61], s[34:35], v[6:7], v[60:61] op_sel_hi:[0,1,1]
	v_pk_fma_f32 v[52:53], s[34:35], v[8:9], v[52:53] op_sel_hi:[0,1,1]
	v_pk_fma_f32 v[54:55], s[34:35], v[10:11], v[54:55] op_sel_hi:[0,1,1]
	v_cvt_scalef32_pk_f32_fp4 v[4:5], v103, 1.0
	v_cvt_scalef32_pk_f32_fp4 v[6:7], v103, 1.0 op_sel:[1,0,0]
	v_cvt_scalef32_pk_f32_fp4 v[8:9], v103, 1.0 op_sel:[0,1,0]
	v_cvt_scalef32_pk_f32_fp4 v[10:11], v103, 1.0 op_sel:[1,1,0]
	v_pk_fma_f32 v[56:57], s[34:35], v[4:5], v[56:57] op_sel_hi:[0,1,1]
	v_pk_fma_f32 v[58:59], s[34:35], v[6:7], v[58:59] op_sel_hi:[0,1,1]
	v_pk_fma_f32 v[50:51], s[34:35], v[8:9], v[50:51] op_sel_hi:[0,1,1]
	v_pk_fma_f32 v[48:49], s[34:35], v[10:11], v[48:49] op_sel_hi:[0,1,1]
	v_readlane_b32 s30, v13, 59
	s_add_u32 s26, s14, s30
	s_addc_u32 s27, s15, 0
	global_load_dwordx2 v[102:103], v213, s[26:27]
	s_waitcnt vmcnt(12)
; __device__ void peer_v(const P& p, int layer, int tok, bool dry) {
;     ...
;   for (int h2 = 0; h2 < 2; ++h2) {
;     for (int jb = 0; jb < 64; jb += 16) {
;       u32x2 vv[16];
; #pragma unroll
;       for (int q = 0; q < 16; ++q) {
;         const int e = __builtin_amdgcn_readlane(eidx[h2], jb + q);
;         vv[q] = ((const u32x2*)(V4 + (size_t)e * 512))[lane];
;       }
; #pragma unroll
;       for (int q = 0; q < 16; ++q) {
;         const float wq = rdlane_f(wreg[h2], jb + q);
;         const f32x2 w2 = {wq, wq};
; #pragma unroll
;         for (int k = 0; k < 2; ++k) {
;           oa2[4 * k + 0] += w2 * __builtin_amdgcn_cvt_scalef32_pk_f32_fp4(vv[q][k], 1.0f, 0);
;           oa2[4 * k + 1] += w2 * __builtin_amdgcn_cvt_scalef32_pk_f32_fp4(vv[q][k], 1.0f, 1);
;           oa2[4 * k + 2] += w2 * __builtin_amdgcn_cvt_scalef32_pk_f32_fp4(vv[q][k], 1.0f, 2);
;           oa2[4 * k + 3] += w2 * __builtin_amdgcn_cvt_scalef32_pk_f32_fp4(vv[q][k], 1.0f, 3);
;         }
;       }
;     }
;   }
;   float* hrow = (float*)(ws + OFF_H) + (size_t)tok * 1024;
;   float hv[16];
; #pragma unroll
;   for (int k = 0; k < 4; ++k) {
;     const f32x4 h4 = ((const f32x4*)hrow)[lane * 4 + k];
;     hv[4 * k] = h4.x; hv[4 * k + 1] = h4.y; hv[4 * k + 2] = h4.z; hv[4 * k + 3] = h4.w;
;   }
	v_readlane_b32 s32, v15, 44
	v_cvt_scalef32_pk_f32_fp4 v[4:5], v104, 1.0
	v_cvt_scalef32_pk_f32_fp4 v[6:7], v104, 1.0 op_sel:[1,0,0]
	v_cvt_scalef32_pk_f32_fp4 v[8:9], v104, 1.0 op_sel:[0,1,0]
	v_cvt_scalef32_pk_f32_fp4 v[10:11], v104, 1.0 op_sel:[1,1,0]
	v_pk_fma_f32 v[62:63], s[32:33], v[4:5], v[62:63] op_sel_hi:[0,1,1]
	v_pk_fma_f32 v[60:61], s[32:33], v[6:7], v[60:61] op_sel_hi:[0,1,1]
	v_pk_fma_f32 v[52:53], s[32:33], v[8:9], v[52:53] op_sel_hi:[0,1,1]
	v_pk_fma_f32 v[54:55], s[32:33], v[10:11], v[54:55] op_sel_hi:[0,1,1]
	v_cvt_scalef32_pk_f32_fp4 v[4:5], v105, 1.0
	v_cvt_scalef32_pk_f32_fp4 v[6:7], v105, 1.0 op_sel:[1,0,0]
	v_cvt_scalef32_pk_f32_fp4 v[8:9], v105, 1.0 op_sel:[0,1,0]
	v_cvt_scalef32_pk_f32_fp4 v[10:11], v105, 1.0 op_sel:[1,1,0]
	v_pk_fma_f32 v[56:57], s[32:33], v[4:5], v[56:57] op_sel_hi:[0,1,1]
	v_pk_fma_f32 v[58:59], s[32:33], v[6:7], v[58:59] op_sel_hi:[0,1,1]
	v_pk_fma_f32 v[50:51], s[32:33], v[8:9], v[50:51] op_sel_hi:[0,1,1]
	v_pk_fma_f32 v[48:49], s[32:33], v[10:11], v[48:49] op_sel_hi:[0,1,1]
	v_readlane_b32 s22, v13, 60
	s_add_u32 s16, s14, s22
	s_addc_u32 s17, s15, 0
	global_load_dwordx2 v[104:105], v213, s[16:17]
	v_readlane_b32 s34, v15, 45
	v_cvt_scalef32_pk_f32_fp4 v[4:5], v106, 1.0
	v_cvt_scalef32_pk_f32_fp4 v[6:7], v106, 1.0 op_sel:[1,0,0]
	v_cvt_scalef32_pk_f32_fp4 v[8:9], v106, 1.0 op_sel:[0,1,0]
	v_cvt_scalef32_pk_f32_fp4 v[10:11], v106, 1.0 op_sel:[1,1,0]
	v_pk_fma_f32 v[62:63], s[34:35], v[4:5], v[62:63] op_sel_hi:[0,1,1]
	v_pk_fma_f32 v[60:61], s[34:35], v[6:7], v[60:61] op_sel_hi:[0,1,1]
	v_pk_fma_f32 v[52:53], s[34:35], v[8:9], v[52:53] op_sel_hi:[0,1,1]
	v_pk_fma_f32 v[54:55], s[34:35], v[10:11], v[54:55] op_sel_hi:[0,1,1]
	v_cvt_scalef32_pk_f32_fp4 v[4:5], v107, 1.0
	v_cvt_scalef32_pk_f32_fp4 v[6:7], v107, 1.0 op_sel:[1,0,0]
	v_cvt_scalef32_pk_f32_fp4 v[8:9], v107, 1.0 op_sel:[0,1,0]
	v_cvt_scalef32_pk_f32_fp4 v[10:11], v107, 1.0 op_sel:[1,1,0]
	v_pk_fma_f32 v[56:57], s[34:35], v[4:5], v[56:57] op_sel_hi:[0,1,1]
	v_pk_fma_f32 v[58:59], s[34:35], v[6:7], v[58:59] op_sel_hi:[0,1,1]
	v_pk_fma_f32 v[50:51], s[34:35], v[8:9], v[50:51] op_sel_hi:[0,1,1]
	v_pk_fma_f32 v[48:49], s[34:35], v[10:11], v[48:49] op_sel_hi:[0,1,1]
	v_readlane_b32 s28, v13, 61
	s_add_u32 s20, s14, s28
	s_addc_u32 s21, s15, 0
	global_load_dwordx2 v[106:107], v213, s[20:21]
	v_readlane_b32 s32, v15, 46
	v_cvt_scalef32_pk_f32_fp4 v[4:5], v108, 1.0
	v_cvt_scalef32_pk_f32_fp4 v[6:7], v108, 1.0 op_sel:[1,0,0]
	v_cvt_scalef32_pk_f32_fp4 v[8:9], v108, 1.0 op_sel:[0,1,0]
	v_cvt_scalef32_pk_f32_fp4 v[10:11], v108, 1.0 op_sel:[1,1,0]
	v_pk_fma_f32 v[62:63], s[32:33], v[4:5], v[62:63] op_sel_hi:[0,1,1]
	v_pk_fma_f32 v[60:61], s[32:33], v[6:7], v[60:61] op_sel_hi:[0,1,1]
	v_pk_fma_f32 v[52:53], s[32:33], v[8:9], v[52:53] op_sel_hi:[0,1,1]
	v_pk_fma_f32 v[54:55], s[32:33], v[10:11], v[54:55] op_sel_hi:[0,1,1]
	v_cvt_scalef32_pk_f32_fp4 v[4:5], v109, 1.0
	v_cvt_scalef32_pk_f32_fp4 v[6:7], v109, 1.0 op_sel:[1,0,0]
	v_cvt_scalef32_pk_f32_fp4 v[8:9], v109, 1.0 op_sel:[0,1,0]
	v_cvt_scalef32_pk_f32_fp4 v[10:11], v109, 1.0 op_sel:[1,1,0]
	v_pk_fma_f32 v[56:57], s[32:33], v[4:5], v[56:57] op_sel_hi:[0,1,1]
	v_pk_fma_f32 v[58:59], s[32:33], v[6:7], v[58:59] op_sel_hi:[0,1,1]
	v_pk_fma_f32 v[50:51], s[32:33], v[8:9], v[50:51] op_sel_hi:[0,1,1]
	v_pk_fma_f32 v[48:49], s[32:33], v[10:11], v[48:49] op_sel_hi:[0,1,1]
	v_readlane_b32 s29, v13, 62
	s_add_u32 s24, s14, s29
	s_addc_u32 s25, s15, 0
	global_load_dwordx2 v[108:109], v213, s[24:25]
	v_readlane_b32 s34, v15, 47
	v_cvt_scalef32_pk_f32_fp4 v[4:5], v110, 1.0
	v_cvt_scalef32_pk_f32_fp4 v[6:7], v110, 1.0 op_sel:[1,0,0]
	v_cvt_scalef32_pk_f32_fp4 v[8:9], v110, 1.0 op_sel:[0,1,0]
	v_cvt_scalef32_pk_f32_fp4 v[10:11], v110, 1.0 op_sel:[1,1,0]
	v_pk_fma_f32 v[62:63], s[34:35], v[4:5], v[62:63] op_sel_hi:[0,1,1]
	v_pk_fma_f32 v[60:61], s[34:35], v[6:7], v[60:61] op_sel_hi:[0,1,1]
	v_pk_fma_f32 v[52:53], s[34:35], v[8:9], v[52:53] op_sel_hi:[0,1,1]
	v_pk_fma_f32 v[54:55], s[34:35], v[10:11], v[54:55] op_sel_hi:[0,1,1]
	v_cvt_scalef32_pk_f32_fp4 v[4:5], v111, 1.0
	v_cvt_scalef32_pk_f32_fp4 v[6:7], v111, 1.0 op_sel:[1,0,0]
	v_cvt_scalef32_pk_f32_fp4 v[8:9], v111, 1.0 op_sel:[0,1,0]
	v_cvt_scalef32_pk_f32_fp4 v[10:11], v111, 1.0 op_sel:[1,1,0]
	v_pk_fma_f32 v[56:57], s[34:35], v[4:5], v[56:57] op_sel_hi:[0,1,1]
	v_pk_fma_f32 v[58:59], s[34:35], v[6:7], v[58:59] op_sel_hi:[0,1,1]
	v_pk_fma_f32 v[50:51], s[34:35], v[8:9], v[50:51] op_sel_hi:[0,1,1]
	v_pk_fma_f32 v[48:49], s[34:35], v[10:11], v[48:49] op_sel_hi:[0,1,1]
	v_readlane_b32 s30, v13, 63
	s_add_u32 s26, s14, s30
	s_addc_u32 s27, s15, 0
	global_load_dwordx2 v[110:111], v213, s[26:27]
	v_lshlrev_b64 v[20:21], 12, v[2:3]
	v_lshl_add_u64 v[20:21], s[8:9], 0, v[20:21]
	v_lshl_add_u64 v[20:21], v[20:21], 0, v[66:67]
	s_mov_b64 s[10:11], 0x13a84000
	v_lshl_add_u64 v[68:69], v[20:21], 0, s[10:11]
	s_mov_b32 s10, 0x13a84000
	v_add_co_u32_e32 v20, vcc, s10, v20
	s_nop 1
	v_addc_co_u32_e32 v21, vcc, 0, v21, vcc
	global_load_dwordx4 v[24:27], v[20:21], off
	s_nop 0
	global_load_dwordx4 v[20:23], v[68:69], off offset:48
	global_load_dwordx4 v[28:31], v[68:69], off offset:32
	global_load_dwordx4 v[40:43], v[68:69], off offset:16
	global_load_dwordx4 v[32:35], v66, s[6:7] offset:48
	global_load_dwordx4 v[36:39], v66, s[6:7] offset:32
	global_load_dwordx4 v[44:47], v66, s[6:7] offset:16
	global_load_dwordx4 v[72:75], v66, s[6:7]
	s_waitcnt vmcnt(20)
; __device__ void peer_v(const P& p, int layer, int tok, bool dry) {
;     ...
; #pragma unroll
;       for (int q = 0; q < 16; ++q) {
;         const float wq = rdlane_f(wreg[h2], jb + q);
;         const f32x2 w2 = {wq, wq};
; #pragma unroll
;         for (int k = 0; k < 2; ++k) {
;           oa2[4 * k + 0] += w2 * __builtin_amdgcn_cvt_scalef32_pk_f32_fp4(vv[q][k], 1.0f, 0);
;           oa2[4 * k + 1] += w2 * __builtin_amdgcn_cvt_scalef32_pk_f32_fp4(vv[q][k], 1.0f, 1);
;           oa2[4 * k + 2] += w2 * __builtin_amdgcn_cvt_scalef32_pk_f32_fp4(vv[q][k], 1.0f, 2);
;           oa2[4 * k + 3] += w2 * __builtin_amdgcn_cvt_scalef32_pk_f32_fp4(vv[q][k], 1.0f, 3);
;         }
;       }
	v_readlane_b32 s32, v15, 48
	v_cvt_scalef32_pk_f32_fp4 v[4:5], v80, 1.0
	v_cvt_scalef32_pk_f32_fp4 v[6:7], v80, 1.0 op_sel:[1,0,0]
	v_cvt_scalef32_pk_f32_fp4 v[8:9], v80, 1.0 op_sel:[0,1,0]
	v_cvt_scalef32_pk_f32_fp4 v[10:11], v80, 1.0 op_sel:[1,1,0]
	v_pk_fma_f32 v[62:63], s[32:33], v[4:5], v[62:63] op_sel_hi:[0,1,1]
	v_pk_fma_f32 v[60:61], s[32:33], v[6:7], v[60:61] op_sel_hi:[0,1,1]
	v_pk_fma_f32 v[52:53], s[32:33], v[8:9], v[52:53] op_sel_hi:[0,1,1]
	v_pk_fma_f32 v[54:55], s[32:33], v[10:11], v[54:55] op_sel_hi:[0,1,1]
	v_cvt_scalef32_pk_f32_fp4 v[4:5], v81, 1.0
	v_cvt_scalef32_pk_f32_fp4 v[6:7], v81, 1.0 op_sel:[1,0,0]
	v_cvt_scalef32_pk_f32_fp4 v[8:9], v81, 1.0 op_sel:[0,1,0]
	v_cvt_scalef32_pk_f32_fp4 v[10:11], v81, 1.0 op_sel:[1,1,0]
	v_pk_fma_f32 v[56:57], s[32:33], v[4:5], v[56:57] op_sel_hi:[0,1,1]
	v_pk_fma_f32 v[58:59], s[32:33], v[6:7], v[58:59] op_sel_hi:[0,1,1]
	v_pk_fma_f32 v[50:51], s[32:33], v[8:9], v[50:51] op_sel_hi:[0,1,1]
	v_pk_fma_f32 v[48:49], s[32:33], v[10:11], v[48:49] op_sel_hi:[0,1,1]
	v_readlane_b32 s34, v15, 49
	v_cvt_scalef32_pk_f32_fp4 v[4:5], v82, 1.0
	v_cvt_scalef32_pk_f32_fp4 v[6:7], v82, 1.0 op_sel:[1,0,0]
	v_cvt_scalef32_pk_f32_fp4 v[8:9], v82, 1.0 op_sel:[0,1,0]
	v_cvt_scalef32_pk_f32_fp4 v[10:11], v82, 1.0 op_sel:[1,1,0]
	v_pk_fma_f32 v[62:63], s[34:35], v[4:5], v[62:63] op_sel_hi:[0,1,1]
	v_pk_fma_f32 v[60:61], s[34:35], v[6:7], v[60:61] op_sel_hi:[0,1,1]
	v_pk_fma_f32 v[52:53], s[34:35], v[8:9], v[52:53] op_sel_hi:[0,1,1]
	v_pk_fma_f32 v[54:55], s[34:35], v[10:11], v[54:55] op_sel_hi:[0,1,1]
	v_cvt_scalef32_pk_f32_fp4 v[4:5], v83, 1.0
	v_cvt_scalef32_pk_f32_fp4 v[6:7], v83, 1.0 op_sel:[1,0,0]
	v_cvt_scalef32_pk_f32_fp4 v[8:9], v83, 1.0 op_sel:[0,1,0]
	v_cvt_scalef32_pk_f32_fp4 v[10:11], v83, 1.0 op_sel:[1,1,0]
	v_pk_fma_f32 v[56:57], s[34:35], v[4:5], v[56:57] op_sel_hi:[0,1,1]
	v_pk_fma_f32 v[58:59], s[34:35], v[6:7], v[58:59] op_sel_hi:[0,1,1]
	v_pk_fma_f32 v[50:51], s[34:35], v[8:9], v[50:51] op_sel_hi:[0,1,1]
	v_pk_fma_f32 v[48:49], s[34:35], v[10:11], v[48:49] op_sel_hi:[0,1,1]
	v_readlane_b32 s32, v15, 50
	v_cvt_scalef32_pk_f32_fp4 v[4:5], v84, 1.0
	v_cvt_scalef32_pk_f32_fp4 v[6:7], v84, 1.0 op_sel:[1,0,0]
	v_cvt_scalef32_pk_f32_fp4 v[8:9], v84, 1.0 op_sel:[0,1,0]
	v_cvt_scalef32_pk_f32_fp4 v[10:11], v84, 1.0 op_sel:[1,1,0]
	v_pk_fma_f32 v[62:63], s[32:33], v[4:5], v[62:63] op_sel_hi:[0,1,1]
	v_pk_fma_f32 v[60:61], s[32:33], v[6:7], v[60:61] op_sel_hi:[0,1,1]
	v_pk_fma_f32 v[52:53], s[32:33], v[8:9], v[52:53] op_sel_hi:[0,1,1]
	v_pk_fma_f32 v[54:55], s[32:33], v[10:11], v[54:55] op_sel_hi:[0,1,1]
	v_cvt_scalef32_pk_f32_fp4 v[4:5], v85, 1.0
	v_cvt_scalef32_pk_f32_fp4 v[6:7], v85, 1.0 op_sel:[1,0,0]
	v_cvt_scalef32_pk_f32_fp4 v[8:9], v85, 1.0 op_sel:[0,1,0]
	v_cvt_scalef32_pk_f32_fp4 v[10:11], v85, 1.0 op_sel:[1,1,0]
	v_pk_fma_f32 v[56:57], s[32:33], v[4:5], v[56:57] op_sel_hi:[0,1,1]
	v_pk_fma_f32 v[58:59], s[32:33], v[6:7], v[58:59] op_sel_hi:[0,1,1]
	v_pk_fma_f32 v[50:51], s[32:33], v[8:9], v[50:51] op_sel_hi:[0,1,1]
	v_pk_fma_f32 v[48:49], s[32:33], v[10:11], v[48:49] op_sel_hi:[0,1,1]
	v_readlane_b32 s34, v15, 51
	v_cvt_scalef32_pk_f32_fp4 v[4:5], v86, 1.0
	v_cvt_scalef32_pk_f32_fp4 v[6:7], v86, 1.0 op_sel:[1,0,0]
	v_cvt_scalef32_pk_f32_fp4 v[8:9], v86, 1.0 op_sel:[0,1,0]
	v_cvt_scalef32_pk_f32_fp4 v[10:11], v86, 1.0 op_sel:[1,1,0]
	v_pk_fma_f32 v[62:63], s[34:35], v[4:5], v[62:63] op_sel_hi:[0,1,1]
	v_pk_fma_f32 v[60:61], s[34:35], v[6:7], v[60:61] op_sel_hi:[0,1,1]
	v_pk_fma_f32 v[52:53], s[34:35], v[8:9], v[52:53] op_sel_hi:[0,1,1]
	v_pk_fma_f32 v[54:55], s[34:35], v[10:11], v[54:55] op_sel_hi:[0,1,1]
	v_cvt_scalef32_pk_f32_fp4 v[4:5], v87, 1.0
	v_cvt_scalef32_pk_f32_fp4 v[6:7], v87, 1.0 op_sel:[1,0,0]
	v_cvt_scalef32_pk_f32_fp4 v[8:9], v87, 1.0 op_sel:[0,1,0]
	v_cvt_scalef32_pk_f32_fp4 v[10:11], v87, 1.0 op_sel:[1,1,0]
	v_pk_fma_f32 v[56:57], s[34:35], v[4:5], v[56:57] op_sel_hi:[0,1,1]
	v_pk_fma_f32 v[58:59], s[34:35], v[6:7], v[58:59] op_sel_hi:[0,1,1]
	v_pk_fma_f32 v[50:51], s[34:35], v[8:9], v[50:51] op_sel_hi:[0,1,1]
	v_pk_fma_f32 v[48:49], s[34:35], v[10:11], v[48:49] op_sel_hi:[0,1,1]
	s_waitcnt vmcnt(16)
	v_readlane_b32 s32, v15, 52
	v_cvt_scalef32_pk_f32_fp4 v[4:5], v88, 1.0
	v_cvt_scalef32_pk_f32_fp4 v[6:7], v88, 1.0 op_sel:[1,0,0]
	v_cvt_scalef32_pk_f32_fp4 v[8:9], v88, 1.0 op_sel:[0,1,0]
	v_cvt_scalef32_pk_f32_fp4 v[10:11], v88, 1.0 op_sel:[1,1,0]
	v_pk_fma_f32 v[62:63], s[32:33], v[4:5], v[62:63] op_sel_hi:[0,1,1]
	v_pk_fma_f32 v[60:61], s[32:33], v[6:7], v[60:61] op_sel_hi:[0,1,1]
	v_pk_fma_f32 v[52:53], s[32:33], v[8:9], v[52:53] op_sel_hi:[0,1,1]
	v_pk_fma_f32 v[54:55], s[32:33], v[10:11], v[54:55] op_sel_hi:[0,1,1]
	v_cvt_scalef32_pk_f32_fp4 v[4:5], v89, 1.0
	v_cvt_scalef32_pk_f32_fp4 v[6:7], v89, 1.0 op_sel:[1,0,0]
	v_cvt_scalef32_pk_f32_fp4 v[8:9], v89, 1.0 op_sel:[0,1,0]
	v_cvt_scalef32_pk_f32_fp4 v[10:11], v89, 1.0 op_sel:[1,1,0]
	v_pk_fma_f32 v[56:57], s[32:33], v[4:5], v[56:57] op_sel_hi:[0,1,1]
	v_pk_fma_f32 v[58:59], s[32:33], v[6:7], v[58:59] op_sel_hi:[0,1,1]
	v_pk_fma_f32 v[50:51], s[32:33], v[8:9], v[50:51] op_sel_hi:[0,1,1]
	v_pk_fma_f32 v[48:49], s[32:33], v[10:11], v[48:49] op_sel_hi:[0,1,1]
	v_readlane_b32 s34, v15, 53
	v_cvt_scalef32_pk_f32_fp4 v[4:5], v90, 1.0
	v_cvt_scalef32_pk_f32_fp4 v[6:7], v90, 1.0 op_sel:[1,0,0]
	v_cvt_scalef32_pk_f32_fp4 v[8:9], v90, 1.0 op_sel:[0,1,0]
	v_cvt_scalef32_pk_f32_fp4 v[10:11], v90, 1.0 op_sel:[1,1,0]
	v_pk_fma_f32 v[62:63], s[34:35], v[4:5], v[62:63] op_sel_hi:[0,1,1]
	v_pk_fma_f32 v[60:61], s[34:35], v[6:7], v[60:61] op_sel_hi:[0,1,1]
	v_pk_fma_f32 v[52:53], s[34:35], v[8:9], v[52:53] op_sel_hi:[0,1,1]
; __device__ void peer_v(const P& p, int layer, int tok, bool dry) {
;     ...
; #pragma unroll
;       for (int q = 0; q < 16; ++q) {
;         const float wq = rdlane_f(wreg[h2], jb + q);
;         const f32x2 w2 = {wq, wq};
; #pragma unroll
;         for (int k = 0; k < 2; ++k) {
;           oa2[4 * k + 0] += w2 * __builtin_amdgcn_cvt_scalef32_pk_f32_fp4(vv[q][k], 1.0f, 0);
;           oa2[4 * k + 1] += w2 * __builtin_amdgcn_cvt_scalef32_pk_f32_fp4(vv[q][k], 1.0f, 1);
;           oa2[4 * k + 2] += w2 * __builtin_amdgcn_cvt_scalef32_pk_f32_fp4(vv[q][k], 1.0f, 2);
;           oa2[4 * k + 3] += w2 * __builtin_amdgcn_cvt_scalef32_pk_f32_fp4(vv[q][k], 1.0f, 3);
;         }
;       }
	v_pk_fma_f32 v[54:55], s[34:35], v[10:11], v[54:55] op_sel_hi:[0,1,1]
	v_cvt_scalef32_pk_f32_fp4 v[4:5], v91, 1.0
	v_cvt_scalef32_pk_f32_fp4 v[6:7], v91, 1.0 op_sel:[1,0,0]
	v_cvt_scalef32_pk_f32_fp4 v[8:9], v91, 1.0 op_sel:[0,1,0]
	v_cvt_scalef32_pk_f32_fp4 v[10:11], v91, 1.0 op_sel:[1,1,0]
	v_pk_fma_f32 v[56:57], s[34:35], v[4:5], v[56:57] op_sel_hi:[0,1,1]
	v_pk_fma_f32 v[58:59], s[34:35], v[6:7], v[58:59] op_sel_hi:[0,1,1]
	v_pk_fma_f32 v[50:51], s[34:35], v[8:9], v[50:51] op_sel_hi:[0,1,1]
	v_pk_fma_f32 v[48:49], s[34:35], v[10:11], v[48:49] op_sel_hi:[0,1,1]
	v_readlane_b32 s32, v15, 54
	v_cvt_scalef32_pk_f32_fp4 v[4:5], v92, 1.0
	v_cvt_scalef32_pk_f32_fp4 v[6:7], v92, 1.0 op_sel:[1,0,0]
	v_cvt_scalef32_pk_f32_fp4 v[8:9], v92, 1.0 op_sel:[0,1,0]
	v_cvt_scalef32_pk_f32_fp4 v[10:11], v92, 1.0 op_sel:[1,1,0]
	v_pk_fma_f32 v[62:63], s[32:33], v[4:5], v[62:63] op_sel_hi:[0,1,1]
	v_pk_fma_f32 v[60:61], s[32:33], v[6:7], v[60:61] op_sel_hi:[0,1,1]
	v_pk_fma_f32 v[52:53], s[32:33], v[8:9], v[52:53] op_sel_hi:[0,1,1]
	v_pk_fma_f32 v[54:55], s[32:33], v[10:11], v[54:55] op_sel_hi:[0,1,1]
	v_cvt_scalef32_pk_f32_fp4 v[4:5], v93, 1.0
	v_cvt_scalef32_pk_f32_fp4 v[6:7], v93, 1.0 op_sel:[1,0,0]
	v_cvt_scalef32_pk_f32_fp4 v[8:9], v93, 1.0 op_sel:[0,1,0]
	v_cvt_scalef32_pk_f32_fp4 v[10:11], v93, 1.0 op_sel:[1,1,0]
	v_pk_fma_f32 v[56:57], s[32:33], v[4:5], v[56:57] op_sel_hi:[0,1,1]
	v_pk_fma_f32 v[58:59], s[32:33], v[6:7], v[58:59] op_sel_hi:[0,1,1]
	v_pk_fma_f32 v[50:51], s[32:33], v[8:9], v[50:51] op_sel_hi:[0,1,1]
	v_pk_fma_f32 v[48:49], s[32:33], v[10:11], v[48:49] op_sel_hi:[0,1,1]
	v_readlane_b32 s34, v15, 55
	v_cvt_scalef32_pk_f32_fp4 v[4:5], v94, 1.0
	v_cvt_scalef32_pk_f32_fp4 v[6:7], v94, 1.0 op_sel:[1,0,0]
	v_cvt_scalef32_pk_f32_fp4 v[8:9], v94, 1.0 op_sel:[0,1,0]
	v_cvt_scalef32_pk_f32_fp4 v[10:11], v94, 1.0 op_sel:[1,1,0]
	v_pk_fma_f32 v[62:63], s[34:35], v[4:5], v[62:63] op_sel_hi:[0,1,1]
	v_pk_fma_f32 v[60:61], s[34:35], v[6:7], v[60:61] op_sel_hi:[0,1,1]
	v_pk_fma_f32 v[52:53], s[34:35], v[8:9], v[52:53] op_sel_hi:[0,1,1]
	v_pk_fma_f32 v[54:55], s[34:35], v[10:11], v[54:55] op_sel_hi:[0,1,1]
	v_cvt_scalef32_pk_f32_fp4 v[4:5], v95, 1.0
	v_cvt_scalef32_pk_f32_fp4 v[6:7], v95, 1.0 op_sel:[1,0,0]
	v_cvt_scalef32_pk_f32_fp4 v[8:9], v95, 1.0 op_sel:[0,1,0]
	v_cvt_scalef32_pk_f32_fp4 v[10:11], v95, 1.0 op_sel:[1,1,0]
	v_pk_fma_f32 v[56:57], s[34:35], v[4:5], v[56:57] op_sel_hi:[0,1,1]
	v_pk_fma_f32 v[58:59], s[34:35], v[6:7], v[58:59] op_sel_hi:[0,1,1]
	v_pk_fma_f32 v[50:51], s[34:35], v[8:9], v[50:51] op_sel_hi:[0,1,1]
	v_pk_fma_f32 v[48:49], s[34:35], v[10:11], v[48:49] op_sel_hi:[0,1,1]
	s_waitcnt vmcnt(12)
	v_readlane_b32 s32, v15, 56
	v_cvt_scalef32_pk_f32_fp4 v[4:5], v96, 1.0
	v_cvt_scalef32_pk_f32_fp4 v[6:7], v96, 1.0 op_sel:[1,0,0]
	v_cvt_scalef32_pk_f32_fp4 v[8:9], v96, 1.0 op_sel:[0,1,0]
	v_cvt_scalef32_pk_f32_fp4 v[10:11], v96, 1.0 op_sel:[1,1,0]
	v_pk_fma_f32 v[62:63], s[32:33], v[4:5], v[62:63] op_sel_hi:[0,1,1]
	v_pk_fma_f32 v[60:61], s[32:33], v[6:7], v[60:61] op_sel_hi:[0,1,1]
	v_pk_fma_f32 v[52:53], s[32:33], v[8:9], v[52:53] op_sel_hi:[0,1,1]
	v_pk_fma_f32 v[54:55], s[32:33], v[10:11], v[54:55] op_sel_hi:[0,1,1]
	v_cvt_scalef32_pk_f32_fp4 v[4:5], v97, 1.0
	v_cvt_scalef32_pk_f32_fp4 v[6:7], v97, 1.0 op_sel:[1,0,0]
	v_cvt_scalef32_pk_f32_fp4 v[8:9], v97, 1.0 op_sel:[0,1,0]
	v_cvt_scalef32_pk_f32_fp4 v[10:11], v97, 1.0 op_sel:[1,1,0]
	v_pk_fma_f32 v[56:57], s[32:33], v[4:5], v[56:57] op_sel_hi:[0,1,1]
	v_pk_fma_f32 v[58:59], s[32:33], v[6:7], v[58:59] op_sel_hi:[0,1,1]
	v_pk_fma_f32 v[50:51], s[32:33], v[8:9], v[50:51] op_sel_hi:[0,1,1]
	v_pk_fma_f32 v[48:49], s[32:33], v[10:11], v[48:49] op_sel_hi:[0,1,1]
	v_readlane_b32 s34, v15, 57
	v_cvt_scalef32_pk_f32_fp4 v[4:5], v98, 1.0
	v_cvt_scalef32_pk_f32_fp4 v[6:7], v98, 1.0 op_sel:[1,0,0]
	v_cvt_scalef32_pk_f32_fp4 v[8:9], v98, 1.0 op_sel:[0,1,0]
	v_cvt_scalef32_pk_f32_fp4 v[10:11], v98, 1.0 op_sel:[1,1,0]
	v_pk_fma_f32 v[62:63], s[34:35], v[4:5], v[62:63] op_sel_hi:[0,1,1]
	v_pk_fma_f32 v[60:61], s[34:35], v[6:7], v[60:61] op_sel_hi:[0,1,1]
	v_pk_fma_f32 v[52:53], s[34:35], v[8:9], v[52:53] op_sel_hi:[0,1,1]
	v_pk_fma_f32 v[54:55], s[34:35], v[10:11], v[54:55] op_sel_hi:[0,1,1]
	v_cvt_scalef32_pk_f32_fp4 v[4:5], v99, 1.0
	v_cvt_scalef32_pk_f32_fp4 v[6:7], v99, 1.0 op_sel:[1,0,0]
	v_cvt_scalef32_pk_f32_fp4 v[8:9], v99, 1.0 op_sel:[0,1,0]
	v_cvt_scalef32_pk_f32_fp4 v[10:11], v99, 1.0 op_sel:[1,1,0]
	v_pk_fma_f32 v[56:57], s[34:35], v[4:5], v[56:57] op_sel_hi:[0,1,1]
	v_pk_fma_f32 v[58:59], s[34:35], v[6:7], v[58:59] op_sel_hi:[0,1,1]
	v_pk_fma_f32 v[50:51], s[34:35], v[8:9], v[50:51] op_sel_hi:[0,1,1]
	v_pk_fma_f32 v[48:49], s[34:35], v[10:11], v[48:49] op_sel_hi:[0,1,1]
	v_readlane_b32 s32, v15, 58
	v_cvt_scalef32_pk_f32_fp4 v[4:5], v100, 1.0
	v_cvt_scalef32_pk_f32_fp4 v[6:7], v100, 1.0 op_sel:[1,0,0]
	v_cvt_scalef32_pk_f32_fp4 v[8:9], v100, 1.0 op_sel:[0,1,0]
	v_cvt_scalef32_pk_f32_fp4 v[10:11], v100, 1.0 op_sel:[1,1,0]
	v_pk_fma_f32 v[62:63], s[32:33], v[4:5], v[62:63] op_sel_hi:[0,1,1]
	v_pk_fma_f32 v[60:61], s[32:33], v[6:7], v[60:61] op_sel_hi:[0,1,1]
	v_pk_fma_f32 v[52:53], s[32:33], v[8:9], v[52:53] op_sel_hi:[0,1,1]
	v_pk_fma_f32 v[54:55], s[32:33], v[10:11], v[54:55] op_sel_hi:[0,1,1]
	v_cvt_scalef32_pk_f32_fp4 v[4:5], v101, 1.0
	v_cvt_scalef32_pk_f32_fp4 v[6:7], v101, 1.0 op_sel:[1,0,0]
	v_cvt_scalef32_pk_f32_fp4 v[8:9], v101, 1.0 op_sel:[0,1,0]
	v_cvt_scalef32_pk_f32_fp4 v[10:11], v101, 1.0 op_sel:[1,1,0]
	v_pk_fma_f32 v[56:57], s[32:33], v[4:5], v[56:57] op_sel_hi:[0,1,1]
	v_pk_fma_f32 v[58:59], s[32:33], v[6:7], v[58:59] op_sel_hi:[0,1,1]
	v_pk_fma_f32 v[50:51], s[32:33], v[8:9], v[50:51] op_sel_hi:[0,1,1]
	v_pk_fma_f32 v[48:49], s[32:33], v[10:11], v[48:49] op_sel_hi:[0,1,1]
	v_readlane_b32 s34, v15, 59
	v_cvt_scalef32_pk_f32_fp4 v[4:5], v102, 1.0
	v_cvt_scalef32_pk_f32_fp4 v[6:7], v102, 1.0 op_sel:[1,0,0]
	v_cvt_scalef32_pk_f32_fp4 v[8:9], v102, 1.0 op_sel:[0,1,0]
	v_cvt_scalef32_pk_f32_fp4 v[10:11], v102, 1.0 op_sel:[1,1,0]
	v_pk_fma_f32 v[62:63], s[34:35], v[4:5], v[62:63] op_sel_hi:[0,1,1]
	v_pk_fma_f32 v[60:61], s[34:35], v[6:7], v[60:61] op_sel_hi:[0,1,1]
	v_pk_fma_f32 v[52:53], s[34:35], v[8:9], v[52:53] op_sel_hi:[0,1,1]
	v_pk_fma_f32 v[54:55], s[34:35], v[10:11], v[54:55] op_sel_hi:[0,1,1]
	v_cvt_scalef32_pk_f32_fp4 v[4:5], v103, 1.0
	v_cvt_scalef32_pk_f32_fp4 v[6:7], v103, 1.0 op_sel:[1,0,0]
	v_cvt_scalef32_pk_f32_fp4 v[8:9], v103, 1.0 op_sel:[0,1,0]
	v_cvt_scalef32_pk_f32_fp4 v[10:11], v103, 1.0 op_sel:[1,1,0]
	v_pk_fma_f32 v[56:57], s[34:35], v[4:5], v[56:57] op_sel_hi:[0,1,1]
	v_pk_fma_f32 v[58:59], s[34:35], v[6:7], v[58:59] op_sel_hi:[0,1,1]
	v_pk_fma_f32 v[50:51], s[34:35], v[8:9], v[50:51] op_sel_hi:[0,1,1]
	v_pk_fma_f32 v[48:49], s[34:35], v[10:11], v[48:49] op_sel_hi:[0,1,1]
	s_waitcnt vmcnt(8)
; __device__ void peer_v(const P& p, int layer, int tok, bool dry) {
;     ...
; #pragma unroll
;       for (int q = 0; q < 16; ++q) {
;         const float wq = rdlane_f(wreg[h2], jb + q);
;         const f32x2 w2 = {wq, wq};
; #pragma unroll
;         for (int k = 0; k < 2; ++k) {
;           oa2[4 * k + 0] += w2 * __builtin_amdgcn_cvt_scalef32_pk_f32_fp4(vv[q][k], 1.0f, 0);
;           oa2[4 * k + 1] += w2 * __builtin_amdgcn_cvt_scalef32_pk_f32_fp4(vv[q][k], 1.0f, 1);
;           oa2[4 * k + 2] += w2 * __builtin_amdgcn_cvt_scalef32_pk_f32_fp4(vv[q][k], 1.0f, 2);
;           oa2[4 * k + 3] += w2 * __builtin_amdgcn_cvt_scalef32_pk_f32_fp4(vv[q][k], 1.0f, 3);
;         }
;       }
	v_readlane_b32 s32, v15, 60
	v_cvt_scalef32_pk_f32_fp4 v[4:5], v104, 1.0
	v_cvt_scalef32_pk_f32_fp4 v[6:7], v104, 1.0 op_sel:[1,0,0]
	v_cvt_scalef32_pk_f32_fp4 v[8:9], v104, 1.0 op_sel:[0,1,0]
	v_cvt_scalef32_pk_f32_fp4 v[10:11], v104, 1.0 op_sel:[1,1,0]
	v_pk_fma_f32 v[62:63], s[32:33], v[4:5], v[62:63] op_sel_hi:[0,1,1]
	v_pk_fma_f32 v[60:61], s[32:33], v[6:7], v[60:61] op_sel_hi:[0,1,1]
	v_pk_fma_f32 v[52:53], s[32:33], v[8:9], v[52:53] op_sel_hi:[0,1,1]
	v_pk_fma_f32 v[54:55], s[32:33], v[10:11], v[54:55] op_sel_hi:[0,1,1]
	v_cvt_scalef32_pk_f32_fp4 v[4:5], v105, 1.0
	v_cvt_scalef32_pk_f32_fp4 v[6:7], v105, 1.0 op_sel:[1,0,0]
	v_cvt_scalef32_pk_f32_fp4 v[8:9], v105, 1.0 op_sel:[0,1,0]
	v_cvt_scalef32_pk_f32_fp4 v[10:11], v105, 1.0 op_sel:[1,1,0]
	v_pk_fma_f32 v[56:57], s[32:33], v[4:5], v[56:57] op_sel_hi:[0,1,1]
	v_pk_fma_f32 v[58:59], s[32:33], v[6:7], v[58:59] op_sel_hi:[0,1,1]
	v_pk_fma_f32 v[50:51], s[32:33], v[8:9], v[50:51] op_sel_hi:[0,1,1]
	v_pk_fma_f32 v[48:49], s[32:33], v[10:11], v[48:49] op_sel_hi:[0,1,1]
	v_readlane_b32 s34, v15, 61
	v_cvt_scalef32_pk_f32_fp4 v[4:5], v106, 1.0
	v_cvt_scalef32_pk_f32_fp4 v[6:7], v106, 1.0 op_sel:[1,0,0]
	v_cvt_scalef32_pk_f32_fp4 v[8:9], v106, 1.0 op_sel:[0,1,0]
	v_cvt_scalef32_pk_f32_fp4 v[10:11], v106, 1.0 op_sel:[1,1,0]
	v_pk_fma_f32 v[62:63], s[34:35], v[4:5], v[62:63] op_sel_hi:[0,1,1]
	v_pk_fma_f32 v[60:61], s[34:35], v[6:7], v[60:61] op_sel_hi:[0,1,1]
	v_pk_fma_f32 v[52:53], s[34:35], v[8:9], v[52:53] op_sel_hi:[0,1,1]
	v_pk_fma_f32 v[54:55], s[34:35], v[10:11], v[54:55] op_sel_hi:[0,1,1]
	v_cvt_scalef32_pk_f32_fp4 v[4:5], v107, 1.0
	v_cvt_scalef32_pk_f32_fp4 v[6:7], v107, 1.0 op_sel:[1,0,0]
	v_cvt_scalef32_pk_f32_fp4 v[8:9], v107, 1.0 op_sel:[0,1,0]
	v_cvt_scalef32_pk_f32_fp4 v[10:11], v107, 1.0 op_sel:[1,1,0]
	v_pk_fma_f32 v[56:57], s[34:35], v[4:5], v[56:57] op_sel_hi:[0,1,1]
	v_pk_fma_f32 v[58:59], s[34:35], v[6:7], v[58:59] op_sel_hi:[0,1,1]
	v_pk_fma_f32 v[50:51], s[34:35], v[8:9], v[50:51] op_sel_hi:[0,1,1]
	v_pk_fma_f32 v[48:49], s[34:35], v[10:11], v[48:49] op_sel_hi:[0,1,1]
	v_readlane_b32 s32, v15, 62
	v_cvt_scalef32_pk_f32_fp4 v[4:5], v108, 1.0
	v_cvt_scalef32_pk_f32_fp4 v[6:7], v108, 1.0 op_sel:[1,0,0]
	v_cvt_scalef32_pk_f32_fp4 v[8:9], v108, 1.0 op_sel:[0,1,0]
	v_cvt_scalef32_pk_f32_fp4 v[10:11], v108, 1.0 op_sel:[1,1,0]
	v_pk_fma_f32 v[62:63], s[32:33], v[4:5], v[62:63] op_sel_hi:[0,1,1]
	v_pk_fma_f32 v[60:61], s[32:33], v[6:7], v[60:61] op_sel_hi:[0,1,1]
	v_pk_fma_f32 v[52:53], s[32:33], v[8:9], v[52:53] op_sel_hi:[0,1,1]
	v_pk_fma_f32 v[54:55], s[32:33], v[10:11], v[54:55] op_sel_hi:[0,1,1]
	v_cvt_scalef32_pk_f32_fp4 v[4:5], v109, 1.0
	v_cvt_scalef32_pk_f32_fp4 v[6:7], v109, 1.0 op_sel:[1,0,0]
	v_cvt_scalef32_pk_f32_fp4 v[8:9], v109, 1.0 op_sel:[0,1,0]
	v_cvt_scalef32_pk_f32_fp4 v[10:11], v109, 1.0 op_sel:[1,1,0]
	v_pk_fma_f32 v[56:57], s[32:33], v[4:5], v[56:57] op_sel_hi:[0,1,1]
	v_pk_fma_f32 v[58:59], s[32:33], v[6:7], v[58:59] op_sel_hi:[0,1,1]
	v_pk_fma_f32 v[50:51], s[32:33], v[8:9], v[50:51] op_sel_hi:[0,1,1]
	v_pk_fma_f32 v[48:49], s[32:33], v[10:11], v[48:49] op_sel_hi:[0,1,1]
	v_readlane_b32 s34, v15, 63
	v_cvt_scalef32_pk_f32_fp4 v[4:5], v110, 1.0
	v_cvt_scalef32_pk_f32_fp4 v[6:7], v110, 1.0 op_sel:[1,0,0]
	v_cvt_scalef32_pk_f32_fp4 v[8:9], v110, 1.0 op_sel:[0,1,0]
	v_cvt_scalef32_pk_f32_fp4 v[10:11], v110, 1.0 op_sel:[1,1,0]
	v_pk_fma_f32 v[62:63], s[34:35], v[4:5], v[62:63] op_sel_hi:[0,1,1]
	v_pk_fma_f32 v[60:61], s[34:35], v[6:7], v[60:61] op_sel_hi:[0,1,1]
	v_pk_fma_f32 v[52:53], s[34:35], v[8:9], v[52:53] op_sel_hi:[0,1,1]
	v_pk_fma_f32 v[54:55], s[34:35], v[10:11], v[54:55] op_sel_hi:[0,1,1]
	v_cvt_scalef32_pk_f32_fp4 v[4:5], v111, 1.0
	v_cvt_scalef32_pk_f32_fp4 v[6:7], v111, 1.0 op_sel:[1,0,0]
	v_cvt_scalef32_pk_f32_fp4 v[8:9], v111, 1.0 op_sel:[0,1,0]
	v_cvt_scalef32_pk_f32_fp4 v[10:11], v111, 1.0 op_sel:[1,1,0]
	v_pk_fma_f32 v[56:57], s[34:35], v[4:5], v[56:57] op_sel_hi:[0,1,1]
	v_pk_fma_f32 v[58:59], s[34:35], v[6:7], v[58:59] op_sel_hi:[0,1,1]
	v_pk_fma_f32 v[50:51], s[34:35], v[8:9], v[50:51] op_sel_hi:[0,1,1]
	v_pk_fma_f32 v[48:49], s[34:35], v[10:11], v[48:49] op_sel_hi:[0,1,1]
	s_waitcnt vmcnt(7)
; __device__ void peer_v(const P& p, int layer, int tok, bool dry) {
;     ...
;   float ss = 0.f;
; #pragma unroll
;   for (int e = 0; e < 8; ++e) {
;     hv[2 * e] += oa2[e].x;
;     hv[2 * e + 1] += oa2[e].y;
;   }
; #pragma unroll
;   for (int e = 0; e < 16; ++e) ss += hv[e] * hv[e];
;   ss = wavesum_f(ss);
;   if (dry) { if (lane == 0) ((float*)(ws + OFF_ST))[tok] = ss; return; }
;   const float rs = rsqrtf(ss * (1.f / 1024.f) + 1e-6f);
;   const float* gw = (layer < 3) ? (p.norm_mix + (size_t)(layer + 1) * 1024) : p.final_norm;
;   float y[16];
; #pragma unroll
;   for (int k = 0; k < 4; ++k) {
;     const f32x4 g4 = ((const f32x4*)gw)[lane * 4 + k];
;     y[4 * k] = hv[4 * k] * rs * g4.x; y[4 * k + 1] = hv[4 * k + 1] * rs * g4.y;
;     y[4 * k + 2] = hv[4 * k + 2] * rs * g4.z; y[4 * k + 3] = hv[4 * k + 3] * rs * g4.w;
;   }
;   if (layer < 3) {
; #pragma unroll
;     for (int k = 0; k < 4; ++k) ((f32x4*)hrow)[lane * 4 + k] = MAKEF4(hv[4 * k], hv[4 * k + 1], hv[4 * k + 2], hv[4 * k + 3]);
;     bf16_t* xo = (bf16_t*)(ws + OFF_XN) + (size_t)tok * 1024;
;     u32x4 o0, o1;
;     o0.x = pk_bf16(y[0], y[1]); o0.y = pk_bf16(y[2], y[3]); o0.z = pk_bf16(y[4], y[5]); o0.w = pk_bf16(y[6], y[7]);
;     o1.x = pk_bf16(y[8], y[9]); o1.y = pk_bf16(y[10], y[11]); o1.z = pk_bf16(y[12], y[13]); o1.w = pk_bf16(y[14], y[15]);
;     ((u32x4*)xo)[lane * 2] = o0;
;     ((u32x4*)xo)[lane * 2 + 1] = o1;
	v_pk_add_f32 v[24:25], v[62:63], v[24:25]
	s_nop 0
	v_pk_mul_f32 v[66:67], v[24:25], v[24:25]
	v_pk_add_f32 v[26:27], v[60:61], v[26:27]
	v_add_f32_e32 v3, v66, v67
	v_pk_mul_f32 v[76:77], v[26:27], v[26:27]
	s_waitcnt vmcnt(4)
	v_pk_add_f32 v[52:53], v[52:53], v[40:41]
	v_add_f32_e32 v3, v76, v3
	v_pk_mul_f32 v[40:41], v[52:53], v[52:53]
	v_add_f32_e32 v3, v77, v3
	v_pk_add_f32 v[54:55], v[54:55], v[42:43]
	v_add_f32_e32 v3, v40, v3
	v_pk_mul_f32 v[42:43], v[54:55], v[54:55]
	v_add_f32_e32 v3, v41, v3
	v_pk_add_f32 v[56:57], v[56:57], v[28:29]
	v_add_f32_e32 v3, v42, v3
	v_pk_mul_f32 v[28:29], v[56:57], v[56:57]
	v_add_f32_e32 v3, v43, v3
	v_pk_add_f32 v[58:59], v[58:59], v[30:31]
	v_add_f32_e32 v3, v28, v3
	v_pk_mul_f32 v[30:31], v[58:59], v[58:59]
	v_add_f32_e32 v3, v29, v3
	v_pk_add_f32 v[60:61], v[50:51], v[20:21]
	v_add_f32_e32 v3, v30, v3
	v_pk_mul_f32 v[20:21], v[60:61], v[60:61]
	v_add_f32_e32 v3, v31, v3
	v_pk_add_f32 v[62:63], v[48:49], v[22:23]
	v_add_f32_e32 v3, v20, v3
	v_pk_mul_f32 v[22:23], v[62:63], v[62:63]
	v_add_f32_e32 v3, v21, v3
	v_add_f32_e32 v3, v22, v3
	v_add_f32_e32 v3, v23, v3
	s_nop 1
	v_add_f32_dpp v3, v3, v3 row_ror:1 row_mask:0xf bank_mask:0xf bound_ctrl:1
	s_nop 1
	v_add_f32_dpp v3, v3, v3 row_ror:2 row_mask:0xf bank_mask:0xf bound_ctrl:1
	s_nop 1
	v_add_f32_dpp v3, v3, v3 row_ror:4 row_mask:0xf bank_mask:0xf bound_ctrl:1
	s_nop 1
	v_add_f32_dpp v3, v3, v3 row_ror:8 row_mask:0xf bank_mask:0xf bound_ctrl:1
	s_nop 0
	v_readlane_b32 s11, v3, 16
	v_readlane_b32 s10, v3, 0
	s_nop 0
	v_mov_b32_e32 v20, s11
	v_add_f32_e32 v20, s10, v20
	v_readlane_b32 s10, v3, 32
	s_nop 1
	v_add_f32_e32 v20, s10, v20
	v_readlane_b32 s10, v3, 48
	s_nop 1
	v_add_f32_e32 v3, s10, v20
	v_fmamk_f32 v3, v3, 0x3a800000, v210
	s_mov_b32 s10, 0x800000
	v_cmp_gt_f32_e32 vcc, s10, v3
	v_mul_f32_e32 v20, 0x4b800000, v3
	s_mov_b64 s[10:11], -1
	v_cndmask_b32_e32 v3, v3, v20, vcc
	v_rsq_f32_e32 v3, v3
	s_nop 0
	v_mul_f32_e32 v20, 0x45800000, v3
	v_cndmask_b32_e32 v22, v3, v20, vcc
	v_pk_mul_f32 v[20:21], v[24:25], v[22:23] op_sel_hi:[1,0]
	s_andn2_b64 vcc, exec, s[0:1]
	s_waitcnt vmcnt(0)
	v_pk_mul_f32 v[48:49], v[72:73], v[20:21]
	v_pk_mul_f32 v[20:21], v[26:27], v[22:23] op_sel_hi:[1,0]
	s_nop 0
	v_pk_mul_f32 v[50:51], v[74:75], v[20:21]
	v_pk_mul_f32 v[20:21], v[52:53], v[22:23] op_sel_hi:[1,0]
	s_nop 0
	v_pk_mul_f32 v[40:41], v[44:45], v[20:21]
	v_pk_mul_f32 v[20:21], v[54:55], v[22:23] op_sel_hi:[1,0]
	s_nop 0
	v_pk_mul_f32 v[42:43], v[46:47], v[20:21]
	v_pk_mul_f32 v[20:21], v[56:57], v[22:23] op_sel_hi:[1,0]
	s_nop 0
	v_pk_mul_f32 v[28:29], v[36:37], v[20:21]
	v_pk_mul_f32 v[20:21], v[58:59], v[22:23] op_sel_hi:[1,0]
	s_nop 0
	v_pk_mul_f32 v[30:31], v[38:39], v[20:21]
	v_pk_mul_f32 v[20:21], v[60:61], v[22:23] op_sel_hi:[1,0]
	v_pk_mul_f32 v[22:23], v[62:63], v[22:23] op_sel_hi:[1,0]
	v_pk_mul_f32 v[20:21], v[32:33], v[20:21]
	v_pk_mul_f32 v[22:23], v[34:35], v[22:23]
	s_cbranch_vccnz .LBB0_1050
	v_lshl_add_u64 v[36:37], v[64:65], 1, s[8:9]
	v_lshlrev_b32_e32 v38, 5, v70
	v_mov_b32_e32 v39, v1
	v_lshl_add_u64 v[36:37], v[36:37], 0, v[38:39]
	s_mov_b64 s[8:9], 0x17a84000
	v_lshl_add_u64 v[38:39], v[36:37], 0, s[8:9]
	v_add_co_u32_e32 v36, vcc, 0x17a84000, v36
	global_store_dwordx4 v[68:69], v[24:27], off
	global_store_dwordx4 v[68:69], v[52:55], off offset:16
	global_store_dwordx4 v[68:69], v[56:59], off offset:32
	global_store_dwordx4 v[68:69], v[60:63], off offset:48
	v_cvt_pk_bf16_f32 v24, v48, v49
	v_cvt_pk_bf16_f32 v25, v50, v51
	v_cvt_pk_bf16_f32 v26, v40, v41
	v_cvt_pk_bf16_f32 v27, v42, v43
	v_addc_co_u32_e32 v37, vcc, 0, v37, vcc
	s_mov_b64 s[10:11], 0
	v_cvt_pk_bf16_f32 v32, v28, v29
	v_cvt_pk_bf16_f32 v33, v30, v31
	v_cvt_pk_bf16_f32 v34, v20, v21
	v_cvt_pk_bf16_f32 v35, v22, v23
	global_store_dwordx4 v[36:37], v[24:27], off
	global_store_dwordx4 v[38:39], v[32:35], off offset:16
